# v_rcp_f32 also in the LoRA / LRU-gate GEMM epilogues (P6); wide-store WAR wait states restored
# speedup vs baseline: 1.0129x; 1.0129x over previous
; __device__ __forceinline__ unsigned cvt_pk_bf16(float lo, float hi) { const f32x2 v = {lo, hi}; return __builtin_bit_cast(unsigned, __builtin_convertvector(v, bf16x2_t)); }
; __device__ __forceinline__ float sigm(float x) { return 1.0f / (1.0f + __expf(-x)); }
; __device__ __forceinline__ float decay_e(float pre) { return 0.6065306597126334f * sigm(pre); }
;     __device__ __forceinline__ void operator()(AccRef acc, const Unit& u, int wr, int wc, int fr, int fq) const {
;     ...
;                 for (int m = 0; m < 4; ++m) { f32x4 v0 = acc[ai][bj][m][0] + b0, v1 = acc[ai][bj][m][1] + b1;
;                     if (kind == 0) { v0 = (f32x4){decay_e(v0[0]), decay_e(v0[1]), decay_e(v0[2]), decay_e(v0[3])}; v1 = (f32x4){decay_e(v1[0]), decay_e(v1[1]), decay_e(v1[2]), decay_e(v1[3])}; }
;                     else if (kind == 1) { v0 = (f32x4){sigm(v0[0]), sigm(v0[1]), sigm(v0[2]), sigm(v0[3])}; v1 = (f32x4){sigm(v1[0]), sigm(v1[1]), sigm(v1[2]), sigm(v1[3])}; }
;                     u32x4 w; w.x = cvt_pk_bf16(v0[0], v0[1]); w.y = cvt_pk_bf16(v0[2], v0[3]); w.z = cvt_pk_bf16(v1[0], v1[1]); w.w = cvt_pk_bf16(v1[2], v1[3]);
;                     *(u32x4*)(base + (size_t)EPI_ROWS(ai, m) * D + colt + bj * HALF) = w; }
.LBB0_778:
	s_cmp_eq_u32 s5, 1
	s_cselect_b64 s[2:3], -1, 0
	s_waitcnt vmcnt(0)
	v_pk_add_f32 v[136:137], v[132:133], v[84:85]
	v_cndmask_b32_e64 v132, 0, 1, s[2:3]
	v_pk_add_f32 v[138:139], v[134:135], v[86:87]
	v_pk_add_f32 v[130:131], v[130:131], v[82:83]
	v_pk_add_f32 v[128:129], v[128:129], v[80:81]
	s_mov_b64 s[54:55], -1
	s_and_b64 vcc, exec, s[52:53]
	v_cmp_ne_u32_e64 s[2:3], 1, v132
	s_cbranch_vccz .LBB0_782
	v_mov_b64_e32 v[142:143], v[130:131]
	v_mov_b64_e32 v[132:133], v[136:137]
	s_and_b64 vcc, exec, s[2:3]
	v_mov_b64_e32 v[140:141], v[128:129]
	v_mov_b64_e32 v[134:135], v[138:139]
	s_cbranch_vccnz .LBB0_781
	v_mul_f32_e32 v132, 0xbfb8aa3b, v138
	v_mul_f32_e32 v133, 0xbfb8aa3b, v139
	v_exp_f32_e32 v132, v132
	v_exp_f32_e32 v133, v133
	v_mul_f32_e32 v134, 0xbfb8aa3b, v136
	v_mul_f32_e32 v135, 0xbfb8aa3b, v137
	v_exp_f32_e32 v134, v134
	v_pk_add_f32 v[132:133], v[132:133], 1.0 op_sel_hi:[1,0]
	v_exp_f32_e32 v135, v135
	s_nop 0
	v_pk_add_f32 v[140:141], v[134:135], 1.0 op_sel_hi:[1,0]
	v_mul_f32_e32 v156, 0xbfb8aa3b, v128
	v_exp_f32_e32 v166, v156
	v_rcp_f32_e32 v135, v133
	v_mul_f32_e32 v156, 0xbfb8aa3b, v129
	v_rcp_f32_e32 v134, v132
	v_exp_f32_e32 v167, v156
	v_rcp_f32_e32 v133, v141
	v_mul_f32_e32 v142, 0xbfb8aa3b, v130
	v_mul_f32_e32 v143, 0xbfb8aa3b, v131
	v_exp_f32_e32 v142, v142
	v_exp_f32_e32 v143, v143
	v_rcp_f32_e32 v132, v140
	v_pk_add_f32 v[140:141], v[166:167], 1.0 op_sel_hi:[1,0]
	v_pk_add_f32 v[142:143], v[142:143], 1.0 op_sel_hi:[1,0]
	s_nop 0
	s_nop 0
	v_rcp_f32_e32 v143, v143
	v_rcp_f32_e32 v142, v142
	v_rcp_f32_e32 v141, v141
	v_rcp_f32_e32 v140, v140

; __device__ __forceinline__ unsigned cvt_pk_bf16(float lo, float hi) { const f32x2 v = {lo, hi}; return __builtin_bit_cast(unsigned, __builtin_convertvector(v, bf16x2_t)); }
; __device__ __forceinline__ float sigm(float x) { return 1.0f / (1.0f + __expf(-x)); }
; __device__ __forceinline__ float decay_e(float pre) { return 0.6065306597126334f * sigm(pre); }
;     __device__ __forceinline__ void operator()(AccRef acc, const Unit& u, int wr, int wc, int fr, int fq) const {
;     ...
;                 for (int m = 0; m < 4; ++m) { f32x4 v0 = acc[ai][bj][m][0] + b0, v1 = acc[ai][bj][m][1] + b1;
;                     if (kind == 0) { v0 = (f32x4){decay_e(v0[0]), decay_e(v0[1]), decay_e(v0[2]), decay_e(v0[3])}; v1 = (f32x4){decay_e(v1[0]), decay_e(v1[1]), decay_e(v1[2]), decay_e(v1[3])}; }
;                     else if (kind == 1) { v0 = (f32x4){sigm(v0[0]), sigm(v0[1]), sigm(v0[2]), sigm(v0[3])}; v1 = (f32x4){sigm(v1[0]), sigm(v1[1]), sigm(v1[2]), sigm(v1[3])}; }
;                     u32x4 w; w.x = cvt_pk_bf16(v0[0], v0[1]); w.y = cvt_pk_bf16(v0[2], v0[3]); w.z = cvt_pk_bf16(v1[0], v1[1]); w.w = cvt_pk_bf16(v1[2], v1[3]);
;                     *(u32x4*)(base + (size_t)EPI_ROWS(ai, m) * D + colt + bj * HALF) = w; }
.LBB0_782:
	s_andn2_b64 vcc, exec, s[54:55]
	s_cbranch_vccnz .LBB0_784
	v_mul_f32_e32 v132, 0xbfb8aa3b, v136
	v_mul_f32_e32 v133, 0xbfb8aa3b, v137
	v_exp_f32_e32 v132, v132
	v_exp_f32_e32 v133, v133
	v_mul_f32_e32 v134, 0xbfb8aa3b, v138
	v_mul_f32_e32 v135, 0xbfb8aa3b, v139
	v_exp_f32_e32 v134, v134
	v_pk_add_f32 v[132:133], v[132:133], 1.0 op_sel_hi:[1,0]
	v_exp_f32_e32 v135, v135
	s_nop 0
	v_pk_add_f32 v[134:135], v[134:135], 1.0 op_sel_hi:[1,0]
	v_mul_f32_e32 v128, 0xbfb8aa3b, v128
	v_mul_f32_e32 v129, 0xbfb8aa3b, v129
	v_rcp_f32_e32 v133, v133
	v_exp_f32_e32 v128, v128
	v_rcp_f32_e32 v132, v132
	v_exp_f32_e32 v129, v129
	v_rcp_f32_e32 v135, v135
	v_pk_add_f32 v[128:129], v[128:129], 1.0 op_sel_hi:[1,0]
	v_rcp_f32_e32 v134, v134
	v_mul_f32_e32 v130, 0xbfb8aa3b, v130
	v_mul_f32_e32 v131, 0xbfb8aa3b, v131
	v_exp_f32_e32 v130, v130
	v_exp_f32_e32 v131, v131
	v_rcp_f32_e32 v129, v129
	v_pk_add_f32 v[130:131], v[130:131], 1.0 op_sel_hi:[1,0]
	v_rcp_f32_e32 v128, v128
	v_pk_mul_f32 v[134:135], v[134:135], s[14:15] op_sel_hi:[1,0]
	v_rcp_f32_e32 v131, v131
	v_pk_mul_f32 v[132:133], v[132:133], s[14:15] op_sel_hi:[1,0]
	v_rcp_f32_e32 v130, v130
	s_nop 0
	v_pk_mul_f32 v[142:143], v[130:131], s[14:15] op_sel_hi:[1,0]
	v_pk_mul_f32 v[140:141], v[128:129], s[14:15] op_sel_hi:[1,0]
.LBB0_784:
	s_mul_hi_i32 s25, s5, 0x2100000
	s_mul_i32 s5, s5, 0x2100000
	s_add_u32 s54, s80, s5
	v_lshl_add_u32 v156, s4, 8, v159
	s_addc_u32 s55, s92, s25
	v_lshlrev_b32_e32 v152, 1, v157
	v_ashrrev_i32_e32 v157, 31, v156
	v_lshl_add_u64 v[138:139], s[54:55], 0, v[152:153]
	v_cvt_pk_bf16_f32 v128, v132, v133
	v_lshlrev_b64 v[132:133], 11, v[156:157]
	v_cvt_pk_bf16_f32 v129, v134, v135
	v_cvt_pk_bf16_f32 v130, v140, v141
	v_cvt_pk_bf16_f32 v131, v142, v143
	v_lshl_add_u64 v[136:137], v[138:139], 0, v[132:133]
	global_store_dwordx4 v[136:137], v[128:131], off
	v_pk_add_f32 v[122:123], v[122:123], v[82:83]
	v_pk_add_f32 v[120:121], v[120:121], v[80:81]
	v_pk_add_f32 v[128:129], v[124:125], v[84:85]
	v_cndmask_b32_e64 v124, 0, 1, s[52:53]
	v_pk_add_f32 v[130:131], v[126:127], v[86:87]
	v_cmp_ne_u32_e64 s[4:5], 1, v124
	s_andn2_b64 vcc, exec, s[52:53]
	s_mov_b64 s[52:53], -1
	s_cbranch_vccnz .LBB0_788
	v_mov_b64_e32 v[134:135], v[122:123]
	v_mov_b64_e32 v[124:125], v[128:129]
	s_and_b64 vcc, exec, s[2:3]
	v_mov_b64_e32 v[132:133], v[120:121]
	v_mov_b64_e32 v[126:127], v[130:131]
	s_cbranch_vccnz .LBB0_787
	v_mul_f32_e32 v124, 0xbfb8aa3b, v130
	v_mul_f32_e32 v125, 0xbfb8aa3b, v131
	v_exp_f32_e32 v124, v124
	v_exp_f32_e32 v125, v125
	v_mul_f32_e32 v126, 0xbfb8aa3b, v128
	v_mul_f32_e32 v127, 0xbfb8aa3b, v129
	v_exp_f32_e32 v126, v126
	v_pk_add_f32 v[124:125], v[124:125], 1.0 op_sel_hi:[1,0]
	v_exp_f32_e32 v127, v127
	s_nop 0
	v_pk_add_f32 v[132:133], v[126:127], 1.0 op_sel_hi:[1,0]
	v_mul_f32_e32 v141, 0xbfb8aa3b, v121
	v_exp_f32_e32 v141, v141
	v_rcp_f32_e32 v127, v125
	v_rcp_f32_e32 v126, v124
	v_rcp_f32_e32 v125, v133
	v_mul_f32_e32 v140, 0xbfb8aa3b, v120
	v_mul_f32_e32 v134, 0xbfb8aa3b, v122
	v_mul_f32_e32 v135, 0xbfb8aa3b, v123
	v_exp_f32_e32 v134, v134
	v_exp_f32_e32 v135, v135
	v_exp_f32_e32 v140, v140
	v_rcp_f32_e32 v124, v132
	v_pk_add_f32 v[134:135], v[134:135], 1.0 op_sel_hi:[1,0]
	v_pk_add_f32 v[132:133], v[140:141], 1.0 op_sel_hi:[1,0]
	s_nop 0
	v_rcp_f32_e32 v135, v135
	v_rcp_f32_e32 v134, v134
	v_rcp_f32_e32 v133, v133
	v_rcp_f32_e32 v132, v132

; __device__ __forceinline__ unsigned cvt_pk_bf16(float lo, float hi) { const f32x2 v = {lo, hi}; return __builtin_bit_cast(unsigned, __builtin_convertvector(v, bf16x2_t)); }
; __device__ __forceinline__ float sigm(float x) { return 1.0f / (1.0f + __expf(-x)); }
; __device__ __forceinline__ float decay_e(float pre) { return 0.6065306597126334f * sigm(pre); }
;     __device__ __forceinline__ void operator()(AccRef acc, const Unit& u, int wr, int wc, int fr, int fq) const {
;     ...
;                 for (int m = 0; m < 4; ++m) { f32x4 v0 = acc[ai][bj][m][0] + b0, v1 = acc[ai][bj][m][1] + b1;
;                     if (kind == 0) { v0 = (f32x4){decay_e(v0[0]), decay_e(v0[1]), decay_e(v0[2]), decay_e(v0[3])}; v1 = (f32x4){decay_e(v1[0]), decay_e(v1[1]), decay_e(v1[2]), decay_e(v1[3])}; }
;                     else if (kind == 1) { v0 = (f32x4){sigm(v0[0]), sigm(v0[1]), sigm(v0[2]), sigm(v0[3])}; v1 = (f32x4){sigm(v1[0]), sigm(v1[1]), sigm(v1[2]), sigm(v1[3])}; }
;                     u32x4 w; w.x = cvt_pk_bf16(v0[0], v0[1]); w.y = cvt_pk_bf16(v0[2], v0[3]); w.z = cvt_pk_bf16(v1[0], v1[1]); w.w = cvt_pk_bf16(v1[2], v1[3]);
;                     *(u32x4*)(base + (size_t)EPI_ROWS(ai, m) * D + colt + bj * HALF) = w; }
.LBB0_788:
	s_andn2_b64 vcc, exec, s[52:53]
	s_cbranch_vccnz .LBB0_790
	v_mul_f32_e32 v124, 0xbfb8aa3b, v128
	v_mul_f32_e32 v125, 0xbfb8aa3b, v129
	v_exp_f32_e32 v124, v124
	v_exp_f32_e32 v125, v125
	v_mul_f32_e32 v126, 0xbfb8aa3b, v130
	v_mul_f32_e32 v127, 0xbfb8aa3b, v131
	v_exp_f32_e32 v126, v126
	v_pk_add_f32 v[124:125], v[124:125], 1.0 op_sel_hi:[1,0]
	v_exp_f32_e32 v127, v127
	s_nop 0
	v_pk_add_f32 v[126:127], v[126:127], 1.0 op_sel_hi:[1,0]
	v_mul_f32_e32 v120, 0xbfb8aa3b, v120
	v_mul_f32_e32 v121, 0xbfb8aa3b, v121
	v_rcp_f32_e32 v125, v125
	v_exp_f32_e32 v120, v120
	v_rcp_f32_e32 v124, v124
	v_exp_f32_e32 v121, v121
	v_rcp_f32_e32 v127, v127
	v_pk_add_f32 v[120:121], v[120:121], 1.0 op_sel_hi:[1,0]
	v_rcp_f32_e32 v126, v126
	v_mul_f32_e32 v122, 0xbfb8aa3b, v122
	v_mul_f32_e32 v123, 0xbfb8aa3b, v123
	v_exp_f32_e32 v122, v122
	v_exp_f32_e32 v123, v123
	v_rcp_f32_e32 v121, v121
	v_pk_add_f32 v[122:123], v[122:123], 1.0 op_sel_hi:[1,0]
	v_rcp_f32_e32 v120, v120
	v_pk_mul_f32 v[126:127], v[126:127], s[14:15] op_sel_hi:[1,0]
	v_rcp_f32_e32 v123, v123
	v_pk_mul_f32 v[124:125], v[124:125], s[14:15] op_sel_hi:[1,0]
	v_rcp_f32_e32 v122, v122
	s_nop 0
	v_pk_mul_f32 v[134:135], v[122:123], s[14:15] op_sel_hi:[1,0]
	v_pk_mul_f32 v[132:133], v[120:121], s[14:15] op_sel_hi:[1,0]
.LBB0_790:
	v_cvt_pk_bf16_f32 v120, v124, v125
	v_or_b32_e32 v124, 16, v156
	v_ashrrev_i32_e32 v125, 31, v124
	v_lshlrev_b64 v[124:125], 11, v[124:125]
	v_cvt_pk_bf16_f32 v121, v126, v127
	v_cvt_pk_bf16_f32 v122, v132, v133
	v_cvt_pk_bf16_f32 v123, v134, v135
	v_lshl_add_u64 v[128:129], v[138:139], 0, v[124:125]
	global_store_dwordx4 v[128:129], v[120:123], off
	v_pk_add_f32 v[114:115], v[114:115], v[82:83]
	v_pk_add_f32 v[112:113], v[112:113], v[80:81]
	v_pk_add_f32 v[122:123], v[118:119], v[86:87]
	v_pk_add_f32 v[120:121], v[116:117], v[84:85]
	s_and_b64 vcc, exec, s[4:5]
	s_mov_b64 s[52:53], -1
	s_cbranch_vccnz .LBB0_794
	v_mov_b64_e32 v[126:127], v[114:115]
	v_mov_b64_e32 v[116:117], v[120:121]
	s_and_b64 vcc, exec, s[2:3]
	v_mov_b64_e32 v[124:125], v[112:113]
	v_mov_b64_e32 v[118:119], v[122:123]
	s_cbranch_vccnz .LBB0_793
	v_mul_f32_e32 v116, 0xbfb8aa3b, v122
	v_mul_f32_e32 v117, 0xbfb8aa3b, v123
	v_exp_f32_e32 v116, v116
	v_exp_f32_e32 v117, v117
	v_mul_f32_e32 v118, 0xbfb8aa3b, v120
	v_mul_f32_e32 v119, 0xbfb8aa3b, v121
	v_exp_f32_e32 v118, v118
	v_pk_add_f32 v[116:117], v[116:117], 1.0 op_sel_hi:[1,0]
	v_exp_f32_e32 v119, v119
	s_nop 0
	v_pk_add_f32 v[124:125], v[118:119], 1.0 op_sel_hi:[1,0]
	v_mul_f32_e32 v131, 0xbfb8aa3b, v113
	v_exp_f32_e32 v131, v131
	v_rcp_f32_e32 v119, v117
	v_rcp_f32_e32 v118, v116
	v_rcp_f32_e32 v117, v125
	v_mul_f32_e32 v130, 0xbfb8aa3b, v112
	v_mul_f32_e32 v126, 0xbfb8aa3b, v114
	v_mul_f32_e32 v127, 0xbfb8aa3b, v115
	v_exp_f32_e32 v126, v126
	v_exp_f32_e32 v127, v127
	v_exp_f32_e32 v130, v130
	v_rcp_f32_e32 v116, v124
	v_pk_add_f32 v[126:127], v[126:127], 1.0 op_sel_hi:[1,0]
	v_pk_add_f32 v[124:125], v[130:131], 1.0 op_sel_hi:[1,0]
	s_nop 0
	v_rcp_f32_e32 v127, v127
	v_rcp_f32_e32 v126, v126
	v_rcp_f32_e32 v125, v125
	v_rcp_f32_e32 v124, v124

; __device__ __forceinline__ unsigned cvt_pk_bf16(float lo, float hi) { const f32x2 v = {lo, hi}; return __builtin_bit_cast(unsigned, __builtin_convertvector(v, bf16x2_t)); }
; __device__ __forceinline__ float sigm(float x) { return 1.0f / (1.0f + __expf(-x)); }
; __device__ __forceinline__ float decay_e(float pre) { return 0.6065306597126334f * sigm(pre); }
;     __device__ __forceinline__ void operator()(AccRef acc, const Unit& u, int wr, int wc, int fr, int fq) const {
;     ...
;                 for (int m = 0; m < 4; ++m) { f32x4 v0 = acc[ai][bj][m][0] + b0, v1 = acc[ai][bj][m][1] + b1;
;                     if (kind == 0) { v0 = (f32x4){decay_e(v0[0]), decay_e(v0[1]), decay_e(v0[2]), decay_e(v0[3])}; v1 = (f32x4){decay_e(v1[0]), decay_e(v1[1]), decay_e(v1[2]), decay_e(v1[3])}; }
;                     else if (kind == 1) { v0 = (f32x4){sigm(v0[0]), sigm(v0[1]), sigm(v0[2]), sigm(v0[3])}; v1 = (f32x4){sigm(v1[0]), sigm(v1[1]), sigm(v1[2]), sigm(v1[3])}; }
;                     u32x4 w; w.x = cvt_pk_bf16(v0[0], v0[1]); w.y = cvt_pk_bf16(v0[2], v0[3]); w.z = cvt_pk_bf16(v1[0], v1[1]); w.w = cvt_pk_bf16(v1[2], v1[3]);
;                     *(u32x4*)(base + (size_t)EPI_ROWS(ai, m) * D + colt + bj * HALF) = w; }
.LBB0_794:
	s_andn2_b64 vcc, exec, s[52:53]
	s_cbranch_vccnz .LBB0_796
	v_mul_f32_e32 v116, 0xbfb8aa3b, v120
	v_mul_f32_e32 v117, 0xbfb8aa3b, v121
	v_exp_f32_e32 v116, v116
	v_exp_f32_e32 v117, v117
	v_mul_f32_e32 v118, 0xbfb8aa3b, v122
	v_mul_f32_e32 v119, 0xbfb8aa3b, v123
	v_exp_f32_e32 v118, v118
	v_pk_add_f32 v[116:117], v[116:117], 1.0 op_sel_hi:[1,0]
	v_exp_f32_e32 v119, v119
	s_nop 0
	v_pk_add_f32 v[118:119], v[118:119], 1.0 op_sel_hi:[1,0]
	v_mul_f32_e32 v112, 0xbfb8aa3b, v112
	v_mul_f32_e32 v113, 0xbfb8aa3b, v113
	v_rcp_f32_e32 v117, v117
	v_exp_f32_e32 v112, v112
	v_rcp_f32_e32 v116, v116
	v_exp_f32_e32 v113, v113
	v_rcp_f32_e32 v119, v119
	v_pk_add_f32 v[112:113], v[112:113], 1.0 op_sel_hi:[1,0]
	v_rcp_f32_e32 v118, v118
	v_mul_f32_e32 v114, 0xbfb8aa3b, v114
	v_mul_f32_e32 v115, 0xbfb8aa3b, v115
	v_exp_f32_e32 v114, v114
	v_exp_f32_e32 v115, v115
	v_rcp_f32_e32 v113, v113
	v_pk_add_f32 v[114:115], v[114:115], 1.0 op_sel_hi:[1,0]
	v_rcp_f32_e32 v112, v112
	v_pk_mul_f32 v[118:119], v[118:119], s[14:15] op_sel_hi:[1,0]
	v_rcp_f32_e32 v115, v115
	v_pk_mul_f32 v[116:117], v[116:117], s[14:15] op_sel_hi:[1,0]
	v_rcp_f32_e32 v114, v114
	s_nop 0
	v_pk_mul_f32 v[126:127], v[114:115], s[14:15] op_sel_hi:[1,0]
	v_pk_mul_f32 v[124:125], v[112:113], s[14:15] op_sel_hi:[1,0]
.LBB0_796:
	v_cvt_pk_bf16_f32 v112, v116, v117
	v_or_b32_e32 v116, 32, v156
	v_ashrrev_i32_e32 v117, 31, v116
	v_lshlrev_b64 v[116:117], 11, v[116:117]
	v_cvt_pk_bf16_f32 v113, v118, v119
	v_cvt_pk_bf16_f32 v114, v124, v125
	v_cvt_pk_bf16_f32 v115, v126, v127
	v_lshl_add_u64 v[120:121], v[138:139], 0, v[116:117]
	global_store_dwordx4 v[120:121], v[112:115], off
	v_pk_add_f32 v[106:107], v[106:107], v[82:83]
	v_pk_add_f32 v[104:105], v[104:105], v[80:81]
	v_pk_add_f32 v[114:115], v[110:111], v[86:87]
	v_pk_add_f32 v[112:113], v[108:109], v[84:85]
	s_and_b64 vcc, exec, s[4:5]
	s_mov_b64 s[52:53], -1
	s_cbranch_vccnz .LBB0_800
	v_mov_b64_e32 v[118:119], v[106:107]
	v_mov_b64_e32 v[108:109], v[112:113]
	s_and_b64 vcc, exec, s[2:3]
	v_mov_b64_e32 v[116:117], v[104:105]
	v_mov_b64_e32 v[110:111], v[114:115]
	s_cbranch_vccnz .LBB0_799
	v_mul_f32_e32 v108, 0xbfb8aa3b, v114
	v_mul_f32_e32 v109, 0xbfb8aa3b, v115
	v_exp_f32_e32 v108, v108
	v_exp_f32_e32 v109, v109
	v_mul_f32_e32 v110, 0xbfb8aa3b, v112
	v_mul_f32_e32 v111, 0xbfb8aa3b, v113
	v_exp_f32_e32 v110, v110
	v_pk_add_f32 v[108:109], v[108:109], 1.0 op_sel_hi:[1,0]
	v_exp_f32_e32 v111, v111
	s_nop 0
	v_pk_add_f32 v[116:117], v[110:111], 1.0 op_sel_hi:[1,0]
	v_mul_f32_e32 v123, 0xbfb8aa3b, v105
	v_exp_f32_e32 v123, v123
	v_rcp_f32_e32 v111, v109
	v_rcp_f32_e32 v110, v108
	v_rcp_f32_e32 v109, v117
	v_mul_f32_e32 v122, 0xbfb8aa3b, v104
	v_mul_f32_e32 v118, 0xbfb8aa3b, v106
	v_mul_f32_e32 v119, 0xbfb8aa3b, v107
	v_exp_f32_e32 v118, v118
	v_exp_f32_e32 v119, v119
	v_exp_f32_e32 v122, v122
	v_rcp_f32_e32 v108, v116
	v_pk_add_f32 v[118:119], v[118:119], 1.0 op_sel_hi:[1,0]
	v_pk_add_f32 v[116:117], v[122:123], 1.0 op_sel_hi:[1,0]
	s_nop 0
	v_rcp_f32_e32 v119, v119
	v_rcp_f32_e32 v118, v118
	v_rcp_f32_e32 v117, v117
	v_rcp_f32_e32 v116, v116

; __device__ __forceinline__ unsigned cvt_pk_bf16(float lo, float hi) { const f32x2 v = {lo, hi}; return __builtin_bit_cast(unsigned, __builtin_convertvector(v, bf16x2_t)); }
; __device__ __forceinline__ float sigm(float x) { return 1.0f / (1.0f + __expf(-x)); }
; __device__ __forceinline__ float decay_e(float pre) { return 0.6065306597126334f * sigm(pre); }
;     __device__ __forceinline__ void operator()(AccRef acc, const Unit& u, int wr, int wc, int fr, int fq) const {
;     ...
;                 for (int m = 0; m < 4; ++m) { f32x4 v0 = acc[ai][bj][m][0] + b0, v1 = acc[ai][bj][m][1] + b1;
;                     if (kind == 0) { v0 = (f32x4){decay_e(v0[0]), decay_e(v0[1]), decay_e(v0[2]), decay_e(v0[3])}; v1 = (f32x4){decay_e(v1[0]), decay_e(v1[1]), decay_e(v1[2]), decay_e(v1[3])}; }
;                     else if (kind == 1) { v0 = (f32x4){sigm(v0[0]), sigm(v0[1]), sigm(v0[2]), sigm(v0[3])}; v1 = (f32x4){sigm(v1[0]), sigm(v1[1]), sigm(v1[2]), sigm(v1[3])}; }
;                     u32x4 w; w.x = cvt_pk_bf16(v0[0], v0[1]); w.y = cvt_pk_bf16(v0[2], v0[3]); w.z = cvt_pk_bf16(v1[0], v1[1]); w.w = cvt_pk_bf16(v1[2], v1[3]);
;                     *(u32x4*)(base + (size_t)EPI_ROWS(ai, m) * D + colt + bj * HALF) = w; }
.LBB0_800:
	s_andn2_b64 vcc, exec, s[52:53]
	s_cbranch_vccnz .LBB0_802
	v_mul_f32_e32 v108, 0xbfb8aa3b, v112
	v_mul_f32_e32 v109, 0xbfb8aa3b, v113
	v_exp_f32_e32 v108, v108
	v_exp_f32_e32 v109, v109
	v_mul_f32_e32 v110, 0xbfb8aa3b, v114
	v_mul_f32_e32 v111, 0xbfb8aa3b, v115
	v_exp_f32_e32 v110, v110
	v_pk_add_f32 v[108:109], v[108:109], 1.0 op_sel_hi:[1,0]
	v_exp_f32_e32 v111, v111
	s_nop 0
	v_pk_add_f32 v[110:111], v[110:111], 1.0 op_sel_hi:[1,0]
	v_mul_f32_e32 v104, 0xbfb8aa3b, v104
	v_mul_f32_e32 v105, 0xbfb8aa3b, v105
	v_rcp_f32_e32 v109, v109
	v_exp_f32_e32 v104, v104
	v_rcp_f32_e32 v108, v108
	v_exp_f32_e32 v105, v105
	v_rcp_f32_e32 v111, v111
	v_pk_add_f32 v[104:105], v[104:105], 1.0 op_sel_hi:[1,0]
	v_rcp_f32_e32 v110, v110
	v_mul_f32_e32 v106, 0xbfb8aa3b, v106
	v_mul_f32_e32 v107, 0xbfb8aa3b, v107
	v_exp_f32_e32 v106, v106
	v_exp_f32_e32 v107, v107
	v_rcp_f32_e32 v105, v105
	v_pk_add_f32 v[106:107], v[106:107], 1.0 op_sel_hi:[1,0]
	v_rcp_f32_e32 v104, v104
	v_pk_mul_f32 v[110:111], v[110:111], s[14:15] op_sel_hi:[1,0]
	v_rcp_f32_e32 v107, v107
	v_pk_mul_f32 v[108:109], v[108:109], s[14:15] op_sel_hi:[1,0]
	v_rcp_f32_e32 v106, v106
	s_nop 0
	v_pk_mul_f32 v[118:119], v[106:107], s[14:15] op_sel_hi:[1,0]
	v_pk_mul_f32 v[116:117], v[104:105], s[14:15] op_sel_hi:[1,0]
.LBB0_802:
	v_cvt_pk_bf16_f32 v104, v108, v109
	v_or_b32_e32 v108, 48, v156
	v_ashrrev_i32_e32 v109, 31, v108
	v_lshlrev_b64 v[108:109], 11, v[108:109]
	v_cvt_pk_bf16_f32 v105, v110, v111
	v_cvt_pk_bf16_f32 v106, v116, v117
	v_cvt_pk_bf16_f32 v107, v118, v119
	v_lshl_add_u64 v[112:113], v[138:139], 0, v[108:109]
	global_store_dwordx4 v[112:113], v[104:107], off
	v_pk_add_f32 v[98:99], v[98:99], v[82:83]
	v_pk_add_f32 v[96:97], v[96:97], v[80:81]
	v_pk_add_f32 v[106:107], v[102:103], v[86:87]
	v_pk_add_f32 v[104:105], v[100:101], v[84:85]
	s_and_b64 vcc, exec, s[4:5]
	s_mov_b64 s[52:53], -1
	s_cbranch_vccnz .LBB0_806
	v_mov_b64_e32 v[110:111], v[98:99]
	v_mov_b64_e32 v[100:101], v[104:105]
	s_and_b64 vcc, exec, s[2:3]
	v_mov_b64_e32 v[108:109], v[96:97]
	v_mov_b64_e32 v[102:103], v[106:107]
	s_cbranch_vccnz .LBB0_805
	v_mul_f32_e32 v100, 0xbfb8aa3b, v106
	v_mul_f32_e32 v101, 0xbfb8aa3b, v107
	v_exp_f32_e32 v100, v100
	v_exp_f32_e32 v101, v101
	v_mul_f32_e32 v102, 0xbfb8aa3b, v104
	v_mul_f32_e32 v103, 0xbfb8aa3b, v105
	v_exp_f32_e32 v102, v102
	v_pk_add_f32 v[100:101], v[100:101], 1.0 op_sel_hi:[1,0]
	v_exp_f32_e32 v103, v103
	s_nop 0
	v_pk_add_f32 v[108:109], v[102:103], 1.0 op_sel_hi:[1,0]
	v_mul_f32_e32 v115, 0xbfb8aa3b, v97
	v_exp_f32_e32 v115, v115
	v_rcp_f32_e32 v103, v101
	v_rcp_f32_e32 v102, v100
	v_rcp_f32_e32 v101, v109
	v_mul_f32_e32 v114, 0xbfb8aa3b, v96
	v_mul_f32_e32 v110, 0xbfb8aa3b, v98
	v_mul_f32_e32 v111, 0xbfb8aa3b, v99
	v_exp_f32_e32 v110, v110
	v_exp_f32_e32 v111, v111
	v_exp_f32_e32 v114, v114
	v_rcp_f32_e32 v100, v108
	v_pk_add_f32 v[110:111], v[110:111], 1.0 op_sel_hi:[1,0]
	v_pk_add_f32 v[108:109], v[114:115], 1.0 op_sel_hi:[1,0]
	s_nop 0
	v_rcp_f32_e32 v111, v111
	v_rcp_f32_e32 v110, v110
	v_rcp_f32_e32 v109, v109
	v_rcp_f32_e32 v108, v108

; __device__ __forceinline__ unsigned cvt_pk_bf16(float lo, float hi) { const f32x2 v = {lo, hi}; return __builtin_bit_cast(unsigned, __builtin_convertvector(v, bf16x2_t)); }
; __device__ __forceinline__ float sigm(float x) { return 1.0f / (1.0f + __expf(-x)); }
; __device__ __forceinline__ float decay_e(float pre) { return 0.6065306597126334f * sigm(pre); }
;     __device__ __forceinline__ void operator()(AccRef acc, const Unit& u, int wr, int wc, int fr, int fq) const {
;     ...
;                 for (int m = 0; m < 4; ++m) { f32x4 v0 = acc[ai][bj][m][0] + b0, v1 = acc[ai][bj][m][1] + b1;
;                     if (kind == 0) { v0 = (f32x4){decay_e(v0[0]), decay_e(v0[1]), decay_e(v0[2]), decay_e(v0[3])}; v1 = (f32x4){decay_e(v1[0]), decay_e(v1[1]), decay_e(v1[2]), decay_e(v1[3])}; }
;                     else if (kind == 1) { v0 = (f32x4){sigm(v0[0]), sigm(v0[1]), sigm(v0[2]), sigm(v0[3])}; v1 = (f32x4){sigm(v1[0]), sigm(v1[1]), sigm(v1[2]), sigm(v1[3])}; }
;                     u32x4 w; w.x = cvt_pk_bf16(v0[0], v0[1]); w.y = cvt_pk_bf16(v0[2], v0[3]); w.z = cvt_pk_bf16(v1[0], v1[1]); w.w = cvt_pk_bf16(v1[2], v1[3]);
;                     *(u32x4*)(base + (size_t)EPI_ROWS(ai, m) * D + colt + bj * HALF) = w; }
.LBB0_806:
	s_andn2_b64 vcc, exec, s[52:53]
	s_cbranch_vccnz .LBB0_808
	v_mul_f32_e32 v100, 0xbfb8aa3b, v104
	v_mul_f32_e32 v101, 0xbfb8aa3b, v105
	v_exp_f32_e32 v100, v100
	v_exp_f32_e32 v101, v101
	v_mul_f32_e32 v102, 0xbfb8aa3b, v106
	v_mul_f32_e32 v103, 0xbfb8aa3b, v107
	v_exp_f32_e32 v102, v102
	v_pk_add_f32 v[100:101], v[100:101], 1.0 op_sel_hi:[1,0]
	v_exp_f32_e32 v103, v103
	s_nop 0
	v_pk_add_f32 v[102:103], v[102:103], 1.0 op_sel_hi:[1,0]
	v_mul_f32_e32 v96, 0xbfb8aa3b, v96
	v_mul_f32_e32 v97, 0xbfb8aa3b, v97
	v_rcp_f32_e32 v101, v101
	v_exp_f32_e32 v96, v96
	v_rcp_f32_e32 v100, v100
	v_exp_f32_e32 v97, v97
	v_rcp_f32_e32 v103, v103
	v_pk_add_f32 v[96:97], v[96:97], 1.0 op_sel_hi:[1,0]
	v_rcp_f32_e32 v102, v102
	v_mul_f32_e32 v98, 0xbfb8aa3b, v98
	v_mul_f32_e32 v99, 0xbfb8aa3b, v99
	v_exp_f32_e32 v98, v98
	v_exp_f32_e32 v99, v99
	v_rcp_f32_e32 v97, v97
	v_pk_add_f32 v[98:99], v[98:99], 1.0 op_sel_hi:[1,0]
	v_rcp_f32_e32 v96, v96
	v_pk_mul_f32 v[102:103], v[102:103], s[14:15] op_sel_hi:[1,0]
	v_rcp_f32_e32 v99, v99
	v_pk_mul_f32 v[100:101], v[100:101], s[14:15] op_sel_hi:[1,0]
	v_rcp_f32_e32 v98, v98
	s_nop 0
	v_pk_mul_f32 v[110:111], v[98:99], s[14:15] op_sel_hi:[1,0]
	v_pk_mul_f32 v[108:109], v[96:97], s[14:15] op_sel_hi:[1,0]
.LBB0_808:
	v_add_u32_e32 v104, 0x80, v156
	v_ashrrev_i32_e32 v105, 31, v104
	v_cvt_pk_bf16_f32 v96, v100, v101
	v_lshlrev_b64 v[100:101], 11, v[104:105]
	v_cvt_pk_bf16_f32 v97, v102, v103
	v_cvt_pk_bf16_f32 v98, v108, v109
	v_cvt_pk_bf16_f32 v99, v110, v111
	v_lshl_add_u64 v[104:105], v[138:139], 0, v[100:101]
	global_store_dwordx4 v[104:105], v[96:99], off
	v_pk_add_f32 v[90:91], v[90:91], v[82:83]
	v_pk_add_f32 v[88:89], v[88:89], v[80:81]
	v_pk_add_f32 v[98:99], v[94:95], v[86:87]
	v_pk_add_f32 v[96:97], v[92:93], v[84:85]
	s_and_b64 vcc, exec, s[4:5]
	s_mov_b64 s[52:53], -1
	s_cbranch_vccnz .LBB0_812
	v_mov_b64_e32 v[102:103], v[90:91]
	v_mov_b64_e32 v[92:93], v[96:97]
	s_and_b64 vcc, exec, s[2:3]
	v_mov_b64_e32 v[100:101], v[88:89]
	v_mov_b64_e32 v[94:95], v[98:99]
	s_cbranch_vccnz .LBB0_811
	v_mul_f32_e32 v92, 0xbfb8aa3b, v98
	v_mul_f32_e32 v93, 0xbfb8aa3b, v99
	v_exp_f32_e32 v92, v92
	v_exp_f32_e32 v93, v93
	v_mul_f32_e32 v94, 0xbfb8aa3b, v96
	v_mul_f32_e32 v95, 0xbfb8aa3b, v97
	v_exp_f32_e32 v94, v94
	v_pk_add_f32 v[92:93], v[92:93], 1.0 op_sel_hi:[1,0]
	v_exp_f32_e32 v95, v95
	s_nop 0
	v_pk_add_f32 v[100:101], v[94:95], 1.0 op_sel_hi:[1,0]
	v_mul_f32_e32 v107, 0xbfb8aa3b, v89
	v_exp_f32_e32 v107, v107
	v_rcp_f32_e32 v95, v93
	v_rcp_f32_e32 v94, v92
	v_rcp_f32_e32 v93, v101
	v_mul_f32_e32 v106, 0xbfb8aa3b, v88
	v_mul_f32_e32 v102, 0xbfb8aa3b, v90
	v_mul_f32_e32 v103, 0xbfb8aa3b, v91
	v_exp_f32_e32 v102, v102
	v_exp_f32_e32 v103, v103
	v_exp_f32_e32 v106, v106
	v_rcp_f32_e32 v92, v100
	v_pk_add_f32 v[102:103], v[102:103], 1.0 op_sel_hi:[1,0]
	v_pk_add_f32 v[100:101], v[106:107], 1.0 op_sel_hi:[1,0]
	s_nop 0
	v_rcp_f32_e32 v103, v103
	v_rcp_f32_e32 v102, v102
	v_rcp_f32_e32 v101, v101
	v_rcp_f32_e32 v100, v100

; __device__ __forceinline__ unsigned cvt_pk_bf16(float lo, float hi) { const f32x2 v = {lo, hi}; return __builtin_bit_cast(unsigned, __builtin_convertvector(v, bf16x2_t)); }
; __device__ __forceinline__ float sigm(float x) { return 1.0f / (1.0f + __expf(-x)); }
; __device__ __forceinline__ float decay_e(float pre) { return 0.6065306597126334f * sigm(pre); }
;     __device__ __forceinline__ void operator()(AccRef acc, const Unit& u, int wr, int wc, int fr, int fq) const {
;     ...
;                 for (int m = 0; m < 4; ++m) { f32x4 v0 = acc[ai][bj][m][0] + b0, v1 = acc[ai][bj][m][1] + b1;
;                     if (kind == 0) { v0 = (f32x4){decay_e(v0[0]), decay_e(v0[1]), decay_e(v0[2]), decay_e(v0[3])}; v1 = (f32x4){decay_e(v1[0]), decay_e(v1[1]), decay_e(v1[2]), decay_e(v1[3])}; }
;                     else if (kind == 1) { v0 = (f32x4){sigm(v0[0]), sigm(v0[1]), sigm(v0[2]), sigm(v0[3])}; v1 = (f32x4){sigm(v1[0]), sigm(v1[1]), sigm(v1[2]), sigm(v1[3])}; }
;                     u32x4 w; w.x = cvt_pk_bf16(v0[0], v0[1]); w.y = cvt_pk_bf16(v0[2], v0[3]); w.z = cvt_pk_bf16(v1[0], v1[1]); w.w = cvt_pk_bf16(v1[2], v1[3]);
;                     *(u32x4*)(base + (size_t)EPI_ROWS(ai, m) * D + colt + bj * HALF) = w; }
.LBB0_812:
	s_andn2_b64 vcc, exec, s[52:53]
	s_cbranch_vccnz .LBB0_814
	v_mul_f32_e32 v92, 0xbfb8aa3b, v96
	v_mul_f32_e32 v93, 0xbfb8aa3b, v97
	v_exp_f32_e32 v92, v92
	v_exp_f32_e32 v93, v93
	v_mul_f32_e32 v94, 0xbfb8aa3b, v98
	v_mul_f32_e32 v95, 0xbfb8aa3b, v99
	v_exp_f32_e32 v94, v94
	v_pk_add_f32 v[92:93], v[92:93], 1.0 op_sel_hi:[1,0]
	v_exp_f32_e32 v95, v95
	s_nop 0
	v_pk_add_f32 v[94:95], v[94:95], 1.0 op_sel_hi:[1,0]
	v_mul_f32_e32 v88, 0xbfb8aa3b, v88
	v_mul_f32_e32 v89, 0xbfb8aa3b, v89
	v_rcp_f32_e32 v93, v93
	v_exp_f32_e32 v88, v88
	v_rcp_f32_e32 v92, v92
	v_exp_f32_e32 v89, v89
	v_rcp_f32_e32 v95, v95
	v_pk_add_f32 v[88:89], v[88:89], 1.0 op_sel_hi:[1,0]
	v_rcp_f32_e32 v94, v94
	v_mul_f32_e32 v90, 0xbfb8aa3b, v90
	v_mul_f32_e32 v91, 0xbfb8aa3b, v91
	v_exp_f32_e32 v90, v90
	v_exp_f32_e32 v91, v91
	v_rcp_f32_e32 v89, v89
	v_pk_add_f32 v[90:91], v[90:91], 1.0 op_sel_hi:[1,0]
	v_rcp_f32_e32 v88, v88
	v_pk_mul_f32 v[94:95], v[94:95], s[14:15] op_sel_hi:[1,0]
	v_rcp_f32_e32 v91, v91
	v_pk_mul_f32 v[92:93], v[92:93], s[14:15] op_sel_hi:[1,0]
	v_rcp_f32_e32 v90, v90
	s_nop 0
	v_pk_mul_f32 v[102:103], v[90:91], s[14:15] op_sel_hi:[1,0]
	v_pk_mul_f32 v[100:101], v[88:89], s[14:15] op_sel_hi:[1,0]
.LBB0_814:
	v_cvt_pk_bf16_f32 v88, v92, v93
	v_add_u32_e32 v92, 0x90, v156
	v_ashrrev_i32_e32 v93, 31, v92
	v_lshlrev_b64 v[92:93], 11, v[92:93]
	v_cvt_pk_bf16_f32 v89, v94, v95
	v_cvt_pk_bf16_f32 v90, v100, v101
	v_cvt_pk_bf16_f32 v91, v102, v103
	v_lshl_add_u64 v[96:97], v[138:139], 0, v[92:93]
	global_store_dwordx4 v[96:97], v[88:91], off
	v_pk_add_f32 v[74:75], v[74:75], v[82:83]
	v_pk_add_f32 v[72:73], v[72:73], v[80:81]
	v_pk_add_f32 v[90:91], v[78:79], v[86:87]
	v_pk_add_f32 v[88:89], v[76:77], v[84:85]
	s_and_b64 vcc, exec, s[4:5]
	s_mov_b64 s[52:53], -1
	s_cbranch_vccnz .LBB0_818
	v_mov_b64_e32 v[94:95], v[74:75]
	v_mov_b64_e32 v[76:77], v[88:89]
	s_and_b64 vcc, exec, s[2:3]
	v_mov_b64_e32 v[92:93], v[72:73]
	v_mov_b64_e32 v[78:79], v[90:91]
	s_cbranch_vccnz .LBB0_817
	v_mul_f32_e32 v76, 0xbfb8aa3b, v90
	v_mul_f32_e32 v77, 0xbfb8aa3b, v91
	v_exp_f32_e32 v76, v76
	v_exp_f32_e32 v77, v77
	v_mul_f32_e32 v78, 0xbfb8aa3b, v88
	v_mul_f32_e32 v79, 0xbfb8aa3b, v89
	v_exp_f32_e32 v78, v78
	v_pk_add_f32 v[76:77], v[76:77], 1.0 op_sel_hi:[1,0]
	v_exp_f32_e32 v79, v79
	s_nop 0
	v_pk_add_f32 v[92:93], v[78:79], 1.0 op_sel_hi:[1,0]
	v_mul_f32_e32 v99, 0xbfb8aa3b, v73
	v_exp_f32_e32 v99, v99
	v_rcp_f32_e32 v79, v77
	v_rcp_f32_e32 v78, v76
	v_rcp_f32_e32 v77, v93
	v_mul_f32_e32 v98, 0xbfb8aa3b, v72
	v_mul_f32_e32 v94, 0xbfb8aa3b, v74
	v_mul_f32_e32 v95, 0xbfb8aa3b, v75
	v_exp_f32_e32 v94, v94
	v_exp_f32_e32 v95, v95
	v_exp_f32_e32 v98, v98
	v_rcp_f32_e32 v76, v92
	v_pk_add_f32 v[94:95], v[94:95], 1.0 op_sel_hi:[1,0]
	v_pk_add_f32 v[92:93], v[98:99], 1.0 op_sel_hi:[1,0]
	s_nop 0
	v_rcp_f32_e32 v95, v95
	v_rcp_f32_e32 v94, v94
	v_rcp_f32_e32 v93, v93
	v_rcp_f32_e32 v92, v92

; __device__ __forceinline__ unsigned cvt_pk_bf16(float lo, float hi) { const f32x2 v = {lo, hi}; return __builtin_bit_cast(unsigned, __builtin_convertvector(v, bf16x2_t)); }
; __device__ __forceinline__ float sigm(float x) { return 1.0f / (1.0f + __expf(-x)); }
; __device__ __forceinline__ float decay_e(float pre) { return 0.6065306597126334f * sigm(pre); }
;     __device__ __forceinline__ void operator()(AccRef acc, const Unit& u, int wr, int wc, int fr, int fq) const {
;     ...
;                 for (int m = 0; m < 4; ++m) { f32x4 v0 = acc[ai][bj][m][0] + b0, v1 = acc[ai][bj][m][1] + b1;
;                     if (kind == 0) { v0 = (f32x4){decay_e(v0[0]), decay_e(v0[1]), decay_e(v0[2]), decay_e(v0[3])}; v1 = (f32x4){decay_e(v1[0]), decay_e(v1[1]), decay_e(v1[2]), decay_e(v1[3])}; }
;                     else if (kind == 1) { v0 = (f32x4){sigm(v0[0]), sigm(v0[1]), sigm(v0[2]), sigm(v0[3])}; v1 = (f32x4){sigm(v1[0]), sigm(v1[1]), sigm(v1[2]), sigm(v1[3])}; }
;                     u32x4 w; w.x = cvt_pk_bf16(v0[0], v0[1]); w.y = cvt_pk_bf16(v0[2], v0[3]); w.z = cvt_pk_bf16(v1[0], v1[1]); w.w = cvt_pk_bf16(v1[2], v1[3]);
;                     *(u32x4*)(base + (size_t)EPI_ROWS(ai, m) * D + colt + bj * HALF) = w; }
.LBB0_818:
	s_andn2_b64 vcc, exec, s[52:53]
	s_cbranch_vccnz .LBB0_820
	v_mul_f32_e32 v76, 0xbfb8aa3b, v88
	v_mul_f32_e32 v77, 0xbfb8aa3b, v89
	v_exp_f32_e32 v76, v76
	v_exp_f32_e32 v77, v77
	v_mul_f32_e32 v78, 0xbfb8aa3b, v90
	v_mul_f32_e32 v79, 0xbfb8aa3b, v91
	v_exp_f32_e32 v78, v78
	v_pk_add_f32 v[76:77], v[76:77], 1.0 op_sel_hi:[1,0]
	v_exp_f32_e32 v79, v79
	s_nop 0
	v_pk_add_f32 v[78:79], v[78:79], 1.0 op_sel_hi:[1,0]
	v_mul_f32_e32 v72, 0xbfb8aa3b, v72
	v_mul_f32_e32 v73, 0xbfb8aa3b, v73
	v_rcp_f32_e32 v77, v77
	v_exp_f32_e32 v72, v72
	v_rcp_f32_e32 v76, v76
	v_exp_f32_e32 v73, v73
	v_rcp_f32_e32 v79, v79
	v_pk_add_f32 v[72:73], v[72:73], 1.0 op_sel_hi:[1,0]
	v_rcp_f32_e32 v78, v78
	v_mul_f32_e32 v74, 0xbfb8aa3b, v74
	v_mul_f32_e32 v75, 0xbfb8aa3b, v75
	v_exp_f32_e32 v74, v74
	v_exp_f32_e32 v75, v75
	v_rcp_f32_e32 v73, v73
	v_pk_add_f32 v[74:75], v[74:75], 1.0 op_sel_hi:[1,0]
	v_rcp_f32_e32 v72, v72
	v_pk_mul_f32 v[78:79], v[78:79], s[14:15] op_sel_hi:[1,0]
	v_rcp_f32_e32 v75, v75
	v_pk_mul_f32 v[76:77], v[76:77], s[14:15] op_sel_hi:[1,0]
	v_rcp_f32_e32 v74, v74
	s_nop 0
	v_pk_mul_f32 v[94:95], v[74:75], s[14:15] op_sel_hi:[1,0]
	v_pk_mul_f32 v[92:93], v[72:73], s[14:15] op_sel_hi:[1,0]
.LBB0_820:
	v_cvt_pk_bf16_f32 v72, v76, v77
	v_add_u32_e32 v76, 0xa0, v156
	v_ashrrev_i32_e32 v77, 31, v76
	v_lshlrev_b64 v[76:77], 11, v[76:77]
	v_cvt_pk_bf16_f32 v73, v78, v79
	v_cvt_pk_bf16_f32 v74, v92, v93
	v_cvt_pk_bf16_f32 v75, v94, v95
	v_lshl_add_u64 v[88:89], v[138:139], 0, v[76:77]
	global_store_dwordx4 v[88:89], v[72:75], off
	v_pk_add_f32 v[66:67], v[66:67], v[82:83]
	v_pk_add_f32 v[64:65], v[64:65], v[80:81]
	v_pk_add_f32 v[74:75], v[70:71], v[86:87]
	v_pk_add_f32 v[72:73], v[68:69], v[84:85]
	s_and_b64 vcc, exec, s[4:5]
	s_mov_b64 s[52:53], -1
	s_cbranch_vccnz .LBB0_824
	v_mov_b64_e32 v[78:79], v[66:67]
	v_mov_b64_e32 v[68:69], v[72:73]
	s_and_b64 vcc, exec, s[2:3]
	v_mov_b64_e32 v[76:77], v[64:65]
	v_mov_b64_e32 v[70:71], v[74:75]
	s_cbranch_vccnz .LBB0_823
	v_mul_f32_e32 v68, 0xbfb8aa3b, v74
	v_mul_f32_e32 v69, 0xbfb8aa3b, v75
	v_exp_f32_e32 v68, v68
	v_exp_f32_e32 v69, v69
	v_mul_f32_e32 v70, 0xbfb8aa3b, v72
	v_mul_f32_e32 v71, 0xbfb8aa3b, v73
	v_exp_f32_e32 v70, v70
	v_pk_add_f32 v[68:69], v[68:69], 1.0 op_sel_hi:[1,0]
	v_exp_f32_e32 v71, v71
	s_nop 0
	v_pk_add_f32 v[76:77], v[70:71], 1.0 op_sel_hi:[1,0]
	v_mul_f32_e32 v81, 0xbfb8aa3b, v65
	v_exp_f32_e32 v81, v81
	v_rcp_f32_e32 v71, v69
	v_rcp_f32_e32 v70, v68
	v_rcp_f32_e32 v69, v77
	v_mul_f32_e32 v80, 0xbfb8aa3b, v64
	v_mul_f32_e32 v78, 0xbfb8aa3b, v66
	v_mul_f32_e32 v79, 0xbfb8aa3b, v67
	v_exp_f32_e32 v78, v78
	v_exp_f32_e32 v79, v79
	v_exp_f32_e32 v80, v80
	v_rcp_f32_e32 v68, v76
	v_pk_add_f32 v[78:79], v[78:79], 1.0 op_sel_hi:[1,0]
	v_pk_add_f32 v[76:77], v[80:81], 1.0 op_sel_hi:[1,0]
	s_nop 0
	v_rcp_f32_e32 v79, v79
	v_rcp_f32_e32 v78, v78
	v_rcp_f32_e32 v77, v77
	v_rcp_f32_e32 v76, v76

; __device__ __forceinline__ float sigm(float x) { return 1.0f / (1.0f + __expf(-x)); }
; __device__ __forceinline__ float decay_e(float pre) { return 0.6065306597126334f * sigm(pre); }
;     __device__ __forceinline__ void operator()(AccRef acc, const Unit& u, int wr, int wc, int fr, int fq) const {
;     ...
;                 for (int m = 0; m < 4; ++m) { f32x4 v0 = acc[ai][bj][m][0] + b0, v1 = acc[ai][bj][m][1] + b1;
;                     if (kind == 0) { v0 = (f32x4){decay_e(v0[0]), decay_e(v0[1]), decay_e(v0[2]), decay_e(v0[3])}; v1 = (f32x4){decay_e(v1[0]), decay_e(v1[1]), decay_e(v1[2]), decay_e(v1[3])}; }
;                     else if (kind == 1) { v0 = (f32x4){sigm(v0[0]), sigm(v0[1]), sigm(v0[2]), sigm(v0[3])}; v1 = (f32x4){sigm(v1[0]), sigm(v1[1]), sigm(v1[2]), sigm(v1[3])}; }
.LBB0_824:
	s_andn2_b64 vcc, exec, s[52:53]
	s_cbranch_vccnz .LBB0_826
	v_mul_f32_e32 v68, 0xbfb8aa3b, v72
	v_mul_f32_e32 v69, 0xbfb8aa3b, v73
	v_exp_f32_e32 v68, v68
	v_exp_f32_e32 v69, v69
	v_mul_f32_e32 v70, 0xbfb8aa3b, v74
	v_mul_f32_e32 v71, 0xbfb8aa3b, v75
	v_exp_f32_e32 v70, v70
	v_pk_add_f32 v[68:69], v[68:69], 1.0 op_sel_hi:[1,0]
	v_exp_f32_e32 v71, v71
	s_nop 0
	v_pk_add_f32 v[70:71], v[70:71], 1.0 op_sel_hi:[1,0]
	v_mul_f32_e32 v64, 0xbfb8aa3b, v64
	v_mul_f32_e32 v65, 0xbfb8aa3b, v65
	v_rcp_f32_e32 v69, v69
	v_exp_f32_e32 v64, v64
	v_rcp_f32_e32 v68, v68
	v_exp_f32_e32 v65, v65
	v_rcp_f32_e32 v71, v71
	v_pk_add_f32 v[64:65], v[64:65], 1.0 op_sel_hi:[1,0]
	v_rcp_f32_e32 v70, v70
	v_mul_f32_e32 v66, 0xbfb8aa3b, v66
	v_mul_f32_e32 v67, 0xbfb8aa3b, v67
	v_exp_f32_e32 v66, v66
	v_exp_f32_e32 v67, v67
	v_rcp_f32_e32 v65, v65
	v_pk_add_f32 v[66:67], v[66:67], 1.0 op_sel_hi:[1,0]
	v_rcp_f32_e32 v64, v64
	v_pk_mul_f32 v[70:71], v[70:71], s[14:15] op_sel_hi:[1,0]
	v_rcp_f32_e32 v67, v67
	v_pk_mul_f32 v[68:69], v[68:69], s[14:15] op_sel_hi:[1,0]
	v_rcp_f32_e32 v66, v66
	s_nop 0
	v_pk_mul_f32 v[78:79], v[66:67], s[14:15] op_sel_hi:[1,0]
	v_pk_mul_f32 v[76:77], v[64:65], s[14:15] op_sel_hi:[1,0]

; __device__ __forceinline__ float sigm(float x) { return 1.0f / (1.0f + __expf(-x)); }
; __device__ __forceinline__ float decay_e(float pre) { return 0.6065306597126334f * sigm(pre); }
;     __device__ __forceinline__ void operator()(AccRef acc, const Unit& u, int wr, int wc, int fr, int fq) const {
;     ...
;             if (kind < 2) { b0 = *(const f32x4*)(bias + colt + bj * HALF); b1 = *(const f32x4*)(bias + colt + bj * HALF + 4); }
; #pragma unroll
;             for (int ai = 0; ai < 2; ++ai)
; #pragma unroll
;                 for (int m = 0; m < 4; ++m) { f32x4 v0 = acc[ai][bj][m][0] + b0, v1 = acc[ai][bj][m][1] + b1;
;                     if (kind == 0) { v0 = (f32x4){decay_e(v0[0]), decay_e(v0[1]), decay_e(v0[2]), decay_e(v0[3])}; v1 = (f32x4){decay_e(v1[0]), decay_e(v1[1]), decay_e(v1[2]), decay_e(v1[3])}; }
;                     else if (kind == 1) { v0 = (f32x4){sigm(v0[0]), sigm(v0[1]), sigm(v0[2]), sigm(v0[3])}; v1 = (f32x4){sigm(v1[0]), sigm(v1[1]), sigm(v1[2]), sigm(v1[3])}; }
.LBB0_828:
	s_waitcnt vmcnt(0)
	v_pk_add_f32 v[74:75], v[62:63], v[70:71]
	v_pk_add_f32 v[72:73], v[60:61], v[68:69]
	v_pk_add_f32 v[58:59], v[58:59], v[66:67]
	v_pk_add_f32 v[56:57], v[56:57], v[64:65]
	s_and_b64 vcc, exec, s[4:5]
	s_mov_b64 s[46:47], -1
	s_cbranch_vccnz .LBB0_832
	v_mov_b64_e32 v[78:79], v[58:59]
	v_mov_b64_e32 v[60:61], v[72:73]
	s_and_b64 vcc, exec, s[2:3]
	v_mov_b64_e32 v[76:77], v[56:57]
	v_mov_b64_e32 v[62:63], v[74:75]
	s_cbranch_vccnz .LBB0_831
	v_mul_f32_e32 v60, 0xbfb8aa3b, v74
	v_mul_f32_e32 v61, 0xbfb8aa3b, v75
	v_exp_f32_e32 v60, v60
	v_exp_f32_e32 v61, v61
	v_mul_f32_e32 v62, 0xbfb8aa3b, v72
	v_mul_f32_e32 v63, 0xbfb8aa3b, v73
	v_exp_f32_e32 v62, v62
	v_pk_add_f32 v[60:61], v[60:61], 1.0 op_sel_hi:[1,0]
	v_exp_f32_e32 v63, v63
	s_nop 0
	v_pk_add_f32 v[76:77], v[62:63], 1.0 op_sel_hi:[1,0]
	v_mul_f32_e32 v83, 0xbfb8aa3b, v57
	v_exp_f32_e32 v83, v83
	v_rcp_f32_e32 v63, v61
	v_rcp_f32_e32 v62, v60
	v_rcp_f32_e32 v61, v77
	v_mul_f32_e32 v82, 0xbfb8aa3b, v56
	v_mul_f32_e32 v78, 0xbfb8aa3b, v58
	v_mul_f32_e32 v79, 0xbfb8aa3b, v59
	v_exp_f32_e32 v78, v78
	v_exp_f32_e32 v79, v79
	v_exp_f32_e32 v82, v82
	v_rcp_f32_e32 v60, v76
	v_pk_add_f32 v[78:79], v[78:79], 1.0 op_sel_hi:[1,0]
	v_pk_add_f32 v[76:77], v[82:83], 1.0 op_sel_hi:[1,0]
	s_nop 0
	v_rcp_f32_e32 v79, v79
	v_rcp_f32_e32 v78, v78
	v_rcp_f32_e32 v77, v77
	v_rcp_f32_e32 v76, v76

; __device__ __forceinline__ unsigned cvt_pk_bf16(float lo, float hi) { const f32x2 v = {lo, hi}; return __builtin_bit_cast(unsigned, __builtin_convertvector(v, bf16x2_t)); }
; __device__ __forceinline__ float sigm(float x) { return 1.0f / (1.0f + __expf(-x)); }
; __device__ __forceinline__ float decay_e(float pre) { return 0.6065306597126334f * sigm(pre); }
;     __device__ __forceinline__ void operator()(AccRef acc, const Unit& u, int wr, int wc, int fr, int fq) const {
;     ...
;                 for (int m = 0; m < 4; ++m) { f32x4 v0 = acc[ai][bj][m][0] + b0, v1 = acc[ai][bj][m][1] + b1;
;                     if (kind == 0) { v0 = (f32x4){decay_e(v0[0]), decay_e(v0[1]), decay_e(v0[2]), decay_e(v0[3])}; v1 = (f32x4){decay_e(v1[0]), decay_e(v1[1]), decay_e(v1[2]), decay_e(v1[3])}; }
;                     else if (kind == 1) { v0 = (f32x4){sigm(v0[0]), sigm(v0[1]), sigm(v0[2]), sigm(v0[3])}; v1 = (f32x4){sigm(v1[0]), sigm(v1[1]), sigm(v1[2]), sigm(v1[3])}; }
;                     u32x4 w; w.x = cvt_pk_bf16(v0[0], v0[1]); w.y = cvt_pk_bf16(v0[2], v0[3]); w.z = cvt_pk_bf16(v1[0], v1[1]); w.w = cvt_pk_bf16(v1[2], v1[3]);
;                     *(u32x4*)(base + (size_t)EPI_ROWS(ai, m) * D + colt + bj * HALF) = w; }
.LBB0_832:
	s_andn2_b64 vcc, exec, s[46:47]
	s_cbranch_vccnz .LBB0_834
	v_mul_f32_e32 v60, 0xbfb8aa3b, v72
	v_mul_f32_e32 v61, 0xbfb8aa3b, v73
	v_exp_f32_e32 v60, v60
	v_exp_f32_e32 v61, v61
	v_mul_f32_e32 v62, 0xbfb8aa3b, v74
	v_mul_f32_e32 v63, 0xbfb8aa3b, v75
	v_exp_f32_e32 v62, v62
	v_pk_add_f32 v[60:61], v[60:61], 1.0 op_sel_hi:[1,0]
	v_exp_f32_e32 v63, v63
	s_nop 0
	v_pk_add_f32 v[62:63], v[62:63], 1.0 op_sel_hi:[1,0]
	v_mul_f32_e32 v56, 0xbfb8aa3b, v56
	v_mul_f32_e32 v57, 0xbfb8aa3b, v57
	v_rcp_f32_e32 v61, v61
	v_exp_f32_e32 v56, v56
	v_rcp_f32_e32 v60, v60
	v_exp_f32_e32 v57, v57
	v_rcp_f32_e32 v63, v63
	v_pk_add_f32 v[56:57], v[56:57], 1.0 op_sel_hi:[1,0]
	v_rcp_f32_e32 v62, v62
	v_mul_f32_e32 v58, 0xbfb8aa3b, v58
	v_mul_f32_e32 v59, 0xbfb8aa3b, v59
	v_exp_f32_e32 v58, v58
	v_exp_f32_e32 v59, v59
	v_rcp_f32_e32 v57, v57
	v_pk_add_f32 v[58:59], v[58:59], 1.0 op_sel_hi:[1,0]
	v_rcp_f32_e32 v56, v56
	v_pk_mul_f32 v[62:63], v[62:63], s[14:15] op_sel_hi:[1,0]
	v_rcp_f32_e32 v59, v59
	v_pk_mul_f32 v[60:61], v[60:61], s[14:15] op_sel_hi:[1,0]
	v_rcp_f32_e32 v58, v58
	s_nop 0
	v_pk_mul_f32 v[78:79], v[58:59], s[14:15] op_sel_hi:[1,0]
	v_pk_mul_f32 v[76:77], v[56:57], s[14:15] op_sel_hi:[1,0]
.LBB0_834:
	v_cvt_pk_bf16_f32 v56, v60, v61
	v_cvt_pk_bf16_f32 v57, v62, v63
	v_cvt_pk_bf16_f32 v58, v76, v77
	v_cvt_pk_bf16_f32 v59, v78, v79
	global_store_dwordx4 v[136:137], v[56:59], off offset:256
	v_pk_add_f32 v[50:51], v[50:51], v[66:67]
	v_pk_add_f32 v[48:49], v[48:49], v[64:65]
	v_pk_add_f32 v[58:59], v[54:55], v[70:71]
	v_pk_add_f32 v[56:57], v[52:53], v[68:69]
	s_and_b64 vcc, exec, s[4:5]
	s_mov_b64 s[46:47], -1
	s_cbranch_vccnz .LBB0_838
	v_mov_b64_e32 v[62:63], v[50:51]
	v_mov_b64_e32 v[52:53], v[56:57]
	s_and_b64 vcc, exec, s[2:3]
	v_mov_b64_e32 v[60:61], v[48:49]
	v_mov_b64_e32 v[54:55], v[58:59]
	s_cbranch_vccnz .LBB0_837
	v_mul_f32_e32 v52, 0xbfb8aa3b, v58
	v_mul_f32_e32 v53, 0xbfb8aa3b, v59
	v_exp_f32_e32 v52, v52
	v_exp_f32_e32 v53, v53
	v_mul_f32_e32 v54, 0xbfb8aa3b, v56
	v_mul_f32_e32 v55, 0xbfb8aa3b, v57
	v_exp_f32_e32 v54, v54
	v_pk_add_f32 v[52:53], v[52:53], 1.0 op_sel_hi:[1,0]
	v_exp_f32_e32 v55, v55
	s_nop 0
	v_pk_add_f32 v[60:61], v[54:55], 1.0 op_sel_hi:[1,0]
	v_mul_f32_e32 v73, 0xbfb8aa3b, v49
	v_exp_f32_e32 v73, v73
	v_rcp_f32_e32 v55, v53
	v_rcp_f32_e32 v54, v52
	v_rcp_f32_e32 v53, v61
	v_mul_f32_e32 v72, 0xbfb8aa3b, v48
	v_mul_f32_e32 v62, 0xbfb8aa3b, v50
	v_mul_f32_e32 v63, 0xbfb8aa3b, v51
	v_exp_f32_e32 v62, v62
	v_exp_f32_e32 v63, v63
	v_exp_f32_e32 v72, v72
	v_rcp_f32_e32 v52, v60
	v_pk_add_f32 v[62:63], v[62:63], 1.0 op_sel_hi:[1,0]
	v_pk_add_f32 v[60:61], v[72:73], 1.0 op_sel_hi:[1,0]
	s_nop 0
	v_rcp_f32_e32 v63, v63
	v_rcp_f32_e32 v62, v62
	v_rcp_f32_e32 v61, v61
	v_rcp_f32_e32 v60, v60

; __device__ __forceinline__ unsigned cvt_pk_bf16(float lo, float hi) { const f32x2 v = {lo, hi}; return __builtin_bit_cast(unsigned, __builtin_convertvector(v, bf16x2_t)); }
; __device__ __forceinline__ float sigm(float x) { return 1.0f / (1.0f + __expf(-x)); }
; __device__ __forceinline__ float decay_e(float pre) { return 0.6065306597126334f * sigm(pre); }
;     __device__ __forceinline__ void operator()(AccRef acc, const Unit& u, int wr, int wc, int fr, int fq) const {
;     ...
;                 for (int m = 0; m < 4; ++m) { f32x4 v0 = acc[ai][bj][m][0] + b0, v1 = acc[ai][bj][m][1] + b1;
;                     if (kind == 0) { v0 = (f32x4){decay_e(v0[0]), decay_e(v0[1]), decay_e(v0[2]), decay_e(v0[3])}; v1 = (f32x4){decay_e(v1[0]), decay_e(v1[1]), decay_e(v1[2]), decay_e(v1[3])}; }
;                     else if (kind == 1) { v0 = (f32x4){sigm(v0[0]), sigm(v0[1]), sigm(v0[2]), sigm(v0[3])}; v1 = (f32x4){sigm(v1[0]), sigm(v1[1]), sigm(v1[2]), sigm(v1[3])}; }
;                     u32x4 w; w.x = cvt_pk_bf16(v0[0], v0[1]); w.y = cvt_pk_bf16(v0[2], v0[3]); w.z = cvt_pk_bf16(v1[0], v1[1]); w.w = cvt_pk_bf16(v1[2], v1[3]);
;                     *(u32x4*)(base + (size_t)EPI_ROWS(ai, m) * D + colt + bj * HALF) = w; }
.LBB0_838:
	s_andn2_b64 vcc, exec, s[46:47]
	s_cbranch_vccnz .LBB0_840
	v_mul_f32_e32 v52, 0xbfb8aa3b, v56
	v_mul_f32_e32 v53, 0xbfb8aa3b, v57
	v_exp_f32_e32 v52, v52
	v_exp_f32_e32 v53, v53
	v_mul_f32_e32 v54, 0xbfb8aa3b, v58
	v_mul_f32_e32 v55, 0xbfb8aa3b, v59
	v_exp_f32_e32 v54, v54
	v_pk_add_f32 v[52:53], v[52:53], 1.0 op_sel_hi:[1,0]
	v_exp_f32_e32 v55, v55
	s_nop 0
	v_pk_add_f32 v[54:55], v[54:55], 1.0 op_sel_hi:[1,0]
	v_mul_f32_e32 v48, 0xbfb8aa3b, v48
	v_mul_f32_e32 v49, 0xbfb8aa3b, v49
	v_rcp_f32_e32 v53, v53
	v_exp_f32_e32 v48, v48
	v_rcp_f32_e32 v52, v52
	v_exp_f32_e32 v49, v49
	v_rcp_f32_e32 v55, v55
	v_pk_add_f32 v[48:49], v[48:49], 1.0 op_sel_hi:[1,0]
	v_rcp_f32_e32 v54, v54
	v_mul_f32_e32 v50, 0xbfb8aa3b, v50
	v_mul_f32_e32 v51, 0xbfb8aa3b, v51
	v_exp_f32_e32 v50, v50
	v_exp_f32_e32 v51, v51
	v_rcp_f32_e32 v49, v49
	v_pk_add_f32 v[50:51], v[50:51], 1.0 op_sel_hi:[1,0]
	v_rcp_f32_e32 v48, v48
	v_pk_mul_f32 v[54:55], v[54:55], s[14:15] op_sel_hi:[1,0]
	v_rcp_f32_e32 v51, v51
	v_pk_mul_f32 v[52:53], v[52:53], s[14:15] op_sel_hi:[1,0]
	v_rcp_f32_e32 v50, v50
	s_nop 0
	v_pk_mul_f32 v[62:63], v[50:51], s[14:15] op_sel_hi:[1,0]
	v_pk_mul_f32 v[60:61], v[48:49], s[14:15] op_sel_hi:[1,0]
.LBB0_840:
	v_cvt_pk_bf16_f32 v48, v52, v53
	v_cvt_pk_bf16_f32 v49, v54, v55
	v_cvt_pk_bf16_f32 v50, v60, v61
	v_cvt_pk_bf16_f32 v51, v62, v63
	global_store_dwordx4 v[128:129], v[48:51], off offset:256
	v_pk_add_f32 v[42:43], v[42:43], v[66:67]
	v_pk_add_f32 v[40:41], v[40:41], v[64:65]
	v_pk_add_f32 v[50:51], v[46:47], v[70:71]
	v_pk_add_f32 v[48:49], v[44:45], v[68:69]
	s_and_b64 vcc, exec, s[4:5]
	s_mov_b64 s[46:47], -1
	s_cbranch_vccnz .LBB0_844
	v_mov_b64_e32 v[54:55], v[42:43]
	v_mov_b64_e32 v[44:45], v[48:49]
	s_and_b64 vcc, exec, s[2:3]
	v_mov_b64_e32 v[52:53], v[40:41]
	v_mov_b64_e32 v[46:47], v[50:51]
	s_cbranch_vccnz .LBB0_843
	v_mul_f32_e32 v44, 0xbfb8aa3b, v50
	v_mul_f32_e32 v45, 0xbfb8aa3b, v51
	v_exp_f32_e32 v44, v44
	v_exp_f32_e32 v45, v45
	v_mul_f32_e32 v46, 0xbfb8aa3b, v48
	v_mul_f32_e32 v47, 0xbfb8aa3b, v49
	v_exp_f32_e32 v46, v46
	v_pk_add_f32 v[44:45], v[44:45], 1.0 op_sel_hi:[1,0]
	v_exp_f32_e32 v47, v47
	s_nop 0
	v_pk_add_f32 v[52:53], v[46:47], 1.0 op_sel_hi:[1,0]
	v_mul_f32_e32 v57, 0xbfb8aa3b, v41
	v_exp_f32_e32 v57, v57
	v_rcp_f32_e32 v47, v45
	v_rcp_f32_e32 v46, v44
	v_rcp_f32_e32 v45, v53
	v_mul_f32_e32 v56, 0xbfb8aa3b, v40
	v_mul_f32_e32 v54, 0xbfb8aa3b, v42
	v_mul_f32_e32 v55, 0xbfb8aa3b, v43
	v_exp_f32_e32 v54, v54
	v_exp_f32_e32 v55, v55
	v_exp_f32_e32 v56, v56
	v_rcp_f32_e32 v44, v52
	v_pk_add_f32 v[54:55], v[54:55], 1.0 op_sel_hi:[1,0]
	v_pk_add_f32 v[52:53], v[56:57], 1.0 op_sel_hi:[1,0]
	s_nop 0
	v_rcp_f32_e32 v55, v55
	v_rcp_f32_e32 v54, v54
	v_rcp_f32_e32 v53, v53
	v_rcp_f32_e32 v52, v52

; __device__ __forceinline__ unsigned cvt_pk_bf16(float lo, float hi) { const f32x2 v = {lo, hi}; return __builtin_bit_cast(unsigned, __builtin_convertvector(v, bf16x2_t)); }
; __device__ __forceinline__ float sigm(float x) { return 1.0f / (1.0f + __expf(-x)); }
; __device__ __forceinline__ float decay_e(float pre) { return 0.6065306597126334f * sigm(pre); }
;     __device__ __forceinline__ void operator()(AccRef acc, const Unit& u, int wr, int wc, int fr, int fq) const {
;     ...
;                 for (int m = 0; m < 4; ++m) { f32x4 v0 = acc[ai][bj][m][0] + b0, v1 = acc[ai][bj][m][1] + b1;
;                     if (kind == 0) { v0 = (f32x4){decay_e(v0[0]), decay_e(v0[1]), decay_e(v0[2]), decay_e(v0[3])}; v1 = (f32x4){decay_e(v1[0]), decay_e(v1[1]), decay_e(v1[2]), decay_e(v1[3])}; }
;                     else if (kind == 1) { v0 = (f32x4){sigm(v0[0]), sigm(v0[1]), sigm(v0[2]), sigm(v0[3])}; v1 = (f32x4){sigm(v1[0]), sigm(v1[1]), sigm(v1[2]), sigm(v1[3])}; }
;                     u32x4 w; w.x = cvt_pk_bf16(v0[0], v0[1]); w.y = cvt_pk_bf16(v0[2], v0[3]); w.z = cvt_pk_bf16(v1[0], v1[1]); w.w = cvt_pk_bf16(v1[2], v1[3]);
;                     *(u32x4*)(base + (size_t)EPI_ROWS(ai, m) * D + colt + bj * HALF) = w; }
.LBB0_844:
	s_andn2_b64 vcc, exec, s[46:47]
	s_cbranch_vccnz .LBB0_846
	v_mul_f32_e32 v44, 0xbfb8aa3b, v48
	v_mul_f32_e32 v45, 0xbfb8aa3b, v49
	v_exp_f32_e32 v44, v44
	v_exp_f32_e32 v45, v45
	v_mul_f32_e32 v46, 0xbfb8aa3b, v50
	v_mul_f32_e32 v47, 0xbfb8aa3b, v51
	v_exp_f32_e32 v46, v46
	v_pk_add_f32 v[44:45], v[44:45], 1.0 op_sel_hi:[1,0]
	v_exp_f32_e32 v47, v47
	s_nop 0
	v_pk_add_f32 v[46:47], v[46:47], 1.0 op_sel_hi:[1,0]
	v_mul_f32_e32 v40, 0xbfb8aa3b, v40
	v_mul_f32_e32 v41, 0xbfb8aa3b, v41
	v_rcp_f32_e32 v45, v45
	v_exp_f32_e32 v40, v40
	v_rcp_f32_e32 v44, v44
	v_exp_f32_e32 v41, v41
	v_rcp_f32_e32 v47, v47
	v_pk_add_f32 v[40:41], v[40:41], 1.0 op_sel_hi:[1,0]
	v_rcp_f32_e32 v46, v46
	v_mul_f32_e32 v42, 0xbfb8aa3b, v42
	v_mul_f32_e32 v43, 0xbfb8aa3b, v43
	v_exp_f32_e32 v42, v42
	v_exp_f32_e32 v43, v43
	v_rcp_f32_e32 v41, v41
	v_pk_add_f32 v[42:43], v[42:43], 1.0 op_sel_hi:[1,0]
	v_rcp_f32_e32 v40, v40
	v_pk_mul_f32 v[46:47], v[46:47], s[14:15] op_sel_hi:[1,0]
	v_rcp_f32_e32 v43, v43
	v_pk_mul_f32 v[44:45], v[44:45], s[14:15] op_sel_hi:[1,0]
	v_rcp_f32_e32 v42, v42
	s_nop 0
	v_pk_mul_f32 v[54:55], v[42:43], s[14:15] op_sel_hi:[1,0]
	v_pk_mul_f32 v[52:53], v[40:41], s[14:15] op_sel_hi:[1,0]
.LBB0_846:
	v_cvt_pk_bf16_f32 v40, v44, v45
	v_cvt_pk_bf16_f32 v41, v46, v47
	v_cvt_pk_bf16_f32 v42, v52, v53
	v_cvt_pk_bf16_f32 v43, v54, v55
	global_store_dwordx4 v[120:121], v[40:43], off offset:256
	v_pk_add_f32 v[34:35], v[34:35], v[66:67]
	v_pk_add_f32 v[32:33], v[32:33], v[64:65]
	v_pk_add_f32 v[42:43], v[38:39], v[70:71]
	v_pk_add_f32 v[40:41], v[36:37], v[68:69]
	s_and_b64 vcc, exec, s[4:5]
	s_mov_b64 s[46:47], -1
	s_cbranch_vccnz .LBB0_850
	v_mov_b64_e32 v[46:47], v[34:35]
	v_mov_b64_e32 v[36:37], v[40:41]
	s_and_b64 vcc, exec, s[2:3]
	v_mov_b64_e32 v[44:45], v[32:33]
	v_mov_b64_e32 v[38:39], v[42:43]
	s_cbranch_vccnz .LBB0_849
	v_mul_f32_e32 v36, 0xbfb8aa3b, v42
	v_mul_f32_e32 v37, 0xbfb8aa3b, v43
	v_exp_f32_e32 v36, v36
	v_exp_f32_e32 v37, v37
	v_mul_f32_e32 v38, 0xbfb8aa3b, v40
	v_mul_f32_e32 v39, 0xbfb8aa3b, v41
	v_exp_f32_e32 v38, v38
	v_pk_add_f32 v[36:37], v[36:37], 1.0 op_sel_hi:[1,0]
	v_exp_f32_e32 v39, v39
	s_nop 0
	v_pk_add_f32 v[44:45], v[38:39], 1.0 op_sel_hi:[1,0]
	v_mul_f32_e32 v49, 0xbfb8aa3b, v33
	v_exp_f32_e32 v49, v49
	v_rcp_f32_e32 v39, v37
	v_rcp_f32_e32 v38, v36
	v_rcp_f32_e32 v37, v45
	v_mul_f32_e32 v48, 0xbfb8aa3b, v32
	v_mul_f32_e32 v46, 0xbfb8aa3b, v34
	v_mul_f32_e32 v47, 0xbfb8aa3b, v35
	v_exp_f32_e32 v46, v46
	v_exp_f32_e32 v47, v47
	v_exp_f32_e32 v48, v48
	v_rcp_f32_e32 v36, v44
	v_pk_add_f32 v[46:47], v[46:47], 1.0 op_sel_hi:[1,0]
	v_pk_add_f32 v[44:45], v[48:49], 1.0 op_sel_hi:[1,0]
	s_nop 0
	v_rcp_f32_e32 v47, v47
	v_rcp_f32_e32 v46, v46
	v_rcp_f32_e32 v45, v45
	v_rcp_f32_e32 v44, v44

; __device__ __forceinline__ unsigned cvt_pk_bf16(float lo, float hi) { const f32x2 v = {lo, hi}; return __builtin_bit_cast(unsigned, __builtin_convertvector(v, bf16x2_t)); }
; __device__ __forceinline__ float sigm(float x) { return 1.0f / (1.0f + __expf(-x)); }
; __device__ __forceinline__ float decay_e(float pre) { return 0.6065306597126334f * sigm(pre); }
;     __device__ __forceinline__ void operator()(AccRef acc, const Unit& u, int wr, int wc, int fr, int fq) const {
;     ...
;                 for (int m = 0; m < 4; ++m) { f32x4 v0 = acc[ai][bj][m][0] + b0, v1 = acc[ai][bj][m][1] + b1;
;                     if (kind == 0) { v0 = (f32x4){decay_e(v0[0]), decay_e(v0[1]), decay_e(v0[2]), decay_e(v0[3])}; v1 = (f32x4){decay_e(v1[0]), decay_e(v1[1]), decay_e(v1[2]), decay_e(v1[3])}; }
;                     else if (kind == 1) { v0 = (f32x4){sigm(v0[0]), sigm(v0[1]), sigm(v0[2]), sigm(v0[3])}; v1 = (f32x4){sigm(v1[0]), sigm(v1[1]), sigm(v1[2]), sigm(v1[3])}; }
;                     u32x4 w; w.x = cvt_pk_bf16(v0[0], v0[1]); w.y = cvt_pk_bf16(v0[2], v0[3]); w.z = cvt_pk_bf16(v1[0], v1[1]); w.w = cvt_pk_bf16(v1[2], v1[3]);
;                     *(u32x4*)(base + (size_t)EPI_ROWS(ai, m) * D + colt + bj * HALF) = w; }
.LBB0_850:
	s_andn2_b64 vcc, exec, s[46:47]
	s_cbranch_vccnz .LBB0_852
	v_mul_f32_e32 v36, 0xbfb8aa3b, v40
	v_mul_f32_e32 v37, 0xbfb8aa3b, v41
	v_exp_f32_e32 v36, v36
	v_exp_f32_e32 v37, v37
	v_mul_f32_e32 v38, 0xbfb8aa3b, v42
	v_mul_f32_e32 v39, 0xbfb8aa3b, v43
	v_exp_f32_e32 v38, v38
	v_pk_add_f32 v[36:37], v[36:37], 1.0 op_sel_hi:[1,0]
	v_exp_f32_e32 v39, v39
	s_nop 0
	v_pk_add_f32 v[38:39], v[38:39], 1.0 op_sel_hi:[1,0]
	v_mul_f32_e32 v32, 0xbfb8aa3b, v32
	v_mul_f32_e32 v33, 0xbfb8aa3b, v33
	v_rcp_f32_e32 v37, v37
	v_exp_f32_e32 v32, v32
	v_rcp_f32_e32 v36, v36
	v_exp_f32_e32 v33, v33
	v_rcp_f32_e32 v39, v39
	v_pk_add_f32 v[32:33], v[32:33], 1.0 op_sel_hi:[1,0]
	v_rcp_f32_e32 v38, v38
	v_mul_f32_e32 v34, 0xbfb8aa3b, v34
	v_mul_f32_e32 v35, 0xbfb8aa3b, v35
	v_exp_f32_e32 v34, v34
	v_exp_f32_e32 v35, v35
	v_rcp_f32_e32 v33, v33
	v_pk_add_f32 v[34:35], v[34:35], 1.0 op_sel_hi:[1,0]
	v_rcp_f32_e32 v32, v32
	v_pk_mul_f32 v[38:39], v[38:39], s[14:15] op_sel_hi:[1,0]
	v_rcp_f32_e32 v35, v35
	v_pk_mul_f32 v[36:37], v[36:37], s[14:15] op_sel_hi:[1,0]
	v_rcp_f32_e32 v34, v34
	s_nop 0
	v_pk_mul_f32 v[46:47], v[34:35], s[14:15] op_sel_hi:[1,0]
	v_pk_mul_f32 v[44:45], v[32:33], s[14:15] op_sel_hi:[1,0]
.LBB0_852:
	v_cvt_pk_bf16_f32 v32, v36, v37
	v_cvt_pk_bf16_f32 v33, v38, v39
	v_cvt_pk_bf16_f32 v34, v44, v45
	v_cvt_pk_bf16_f32 v35, v46, v47
	global_store_dwordx4 v[112:113], v[32:35], off offset:256
	v_pk_add_f32 v[26:27], v[26:27], v[66:67]
	v_pk_add_f32 v[24:25], v[24:25], v[64:65]
	v_pk_add_f32 v[34:35], v[30:31], v[70:71]
	v_pk_add_f32 v[32:33], v[28:29], v[68:69]
	s_and_b64 vcc, exec, s[4:5]
	s_mov_b64 s[46:47], -1
	s_cbranch_vccnz .LBB0_856
	v_mov_b64_e32 v[38:39], v[26:27]
	v_mov_b64_e32 v[28:29], v[32:33]
	s_and_b64 vcc, exec, s[2:3]
	v_mov_b64_e32 v[36:37], v[24:25]
	v_mov_b64_e32 v[30:31], v[34:35]
	s_cbranch_vccnz .LBB0_855
	v_mul_f32_e32 v28, 0xbfb8aa3b, v34
	v_mul_f32_e32 v29, 0xbfb8aa3b, v35
	v_exp_f32_e32 v28, v28
	v_exp_f32_e32 v29, v29
	v_mul_f32_e32 v30, 0xbfb8aa3b, v32
	v_mul_f32_e32 v31, 0xbfb8aa3b, v33
	v_exp_f32_e32 v30, v30
	v_pk_add_f32 v[28:29], v[28:29], 1.0 op_sel_hi:[1,0]
	v_exp_f32_e32 v31, v31
	s_nop 0
	v_pk_add_f32 v[36:37], v[30:31], 1.0 op_sel_hi:[1,0]
	v_mul_f32_e32 v41, 0xbfb8aa3b, v25
	v_exp_f32_e32 v41, v41
	v_rcp_f32_e32 v31, v29
	v_rcp_f32_e32 v30, v28
	v_rcp_f32_e32 v29, v37
	v_mul_f32_e32 v40, 0xbfb8aa3b, v24
	v_mul_f32_e32 v38, 0xbfb8aa3b, v26
	v_mul_f32_e32 v39, 0xbfb8aa3b, v27
	v_exp_f32_e32 v38, v38
	v_exp_f32_e32 v39, v39
	v_exp_f32_e32 v40, v40
	v_rcp_f32_e32 v28, v36
	v_pk_add_f32 v[38:39], v[38:39], 1.0 op_sel_hi:[1,0]
	v_pk_add_f32 v[36:37], v[40:41], 1.0 op_sel_hi:[1,0]
	s_nop 0
	v_rcp_f32_e32 v39, v39
	v_rcp_f32_e32 v38, v38
	v_rcp_f32_e32 v37, v37
	v_rcp_f32_e32 v36, v36

; __device__ __forceinline__ unsigned cvt_pk_bf16(float lo, float hi) { const f32x2 v = {lo, hi}; return __builtin_bit_cast(unsigned, __builtin_convertvector(v, bf16x2_t)); }
; __device__ __forceinline__ float sigm(float x) { return 1.0f / (1.0f + __expf(-x)); }
; __device__ __forceinline__ float decay_e(float pre) { return 0.6065306597126334f * sigm(pre); }
;     __device__ __forceinline__ void operator()(AccRef acc, const Unit& u, int wr, int wc, int fr, int fq) const {
;     ...
;                 for (int m = 0; m < 4; ++m) { f32x4 v0 = acc[ai][bj][m][0] + b0, v1 = acc[ai][bj][m][1] + b1;
;                     if (kind == 0) { v0 = (f32x4){decay_e(v0[0]), decay_e(v0[1]), decay_e(v0[2]), decay_e(v0[3])}; v1 = (f32x4){decay_e(v1[0]), decay_e(v1[1]), decay_e(v1[2]), decay_e(v1[3])}; }
;                     else if (kind == 1) { v0 = (f32x4){sigm(v0[0]), sigm(v0[1]), sigm(v0[2]), sigm(v0[3])}; v1 = (f32x4){sigm(v1[0]), sigm(v1[1]), sigm(v1[2]), sigm(v1[3])}; }
;                     u32x4 w; w.x = cvt_pk_bf16(v0[0], v0[1]); w.y = cvt_pk_bf16(v0[2], v0[3]); w.z = cvt_pk_bf16(v1[0], v1[1]); w.w = cvt_pk_bf16(v1[2], v1[3]);
;                     *(u32x4*)(base + (size_t)EPI_ROWS(ai, m) * D + colt + bj * HALF) = w; }
.LBB0_856:
	s_andn2_b64 vcc, exec, s[46:47]
	s_cbranch_vccnz .LBB0_858
	v_mul_f32_e32 v28, 0xbfb8aa3b, v32
	v_mul_f32_e32 v29, 0xbfb8aa3b, v33
	v_exp_f32_e32 v28, v28
	v_exp_f32_e32 v29, v29
	v_mul_f32_e32 v30, 0xbfb8aa3b, v34
	v_mul_f32_e32 v31, 0xbfb8aa3b, v35
	v_exp_f32_e32 v30, v30
	v_pk_add_f32 v[28:29], v[28:29], 1.0 op_sel_hi:[1,0]
	v_exp_f32_e32 v31, v31
	s_nop 0
	v_pk_add_f32 v[30:31], v[30:31], 1.0 op_sel_hi:[1,0]
	v_mul_f32_e32 v24, 0xbfb8aa3b, v24
	v_mul_f32_e32 v25, 0xbfb8aa3b, v25
	v_rcp_f32_e32 v29, v29
	v_exp_f32_e32 v24, v24
	v_rcp_f32_e32 v28, v28
	v_exp_f32_e32 v25, v25
	v_rcp_f32_e32 v31, v31
	v_pk_add_f32 v[24:25], v[24:25], 1.0 op_sel_hi:[1,0]
	v_rcp_f32_e32 v30, v30
	v_mul_f32_e32 v26, 0xbfb8aa3b, v26
	v_mul_f32_e32 v27, 0xbfb8aa3b, v27
	v_exp_f32_e32 v26, v26
	v_exp_f32_e32 v27, v27
	v_rcp_f32_e32 v25, v25
	v_pk_add_f32 v[26:27], v[26:27], 1.0 op_sel_hi:[1,0]
	v_rcp_f32_e32 v24, v24
	v_pk_mul_f32 v[30:31], v[30:31], s[14:15] op_sel_hi:[1,0]
	v_rcp_f32_e32 v27, v27
	v_pk_mul_f32 v[28:29], v[28:29], s[14:15] op_sel_hi:[1,0]
	v_rcp_f32_e32 v26, v26
	s_nop 0
	v_pk_mul_f32 v[38:39], v[26:27], s[14:15] op_sel_hi:[1,0]
	v_pk_mul_f32 v[36:37], v[24:25], s[14:15] op_sel_hi:[1,0]
.LBB0_858:
	v_cvt_pk_bf16_f32 v24, v28, v29
	v_cvt_pk_bf16_f32 v25, v30, v31
	v_cvt_pk_bf16_f32 v26, v36, v37
	v_cvt_pk_bf16_f32 v27, v38, v39
	global_store_dwordx4 v[104:105], v[24:27], off offset:256
	v_pk_add_f32 v[18:19], v[18:19], v[66:67]
	v_pk_add_f32 v[16:17], v[16:17], v[64:65]
	v_pk_add_f32 v[26:27], v[22:23], v[70:71]
	v_pk_add_f32 v[24:25], v[20:21], v[68:69]
	s_and_b64 vcc, exec, s[4:5]
	s_mov_b64 s[46:47], -1
	s_cbranch_vccnz .LBB0_862
	v_mov_b64_e32 v[30:31], v[18:19]
	v_mov_b64_e32 v[20:21], v[24:25]
	s_and_b64 vcc, exec, s[2:3]
	v_mov_b64_e32 v[28:29], v[16:17]
	v_mov_b64_e32 v[22:23], v[26:27]
	s_cbranch_vccnz .LBB0_861
	v_mul_f32_e32 v20, 0xbfb8aa3b, v26
	v_mul_f32_e32 v21, 0xbfb8aa3b, v27
	v_exp_f32_e32 v20, v20
	v_exp_f32_e32 v21, v21
	v_mul_f32_e32 v22, 0xbfb8aa3b, v24
	v_mul_f32_e32 v23, 0xbfb8aa3b, v25
	v_exp_f32_e32 v22, v22
	v_pk_add_f32 v[20:21], v[20:21], 1.0 op_sel_hi:[1,0]
	v_exp_f32_e32 v23, v23
	s_nop 0
	v_pk_add_f32 v[28:29], v[22:23], 1.0 op_sel_hi:[1,0]
	v_mul_f32_e32 v33, 0xbfb8aa3b, v17
	v_exp_f32_e32 v33, v33
	v_rcp_f32_e32 v23, v21
	v_rcp_f32_e32 v22, v20
	v_rcp_f32_e32 v21, v29
	v_mul_f32_e32 v32, 0xbfb8aa3b, v16
	v_mul_f32_e32 v30, 0xbfb8aa3b, v18
	v_mul_f32_e32 v31, 0xbfb8aa3b, v19
	v_exp_f32_e32 v30, v30
	v_exp_f32_e32 v31, v31
	v_exp_f32_e32 v32, v32
	v_rcp_f32_e32 v20, v28
	v_pk_add_f32 v[30:31], v[30:31], 1.0 op_sel_hi:[1,0]
	v_pk_add_f32 v[28:29], v[32:33], 1.0 op_sel_hi:[1,0]
	s_nop 0
	v_rcp_f32_e32 v31, v31
	v_rcp_f32_e32 v30, v30
	v_rcp_f32_e32 v29, v29
	v_rcp_f32_e32 v28, v28

; __device__ __forceinline__ unsigned cvt_pk_bf16(float lo, float hi) { const f32x2 v = {lo, hi}; return __builtin_bit_cast(unsigned, __builtin_convertvector(v, bf16x2_t)); }
; __device__ __forceinline__ float sigm(float x) { return 1.0f / (1.0f + __expf(-x)); }
; __device__ __forceinline__ float decay_e(float pre) { return 0.6065306597126334f * sigm(pre); }
;     __device__ __forceinline__ void operator()(AccRef acc, const Unit& u, int wr, int wc, int fr, int fq) const {
;     ...
;                 for (int m = 0; m < 4; ++m) { f32x4 v0 = acc[ai][bj][m][0] + b0, v1 = acc[ai][bj][m][1] + b1;
;                     if (kind == 0) { v0 = (f32x4){decay_e(v0[0]), decay_e(v0[1]), decay_e(v0[2]), decay_e(v0[3])}; v1 = (f32x4){decay_e(v1[0]), decay_e(v1[1]), decay_e(v1[2]), decay_e(v1[3])}; }
;                     else if (kind == 1) { v0 = (f32x4){sigm(v0[0]), sigm(v0[1]), sigm(v0[2]), sigm(v0[3])}; v1 = (f32x4){sigm(v1[0]), sigm(v1[1]), sigm(v1[2]), sigm(v1[3])}; }
;                     u32x4 w; w.x = cvt_pk_bf16(v0[0], v0[1]); w.y = cvt_pk_bf16(v0[2], v0[3]); w.z = cvt_pk_bf16(v1[0], v1[1]); w.w = cvt_pk_bf16(v1[2], v1[3]);
;                     *(u32x4*)(base + (size_t)EPI_ROWS(ai, m) * D + colt + bj * HALF) = w; }
.LBB0_862:
	s_andn2_b64 vcc, exec, s[46:47]
	s_cbranch_vccnz .LBB0_864
	v_mul_f32_e32 v20, 0xbfb8aa3b, v24
	v_mul_f32_e32 v21, 0xbfb8aa3b, v25
	v_exp_f32_e32 v20, v20
	v_exp_f32_e32 v21, v21
	v_mul_f32_e32 v22, 0xbfb8aa3b, v26
	v_mul_f32_e32 v23, 0xbfb8aa3b, v27
	v_exp_f32_e32 v22, v22
	v_pk_add_f32 v[20:21], v[20:21], 1.0 op_sel_hi:[1,0]
	v_exp_f32_e32 v23, v23
	s_nop 0
	v_pk_add_f32 v[22:23], v[22:23], 1.0 op_sel_hi:[1,0]
	v_mul_f32_e32 v16, 0xbfb8aa3b, v16
	v_mul_f32_e32 v17, 0xbfb8aa3b, v17
	v_rcp_f32_e32 v21, v21
	v_exp_f32_e32 v16, v16
	v_rcp_f32_e32 v20, v20
	v_exp_f32_e32 v17, v17
	v_rcp_f32_e32 v23, v23
	v_pk_add_f32 v[16:17], v[16:17], 1.0 op_sel_hi:[1,0]
	v_rcp_f32_e32 v22, v22
	v_mul_f32_e32 v18, 0xbfb8aa3b, v18
	v_mul_f32_e32 v19, 0xbfb8aa3b, v19
	v_exp_f32_e32 v18, v18
	v_exp_f32_e32 v19, v19
	v_rcp_f32_e32 v17, v17
	v_pk_add_f32 v[18:19], v[18:19], 1.0 op_sel_hi:[1,0]
	v_rcp_f32_e32 v16, v16
	v_pk_mul_f32 v[22:23], v[22:23], s[14:15] op_sel_hi:[1,0]
	v_rcp_f32_e32 v19, v19
	v_pk_mul_f32 v[20:21], v[20:21], s[14:15] op_sel_hi:[1,0]
	v_rcp_f32_e32 v18, v18
	s_nop 0
	v_pk_mul_f32 v[30:31], v[18:19], s[14:15] op_sel_hi:[1,0]
	v_pk_mul_f32 v[28:29], v[16:17], s[14:15] op_sel_hi:[1,0]
.LBB0_864:
	v_cvt_pk_bf16_f32 v16, v20, v21
	v_cvt_pk_bf16_f32 v17, v22, v23
	v_cvt_pk_bf16_f32 v18, v28, v29
	v_cvt_pk_bf16_f32 v19, v30, v31
	global_store_dwordx4 v[96:97], v[16:19], off offset:256
	v_pk_add_f32 v[10:11], v[10:11], v[66:67]
	v_pk_add_f32 v[8:9], v[8:9], v[64:65]
	v_pk_add_f32 v[18:19], v[14:15], v[70:71]
	v_pk_add_f32 v[16:17], v[12:13], v[68:69]
	s_and_b64 vcc, exec, s[4:5]
	s_mov_b64 s[46:47], -1
	s_cbranch_vccnz .LBB0_868
	v_mov_b64_e32 v[22:23], v[10:11]
	v_mov_b64_e32 v[12:13], v[16:17]
	s_and_b64 vcc, exec, s[2:3]
	v_mov_b64_e32 v[20:21], v[8:9]
	v_mov_b64_e32 v[14:15], v[18:19]
	s_cbranch_vccnz .LBB0_867
	v_mul_f32_e32 v12, 0xbfb8aa3b, v18
	v_mul_f32_e32 v13, 0xbfb8aa3b, v19
	v_exp_f32_e32 v12, v12
	v_exp_f32_e32 v13, v13
	v_mul_f32_e32 v14, 0xbfb8aa3b, v16
	v_mul_f32_e32 v15, 0xbfb8aa3b, v17
	v_exp_f32_e32 v14, v14
	v_pk_add_f32 v[12:13], v[12:13], 1.0 op_sel_hi:[1,0]
	v_exp_f32_e32 v15, v15
	s_nop 0
	v_pk_add_f32 v[20:21], v[14:15], 1.0 op_sel_hi:[1,0]
	v_mul_f32_e32 v25, 0xbfb8aa3b, v9
	v_exp_f32_e32 v25, v25
	v_rcp_f32_e32 v15, v13
	v_rcp_f32_e32 v14, v12
	v_rcp_f32_e32 v13, v21
	v_mul_f32_e32 v24, 0xbfb8aa3b, v8
	v_mul_f32_e32 v22, 0xbfb8aa3b, v10
	v_mul_f32_e32 v23, 0xbfb8aa3b, v11
	v_exp_f32_e32 v22, v22
	v_exp_f32_e32 v23, v23
	v_exp_f32_e32 v24, v24
	v_rcp_f32_e32 v12, v20
	v_pk_add_f32 v[22:23], v[22:23], 1.0 op_sel_hi:[1,0]
	v_pk_add_f32 v[20:21], v[24:25], 1.0 op_sel_hi:[1,0]
	s_nop 0
	v_rcp_f32_e32 v23, v23
	v_rcp_f32_e32 v22, v22
	v_rcp_f32_e32 v21, v21
	v_rcp_f32_e32 v20, v20

; __device__ __forceinline__ unsigned cvt_pk_bf16(float lo, float hi) { const f32x2 v = {lo, hi}; return __builtin_bit_cast(unsigned, __builtin_convertvector(v, bf16x2_t)); }
; __device__ __forceinline__ float sigm(float x) { return 1.0f / (1.0f + __expf(-x)); }
; __device__ __forceinline__ float decay_e(float pre) { return 0.6065306597126334f * sigm(pre); }
;     __device__ __forceinline__ void operator()(AccRef acc, const Unit& u, int wr, int wc, int fr, int fq) const {
;         const int kind = u.pn >> 2, colt = (u.pn & 3) * 256 + wc * 32 + 8 * fq;
;         bf16_t* base = WD + (size_t)kind * ((WS_AA - WS_WD) / 2);
;         const float* bias = kind == 0 ? w0 : a0;
; #pragma unroll
;         for (int bj = 0; bj < 2; ++bj) {
;             f32x4 b0 = (f32x4){0.f, 0.f, 0.f, 0.f}, b1 = b0;
;             if (kind < 2) { b0 = *(const f32x4*)(bias + colt + bj * HALF); b1 = *(const f32x4*)(bias + colt + bj * HALF + 4); }
; #pragma unroll
;             for (int ai = 0; ai < 2; ++ai)
; #pragma unroll
;                 for (int m = 0; m < 4; ++m) { f32x4 v0 = acc[ai][bj][m][0] + b0, v1 = acc[ai][bj][m][1] + b1;
;                     if (kind == 0) { v0 = (f32x4){decay_e(v0[0]), decay_e(v0[1]), decay_e(v0[2]), decay_e(v0[3])}; v1 = (f32x4){decay_e(v1[0]), decay_e(v1[1]), decay_e(v1[2]), decay_e(v1[3])}; }
;                     else if (kind == 1) { v0 = (f32x4){sigm(v0[0]), sigm(v0[1]), sigm(v0[2]), sigm(v0[3])}; v1 = (f32x4){sigm(v1[0]), sigm(v1[1]), sigm(v1[2]), sigm(v1[3])}; }
;                     u32x4 w; w.x = cvt_pk_bf16(v0[0], v0[1]); w.y = cvt_pk_bf16(v0[2], v0[3]); w.z = cvt_pk_bf16(v1[0], v1[1]); w.w = cvt_pk_bf16(v1[2], v1[3]);
;                     *(u32x4*)(base + (size_t)EPI_ROWS(ai, m) * D + colt + bj * HALF) = w; }
;         }
;     }
.LBB0_868:
	s_andn2_b64 vcc, exec, s[46:47]
	s_cbranch_vccnz .LBB0_870
	v_mul_f32_e32 v12, 0xbfb8aa3b, v16
	v_mul_f32_e32 v13, 0xbfb8aa3b, v17
	v_exp_f32_e32 v12, v12
	v_exp_f32_e32 v13, v13
	v_mul_f32_e32 v14, 0xbfb8aa3b, v18
	v_mul_f32_e32 v15, 0xbfb8aa3b, v19
	v_exp_f32_e32 v14, v14
	v_pk_add_f32 v[12:13], v[12:13], 1.0 op_sel_hi:[1,0]
	v_exp_f32_e32 v15, v15
	s_nop 0
	v_pk_add_f32 v[14:15], v[14:15], 1.0 op_sel_hi:[1,0]
	v_mul_f32_e32 v8, 0xbfb8aa3b, v8
	v_mul_f32_e32 v9, 0xbfb8aa3b, v9
	v_rcp_f32_e32 v13, v13
	v_exp_f32_e32 v8, v8
	v_rcp_f32_e32 v12, v12
	v_exp_f32_e32 v9, v9
	v_rcp_f32_e32 v15, v15
	v_pk_add_f32 v[8:9], v[8:9], 1.0 op_sel_hi:[1,0]
	v_rcp_f32_e32 v14, v14
	v_mul_f32_e32 v10, 0xbfb8aa3b, v10
	v_mul_f32_e32 v11, 0xbfb8aa3b, v11
	v_exp_f32_e32 v10, v10
	v_exp_f32_e32 v11, v11
	v_rcp_f32_e32 v9, v9
	v_pk_add_f32 v[10:11], v[10:11], 1.0 op_sel_hi:[1,0]
	v_rcp_f32_e32 v8, v8
	v_pk_mul_f32 v[14:15], v[14:15], s[14:15] op_sel_hi:[1,0]
	v_rcp_f32_e32 v11, v11
	v_pk_mul_f32 v[12:13], v[12:13], s[14:15] op_sel_hi:[1,0]
	v_rcp_f32_e32 v10, v10
	s_nop 0
	v_pk_mul_f32 v[22:23], v[10:11], s[14:15] op_sel_hi:[1,0]
	v_pk_mul_f32 v[20:21], v[8:9], s[14:15] op_sel_hi:[1,0]
.LBB0_870:
	v_cvt_pk_bf16_f32 v8, v12, v13
	v_cvt_pk_bf16_f32 v9, v14, v15
	v_cvt_pk_bf16_f32 v10, v20, v21
	v_cvt_pk_bf16_f32 v11, v22, v23
	global_store_dwordx4 v[88:89], v[8:11], off offset:256
	v_pk_add_f32 v[2:3], v[2:3], v[66:67]
	v_pk_add_f32 v[0:1], v[0:1], v[64:65]
	v_pk_add_f32 v[10:11], v[6:7], v[70:71]
	v_pk_add_f32 v[8:9], v[4:5], v[68:69]
	s_and_b64 vcc, exec, s[4:5]
	s_mov_b64 s[4:5], -1
	s_cbranch_vccnz .LBB0_874
	v_mov_b64_e32 v[14:15], v[2:3]
	v_mov_b64_e32 v[4:5], v[8:9]
	s_and_b64 vcc, exec, s[2:3]
	v_mov_b64_e32 v[12:13], v[0:1]
	v_mov_b64_e32 v[6:7], v[10:11]
	s_cbranch_vccnz .LBB0_873
	v_mul_f32_e32 v4, 0xbfb8aa3b, v10
	v_mul_f32_e32 v5, 0xbfb8aa3b, v11
	v_exp_f32_e32 v4, v4
	v_exp_f32_e32 v5, v5
	v_mul_f32_e32 v6, 0xbfb8aa3b, v8
	v_mul_f32_e32 v7, 0xbfb8aa3b, v9
	v_exp_f32_e32 v6, v6
	v_pk_add_f32 v[4:5], v[4:5], 1.0 op_sel_hi:[1,0]
	v_exp_f32_e32 v7, v7
	s_nop 0
	v_pk_add_f32 v[12:13], v[6:7], 1.0 op_sel_hi:[1,0]
	v_mul_f32_e32 v17, 0xbfb8aa3b, v1
	v_exp_f32_e32 v17, v17
	v_rcp_f32_e32 v7, v5
	v_rcp_f32_e32 v6, v4
	v_rcp_f32_e32 v5, v13
	v_mul_f32_e32 v16, 0xbfb8aa3b, v0
	v_mul_f32_e32 v14, 0xbfb8aa3b, v2
	v_mul_f32_e32 v15, 0xbfb8aa3b, v3
	v_exp_f32_e32 v14, v14
	v_exp_f32_e32 v15, v15
	v_exp_f32_e32 v16, v16
	v_rcp_f32_e32 v4, v12
	v_pk_add_f32 v[14:15], v[14:15], 1.0 op_sel_hi:[1,0]
	v_pk_add_f32 v[12:13], v[16:17], 1.0 op_sel_hi:[1,0]
	s_nop 0
	v_rcp_f32_e32 v15, v15
	v_rcp_f32_e32 v14, v14
	v_rcp_f32_e32 v13, v13
	v_rcp_f32_e32 v12, v12

; __device__ __forceinline__ unsigned cvt_pk_bf16(float lo, float hi) { const f32x2 v = {lo, hi}; return __builtin_bit_cast(unsigned, __builtin_convertvector(v, bf16x2_t)); }
; __device__ __forceinline__ float sigm(float x) { return 1.0f / (1.0f + __expf(-x)); }
; __device__ __forceinline__ float decay_e(float pre) { return 0.6065306597126334f * sigm(pre); }
;     __device__ __forceinline__ void operator()(AccRef acc, const Unit& u, int wr, int wc, int fr, int fq) const {
;     ...
;                 for (int m = 0; m < 4; ++m) { f32x4 v0 = acc[ai][bj][m][0] + b0, v1 = acc[ai][bj][m][1] + b1;
;                     if (kind == 0) { v0 = (f32x4){decay_e(v0[0]), decay_e(v0[1]), decay_e(v0[2]), decay_e(v0[3])}; v1 = (f32x4){decay_e(v1[0]), decay_e(v1[1]), decay_e(v1[2]), decay_e(v1[3])}; }
;                     else if (kind == 1) { v0 = (f32x4){sigm(v0[0]), sigm(v0[1]), sigm(v0[2]), sigm(v0[3])}; v1 = (f32x4){sigm(v1[0]), sigm(v1[1]), sigm(v1[2]), sigm(v1[3])}; }
;                     u32x4 w; w.x = cvt_pk_bf16(v0[0], v0[1]); w.y = cvt_pk_bf16(v0[2], v0[3]); w.z = cvt_pk_bf16(v1[0], v1[1]); w.w = cvt_pk_bf16(v1[2], v1[3]);
;                     *(u32x4*)(base + (size_t)EPI_ROWS(ai, m) * D + colt + bj * HALF) = w; }
.LBB0_874:
	s_andn2_b64 vcc, exec, s[4:5]
	s_cbranch_vccnz .LBB0_876
	v_mul_f32_e32 v4, 0xbfb8aa3b, v8
	v_mul_f32_e32 v5, 0xbfb8aa3b, v9
	v_exp_f32_e32 v4, v4
	v_exp_f32_e32 v5, v5
	v_mul_f32_e32 v6, 0xbfb8aa3b, v10
	v_mul_f32_e32 v7, 0xbfb8aa3b, v11
	v_exp_f32_e32 v6, v6
	v_pk_add_f32 v[4:5], v[4:5], 1.0 op_sel_hi:[1,0]
	v_exp_f32_e32 v7, v7
	s_nop 0
	v_pk_add_f32 v[6:7], v[6:7], 1.0 op_sel_hi:[1,0]
	v_mul_f32_e32 v0, 0xbfb8aa3b, v0
	v_mul_f32_e32 v1, 0xbfb8aa3b, v1
	v_rcp_f32_e32 v5, v5
	v_exp_f32_e32 v0, v0
	v_rcp_f32_e32 v4, v4
	v_exp_f32_e32 v1, v1
	v_rcp_f32_e32 v7, v7
	v_pk_add_f32 v[0:1], v[0:1], 1.0 op_sel_hi:[1,0]
	v_rcp_f32_e32 v6, v6
	v_mul_f32_e32 v2, 0xbfb8aa3b, v2
	v_mul_f32_e32 v3, 0xbfb8aa3b, v3
	v_exp_f32_e32 v2, v2
	v_exp_f32_e32 v3, v3
	v_rcp_f32_e32 v1, v1
	v_pk_add_f32 v[2:3], v[2:3], 1.0 op_sel_hi:[1,0]
	v_rcp_f32_e32 v0, v0
	v_pk_mul_f32 v[6:7], v[6:7], s[14:15] op_sel_hi:[1,0]
	v_rcp_f32_e32 v3, v3
	v_pk_mul_f32 v[4:5], v[4:5], s[14:15] op_sel_hi:[1,0]
	v_rcp_f32_e32 v2, v2
	s_nop 0
	v_pk_mul_f32 v[14:15], v[2:3], s[14:15] op_sel_hi:[1,0]
	v_pk_mul_f32 v[12:13], v[0:1], s[14:15] op_sel_hi:[1,0]

; __device__ __forceinline__ unsigned cvt_pk_bf16(float lo, float hi) { const f32x2 v = {lo, hi}; return __builtin_bit_cast(unsigned, __builtin_convertvector(v, bf16x2_t)); }
; __device__ __forceinline__ float sigm(float x) { return 1.0f / (1.0f + __expf(-x)); }
;     __device__ __forceinline__ void operator()(AccRef acc, const Unit& u, int wr, int wc, int fr, int fq) const {
;         const int col0 = u.pn * 128 + wc * 32 + 8 * fq;
; #pragma unroll
;         for (int bj = 0; bj < 2; ++bj) {
;             const float* bias = bj ? bi : br; bf16_t* base = bj ? GI : GR;
;             const f32x4 b0 = *(const f32x4*)(bias + col0), b1 = *(const f32x4*)(bias + col0 + 4);
; #pragma unroll
;             for (int ai = 0; ai < 2; ++ai)
; #pragma unroll
;                 for (int m = 0; m < 4; ++m) { const f32x4 v0 = acc[ai][bj][m][0] + b0, v1 = acc[ai][bj][m][1] + b1;
;                     u32x4 w; w.x = cvt_pk_bf16(sigm(v0[0]), sigm(v0[1])); w.y = cvt_pk_bf16(sigm(v0[2]), sigm(v0[3])); w.z = cvt_pk_bf16(sigm(v1[0]), sigm(v1[1])); w.w = cvt_pk_bf16(sigm(v1[2]), sigm(v1[3]));
;                     *(u32x4*)(base + (size_t)EPI_ROWS(ai, m) * D + col0) = w; }
;         }
;     }
.LBB0_903:
	v_lshl_or_b32 v146, s61, 7, v154
	v_ashrrev_i32_e32 v147, 31, v146
	v_readlane_b32 s12, v229, 32
	v_lshlrev_b64 v[144:145], 2, v[146:147]
	v_readlane_b32 s24, v229, 44
	v_readlane_b32 s25, v229, 45
	v_lshl_add_u32 v150, s0, 8, v152
	v_readlane_b32 s14, v229, 34
	v_lshl_add_u64 v[96:97], s[24:25], 0, v[144:145]
	global_load_dwordx4 v[100:103], v[96:97], off
	s_nop 0
	global_load_dwordx4 v[96:99], v[96:97], off offset:16
	v_readlane_b32 s15, v229, 35
	v_lshlrev_b64 v[146:147], 1, v[146:147]
	v_lshl_add_u64 v[148:149], s[70:71], 0, v[146:147]
	v_readlane_b32 s13, v229, 33
	v_readlane_b32 s16, v229, 36
	v_readlane_b32 s17, v229, 37
	v_readlane_b32 s18, v229, 38
	v_readlane_b32 s19, v229, 39
	v_readlane_b32 s20, v229, 40
	v_readlane_b32 s21, v229, 41
	v_readlane_b32 s22, v229, 42
	v_readlane_b32 s23, v229, 43
	v_readlane_b32 s26, v229, 46
	v_readlane_b32 s27, v229, 47
	s_waitcnt vmcnt(0)
	v_pk_add_f32 v[132:133], v[132:133], v[100:101]
	v_pk_add_f32 v[128:129], v[128:129], v[96:97]
	v_mul_f32_e32 v132, 0xbfb8aa3b, v132
	v_mul_f32_e32 v133, 0xbfb8aa3b, v133
	v_pk_add_f32 v[134:135], v[134:135], v[102:103]
	v_mul_f32_e32 v151, 0xbfb8aa3b, v128
	v_mul_f32_e32 v159, 0xbfb8aa3b, v129
	v_exp_f32_e32 v128, v132
	v_exp_f32_e32 v129, v133
	v_mul_f32_e32 v134, 0xbfb8aa3b, v134
	v_mul_f32_e32 v135, 0xbfb8aa3b, v135
	v_exp_f32_e32 v132, v134
	v_exp_f32_e32 v133, v135
	v_pk_add_f32 v[128:129], v[128:129], 1.0 op_sel_hi:[1,0]
	v_exp_f32_e32 v134, v151
	v_exp_f32_e32 v135, v159
	v_pk_add_f32 v[132:133], v[132:133], 1.0 op_sel_hi:[1,0]
	v_div_scale_f32 v160, s[0:1], v128, v128, 1.0
	v_div_scale_f32 v162, s[4:5], v133, v133, 1.0
	v_rcp_f32_e32 v171, v160
	v_div_scale_f32 v164, s[6:7], v132, v132, 1.0
	v_rcp_f32_e32 v172, v162
	v_pk_add_f32 v[134:135], v[134:135], 1.0 op_sel_hi:[1,0]
	v_rcp_f32_e32 v173, v164
	v_div_scale_f32 v166, s[8:9], v135, v135, 1.0
	s_nop 0
	v_rcp_f32_e32 v174, v166
	v_fma_f32 v177, -v160, v171, 1.0
	v_div_scale_f32 v161, s[0:1], 1.0, v128, 1.0
	v_fma_f32 v178, -v162, v172, 1.0
	v_fmac_f32_e32 v171, v177, v171
	v_div_scale_f32 v163, s[4:5], 1.0, v133, 1.0
	v_div_scale_f32 v168, s[14:15], v134, v134, 1.0
	v_fma_f32 v179, -v164, v173, 1.0
	v_fmac_f32_e32 v172, v178, v172
	v_mul_f32_e32 v177, v161, v171
	v_div_scale_f32 v165, s[6:7], 1.0, v132, 1.0
	v_rcp_f32_e32 v175, v168
	v_fmac_f32_e32 v173, v179, v173
	v_mul_f32_e32 v178, v163, v172
	v_fma_f32 v183, -v160, v177, v161
	v_fma_f32 v180, -v166, v174, 1.0
	v_mul_f32_e32 v179, v165, v173
	v_fma_f32 v184, -v162, v178, v163
	v_fmac_f32_e32 v177, v183, v171
	v_pk_add_f32 v[130:131], v[130:131], v[98:99]
	v_div_scale_f32 v167, s[8:9], 1.0, v135, 1.0
	v_fmac_f32_e32 v174, v180, v174
	v_fma_f32 v185, -v164, v179, v165
	v_fmac_f32_e32 v178, v184, v172
	v_fma_f32 v159, -v160, v177, v161
	s_mov_b64 vcc, s[0:1]
	v_mul_f32_e32 v180, v167, v174
	v_fmac_f32_e32 v179, v185, v173
	v_fma_f32 v160, -v162, v178, v163
	v_rcp_f32_e32 v129, v129
	v_div_fmas_f32 v151, v159, v171, v177
	s_mov_b64 vcc, s[4:5]
	v_mul_f32_e32 v130, 0xbfb8aa3b, v130
	v_mul_f32_e32 v131, 0xbfb8aa3b, v131
	v_fma_f32 v181, -v168, v175, 1.0
	v_fma_f32 v186, -v166, v180, v167
	v_fma_f32 v161, -v164, v179, v165
	v_div_fixup_f32 v128, v151, v128, 1.0
	v_div_fmas_f32 v151, v160, v172, v178
	s_mov_b64 vcc, s[6:7]
	v_exp_f32_e32 v130, v130
	v_exp_f32_e32 v131, v131
	v_div_scale_f32 v169, s[14:15], 1.0, v134, 1.0
	v_fmac_f32_e32 v175, v181, v175
	v_fmac_f32_e32 v180, v186, v174
	v_cvt_pk_bf16_f32 v128, v128, v129
	v_div_fixup_f32 v129, v151, v133, 1.0
	v_div_fmas_f32 v133, v161, v173, v179
	v_mul_f32_e32 v181, v169, v175
	v_fma_f32 v162, -v166, v180, v167
	v_div_fixup_f32 v132, v133, v132, 1.0
	s_mov_b64 vcc, s[8:9]
	v_div_fmas_f32 v133, v162, v174, v180
	v_cvt_pk_bf16_f32 v129, v132, v129
	v_fma_f32 v132, -v168, v181, v169
	v_div_fixup_f32 v135, v133, v135, 1.0
	v_fmac_f32_e32 v181, v132, v175
	v_pk_add_f32 v[132:133], v[130:131], 1.0 op_sel_hi:[1,0]
	v_fma_f32 v151, -v168, v181, v169
	s_mov_b64 vcc, s[14:15]
	v_div_fmas_f32 v130, v151, v175, v181
	v_div_fixup_f32 v130, v130, v134, 1.0
	v_cvt_pk_bf16_f32 v130, v130, v135
	v_rcp_f32_e32 v131, v133
	v_pk_add_f32 v[124:125], v[124:125], v[100:101]
	v_rcp_f32_e32 v132, v132
	v_mul_f32_e32 v124, 0xbfb8aa3b, v124
	v_cvt_pk_bf16_f32 v131, v132, v131
	v_exp_f32_e32 v132, v124
	v_mul_f32_e32 v124, 0xbfb8aa3b, v125
	v_exp_f32_e32 v133, v124
	v_ashrrev_i32_e32 v151, 31, v150
	v_lshlrev_b64 v[124:125], 11, v[150:151]
	v_lshl_add_u64 v[134:135], v[148:149], 0, v[124:125]
	global_store_dwordx4 v[134:135], v[128:131], off
	v_pk_add_f32 v[126:127], v[126:127], v[102:103]
	v_pk_add_f32 v[122:123], v[122:123], v[98:99]
	v_pk_add_f32 v[128:129], v[132:133], 1.0 op_sel_hi:[1,0]
	v_pk_add_f32 v[130:131], v[120:121], v[96:97]
	v_mul_f32_e32 v122, 0xbfb8aa3b, v122
	v_mul_f32_e32 v123, 0xbfb8aa3b, v123
	v_exp_f32_e32 v122, v122
	v_rcp_f32_e32 v129, v129
	v_mul_f32_e32 v121, 0xbfb8aa3b, v127
	v_mul_f32_e32 v120, 0xbfb8aa3b, v126
	v_exp_f32_e32 v120, v120
	v_exp_f32_e32 v121, v121
	s_nop 0
	v_pk_add_f32 v[126:127], v[120:121], 1.0 op_sel_hi:[1,0]
	v_rcp_f32_e32 v120, v128
	s_nop 0
	v_cvt_pk_bf16_f32 v120, v120, v129
	v_mul_f32_e32 v128, 0xbfb8aa3b, v130
	v_mul_f32_e32 v129, 0xbfb8aa3b, v131
	v_exp_f32_e32 v128, v128
	v_exp_f32_e32 v129, v129
	v_rcp_f32_e32 v121, v127
	v_pk_add_f32 v[128:129], v[128:129], 1.0 op_sel_hi:[1,0]
	v_rcp_f32_e32 v126, v126
	s_nop 0
	v_cvt_pk_bf16_f32 v121, v126, v121
	v_rcp_f32_e32 v129, v129
	v_exp_f32_e32 v123, v123
	s_nop 0
	v_pk_add_f32 v[126:127], v[122:123], 1.0 op_sel_hi:[1,0]
	v_rcp_f32_e32 v122, v128
	s_nop 0
	v_cvt_pk_bf16_f32 v122, v122, v129
; __device__ __forceinline__ unsigned cvt_pk_bf16(float lo, float hi) { const f32x2 v = {lo, hi}; return __builtin_bit_cast(unsigned, __builtin_convertvector(v, bf16x2_t)); }
; __device__ __forceinline__ float sigm(float x) { return 1.0f / (1.0f + __expf(-x)); }
;     __device__ __forceinline__ void operator()(AccRef acc, const Unit& u, int wr, int wc, int fr, int fq) const {
;     ...
;             for (int ai = 0; ai < 2; ++ai)
; #pragma unroll
;                 for (int m = 0; m < 4; ++m) { const f32x4 v0 = acc[ai][bj][m][0] + b0, v1 = acc[ai][bj][m][1] + b1;
;                     u32x4 w; w.x = cvt_pk_bf16(sigm(v0[0]), sigm(v0[1])); w.y = cvt_pk_bf16(sigm(v0[2]), sigm(v0[3])); w.z = cvt_pk_bf16(sigm(v1[0]), sigm(v1[1])); w.w = cvt_pk_bf16(sigm(v1[2]), sigm(v1[3]));
;                     *(u32x4*)(base + (size_t)EPI_ROWS(ai, m) * D + col0) = w; }
	v_pk_add_f32 v[116:117], v[116:117], v[100:101]
	v_rcp_f32_e32 v123, v127
	v_mul_f32_e32 v116, 0xbfb8aa3b, v116
	v_rcp_f32_e32 v126, v126
	v_exp_f32_e32 v128, v116
	v_mul_f32_e32 v116, 0xbfb8aa3b, v117
	v_cvt_pk_bf16_f32 v123, v126, v123
	v_or_b32_e32 v126, 16, v150
	v_exp_f32_e32 v129, v116
	v_ashrrev_i32_e32 v127, 31, v126
	v_lshlrev_b64 v[116:117], 11, v[126:127]
	v_lshl_add_u64 v[126:127], v[148:149], 0, v[116:117]
	global_store_dwordx4 v[126:127], v[120:123], off
	v_pk_add_f32 v[118:119], v[118:119], v[102:103]
	v_pk_add_f32 v[114:115], v[114:115], v[98:99]
	v_pk_add_f32 v[120:121], v[128:129], 1.0 op_sel_hi:[1,0]
	v_pk_add_f32 v[122:123], v[112:113], v[96:97]
	v_mul_f32_e32 v114, 0xbfb8aa3b, v114
	v_mul_f32_e32 v115, 0xbfb8aa3b, v115
	v_exp_f32_e32 v114, v114
	v_rcp_f32_e32 v121, v121
	v_mul_f32_e32 v113, 0xbfb8aa3b, v119
	v_mul_f32_e32 v112, 0xbfb8aa3b, v118
	v_exp_f32_e32 v112, v112
	v_exp_f32_e32 v113, v113
	s_nop 0
	v_pk_add_f32 v[118:119], v[112:113], 1.0 op_sel_hi:[1,0]
	v_rcp_f32_e32 v112, v120
	s_nop 0
	v_cvt_pk_bf16_f32 v112, v112, v121
	v_mul_f32_e32 v120, 0xbfb8aa3b, v122
	v_mul_f32_e32 v121, 0xbfb8aa3b, v123
	v_exp_f32_e32 v120, v120
	v_exp_f32_e32 v121, v121
	v_rcp_f32_e32 v113, v119
	v_pk_add_f32 v[120:121], v[120:121], 1.0 op_sel_hi:[1,0]
	v_rcp_f32_e32 v118, v118
	s_nop 0
	v_cvt_pk_bf16_f32 v113, v118, v113
	v_rcp_f32_e32 v121, v121
	v_exp_f32_e32 v115, v115
	s_nop 0
	v_pk_add_f32 v[118:119], v[114:115], 1.0 op_sel_hi:[1,0]
	v_rcp_f32_e32 v114, v120
	s_nop 0
	v_cvt_pk_bf16_f32 v114, v114, v121
	v_pk_add_f32 v[108:109], v[108:109], v[100:101]
	v_rcp_f32_e32 v115, v119
	v_mul_f32_e32 v108, 0xbfb8aa3b, v108
	v_rcp_f32_e32 v118, v118
	v_exp_f32_e32 v120, v108
	v_mul_f32_e32 v108, 0xbfb8aa3b, v109
	v_cvt_pk_bf16_f32 v115, v118, v115
	v_or_b32_e32 v118, 32, v150
	v_exp_f32_e32 v121, v108
	v_ashrrev_i32_e32 v119, 31, v118
	v_lshlrev_b64 v[108:109], 11, v[118:119]
	v_lshl_add_u64 v[118:119], v[148:149], 0, v[108:109]
	global_store_dwordx4 v[118:119], v[112:115], off
	v_pk_add_f32 v[110:111], v[110:111], v[102:103]
	v_pk_add_f32 v[104:105], v[104:105], v[96:97]
	v_pk_add_f32 v[112:113], v[120:121], 1.0 op_sel_hi:[1,0]
	v_mul_f32_e32 v110, 0xbfb8aa3b, v110
	v_mul_f32_e32 v111, 0xbfb8aa3b, v111
	v_exp_f32_e32 v110, v110
	v_exp_f32_e32 v111, v111
	v_rcp_f32_e32 v113, v113
	v_mul_f32_e32 v104, 0xbfb8aa3b, v104
	v_pk_add_f32 v[114:115], v[110:111], 1.0 op_sel_hi:[1,0]
	v_rcp_f32_e32 v110, v112
	s_nop 0
	v_cvt_pk_bf16_f32 v110, v110, v113
	v_mul_f32_e32 v105, 0xbfb8aa3b, v105
	v_exp_f32_e32 v104, v104
	v_exp_f32_e32 v105, v105
	v_rcp_f32_e32 v111, v115
	v_pk_add_f32 v[104:105], v[104:105], 1.0 op_sel_hi:[1,0]
	v_rcp_f32_e32 v112, v114
	s_nop 0
	v_cvt_pk_bf16_f32 v111, v112, v111
	v_pk_add_f32 v[106:107], v[106:107], v[98:99]
	v_mul_f32_e32 v106, 0xbfb8aa3b, v106
	v_mul_f32_e32 v107, 0xbfb8aa3b, v107
	v_rcp_f32_e32 v105, v105
	v_exp_f32_e32 v106, v106
	v_exp_f32_e32 v107, v107
	s_nop 0
	v_pk_add_f32 v[106:107], v[106:107], 1.0 op_sel_hi:[1,0]
	v_rcp_f32_e32 v104, v104
	s_nop 0
	v_cvt_pk_bf16_f32 v112, v104, v105
	v_rcp_f32_e32 v104, v107
	v_pk_add_f32 v[92:93], v[92:93], v[100:101]
	v_mul_f32_e32 v92, 0xbfb8aa3b, v92
	v_mul_f32_e32 v93, 0xbfb8aa3b, v93
	v_rcp_f32_e32 v105, v106
	v_exp_f32_e32 v92, v92
	v_exp_f32_e32 v93, v93
	v_cvt_pk_bf16_f32 v113, v105, v104
	v_or_b32_e32 v104, 48, v150
	v_ashrrev_i32_e32 v105, 31, v104
	v_lshlrev_b64 v[104:105], 11, v[104:105]
	v_lshl_add_u64 v[106:107], v[148:149], 0, v[104:105]
	v_pk_add_f32 v[92:93], v[92:93], 1.0 op_sel_hi:[1,0]
	global_store_dwordx4 v[106:107], v[110:113], off
	s_nop 0
	s_nop 0
	v_pk_add_f32 v[110:111], v[88:89], v[96:97]
	v_pk_add_f32 v[94:95], v[94:95], v[102:103]
	v_pk_add_f32 v[90:91], v[90:91], v[98:99]
	v_rcp_f32_e32 v93, v93
	v_mul_f32_e32 v89, 0xbfb8aa3b, v95
	v_mul_f32_e32 v88, 0xbfb8aa3b, v94
	v_exp_f32_e32 v88, v88
	v_exp_f32_e32 v89, v89
	s_nop 0
	v_pk_add_f32 v[94:95], v[88:89], 1.0 op_sel_hi:[1,0]
	v_rcp_f32_e32 v88, v92
	s_nop 0
	v_cvt_pk_bf16_f32 v88, v88, v93
	v_mul_f32_e32 v93, 0xbfb8aa3b, v111
	v_mul_f32_e32 v92, 0xbfb8aa3b, v110
	v_exp_f32_e32 v92, v92
	v_exp_f32_e32 v93, v93
	v_rcp_f32_e32 v89, v95
	v_pk_add_f32 v[92:93], v[92:93], 1.0 op_sel_hi:[1,0]
	v_rcp_f32_e32 v94, v94
	s_nop 0
	v_cvt_pk_bf16_f32 v89, v94, v89
	v_rcp_f32_e32 v93, v93
	v_mul_f32_e32 v90, 0xbfb8aa3b, v90
	v_mul_f32_e32 v91, 0xbfb8aa3b, v91
	v_exp_f32_e32 v90, v90
	v_exp_f32_e32 v91, v91
	s_nop 0
	v_pk_add_f32 v[94:95], v[90:91], 1.0 op_sel_hi:[1,0]
	v_rcp_f32_e32 v90, v92
	s_nop 0
	v_cvt_pk_bf16_f32 v90, v90, v93
	v_pk_add_f32 v[84:85], v[84:85], v[100:101]
	v_rcp_f32_e32 v91, v95
	v_mul_f32_e32 v84, 0xbfb8aa3b, v84
	v_rcp_f32_e32 v92, v94
	s_nop 0
	v_cvt_pk_bf16_f32 v91, v92, v91
	v_exp_f32_e32 v92, v84
	v_mul_f32_e32 v84, 0xbfb8aa3b, v85
	v_add_u32_e32 v106, 0x80, v150
	v_exp_f32_e32 v93, v84
	v_ashrrev_i32_e32 v107, 31, v106
	v_lshlrev_b64 v[84:85], 11, v[106:107]
	v_lshl_add_u64 v[94:95], v[148:149], 0, v[84:85]
	global_store_dwordx4 v[94:95], v[88:91], off
	v_pk_add_f32 v[86:87], v[86:87], v[102:103]
	v_pk_add_f32 v[82:83], v[82:83], v[98:99]
	v_pk_add_f32 v[88:89], v[92:93], 1.0 op_sel_hi:[1,0]
	v_pk_add_f32 v[90:91], v[80:81], v[96:97]
	v_mul_f32_e32 v82, 0xbfb8aa3b, v82
	v_mul_f32_e32 v83, 0xbfb8aa3b, v83
	v_exp_f32_e32 v82, v82
	v_rcp_f32_e32 v89, v89
	v_mul_f32_e32 v81, 0xbfb8aa3b, v87
	v_mul_f32_e32 v80, 0xbfb8aa3b, v86
	v_exp_f32_e32 v80, v80
	v_exp_f32_e32 v81, v81
	s_nop 0
	v_pk_add_f32 v[86:87], v[80:81], 1.0 op_sel_hi:[1,0]
	v_rcp_f32_e32 v80, v88
	s_nop 0
	v_cvt_pk_bf16_f32 v80, v80, v89
	v_mul_f32_e32 v88, 0xbfb8aa3b, v90
	v_mul_f32_e32 v89, 0xbfb8aa3b, v91
; __device__ __forceinline__ unsigned cvt_pk_bf16(float lo, float hi) { const f32x2 v = {lo, hi}; return __builtin_bit_cast(unsigned, __builtin_convertvector(v, bf16x2_t)); }
; __device__ __forceinline__ float sigm(float x) { return 1.0f / (1.0f + __expf(-x)); }
;     __device__ __forceinline__ void operator()(AccRef acc, const Unit& u, int wr, int wc, int fr, int fq) const {
;     ...
;             for (int ai = 0; ai < 2; ++ai)
; #pragma unroll
;                 for (int m = 0; m < 4; ++m) { const f32x4 v0 = acc[ai][bj][m][0] + b0, v1 = acc[ai][bj][m][1] + b1;
;                     u32x4 w; w.x = cvt_pk_bf16(sigm(v0[0]), sigm(v0[1])); w.y = cvt_pk_bf16(sigm(v0[2]), sigm(v0[3])); w.z = cvt_pk_bf16(sigm(v1[0]), sigm(v1[1])); w.w = cvt_pk_bf16(sigm(v1[2]), sigm(v1[3]));
;                     *(u32x4*)(base + (size_t)EPI_ROWS(ai, m) * D + col0) = w; }
	v_exp_f32_e32 v88, v88
	v_exp_f32_e32 v89, v89
	v_rcp_f32_e32 v81, v87
	v_pk_add_f32 v[88:89], v[88:89], 1.0 op_sel_hi:[1,0]
	v_rcp_f32_e32 v86, v86
	s_nop 0
	v_cvt_pk_bf16_f32 v81, v86, v81
	v_rcp_f32_e32 v89, v89
	v_exp_f32_e32 v83, v83
	s_nop 0
	v_pk_add_f32 v[86:87], v[82:83], 1.0 op_sel_hi:[1,0]
	v_rcp_f32_e32 v82, v88
	s_nop 0
	v_cvt_pk_bf16_f32 v82, v82, v89
	v_pk_add_f32 v[76:77], v[76:77], v[100:101]
	v_rcp_f32_e32 v83, v87
	v_mul_f32_e32 v76, 0xbfb8aa3b, v76
	v_rcp_f32_e32 v86, v86
	v_exp_f32_e32 v88, v76
	v_mul_f32_e32 v76, 0xbfb8aa3b, v77
	v_cvt_pk_bf16_f32 v83, v86, v83
	v_add_u32_e32 v86, 0x90, v150
	v_exp_f32_e32 v89, v76
	v_ashrrev_i32_e32 v87, 31, v86
	v_lshlrev_b64 v[76:77], 11, v[86:87]
	v_lshl_add_u64 v[86:87], v[148:149], 0, v[76:77]
	global_store_dwordx4 v[86:87], v[80:83], off
	v_pk_add_f32 v[78:79], v[78:79], v[102:103]
	v_pk_add_f32 v[72:73], v[72:73], v[96:97]
	v_pk_add_f32 v[80:81], v[88:89], 1.0 op_sel_hi:[1,0]
	v_mul_f32_e32 v78, 0xbfb8aa3b, v78
	v_mul_f32_e32 v79, 0xbfb8aa3b, v79
	v_exp_f32_e32 v78, v78
	v_exp_f32_e32 v79, v79
	v_rcp_f32_e32 v81, v81
	v_mul_f32_e32 v72, 0xbfb8aa3b, v72
	v_pk_add_f32 v[82:83], v[78:79], 1.0 op_sel_hi:[1,0]
	v_rcp_f32_e32 v78, v80
	s_nop 0
	v_cvt_pk_bf16_f32 v78, v78, v81
	v_mul_f32_e32 v73, 0xbfb8aa3b, v73
	v_exp_f32_e32 v72, v72
	v_exp_f32_e32 v73, v73
	v_rcp_f32_e32 v79, v83
	v_pk_add_f32 v[72:73], v[72:73], 1.0 op_sel_hi:[1,0]
	v_rcp_f32_e32 v80, v82
	s_nop 0
	v_cvt_pk_bf16_f32 v79, v80, v79
	v_pk_add_f32 v[74:75], v[74:75], v[98:99]
	v_mul_f32_e32 v74, 0xbfb8aa3b, v74
	v_mul_f32_e32 v75, 0xbfb8aa3b, v75
	v_rcp_f32_e32 v73, v73
	v_exp_f32_e32 v74, v74
	v_exp_f32_e32 v75, v75
	s_nop 0
	v_pk_add_f32 v[74:75], v[74:75], 1.0 op_sel_hi:[1,0]
	v_rcp_f32_e32 v72, v72
	s_nop 0
	v_cvt_pk_bf16_f32 v80, v72, v73
	v_rcp_f32_e32 v72, v75
	v_pk_add_f32 v[68:69], v[68:69], v[100:101]
	v_mul_f32_e32 v68, 0xbfb8aa3b, v68
	v_mul_f32_e32 v69, 0xbfb8aa3b, v69
	v_rcp_f32_e32 v73, v74
	v_exp_f32_e32 v68, v68
	v_exp_f32_e32 v69, v69
	v_cvt_pk_bf16_f32 v81, v73, v72
	v_add_u32_e32 v72, 0xa0, v150
	v_ashrrev_i32_e32 v73, 31, v72
	v_lshlrev_b64 v[72:73], 11, v[72:73]
	v_lshl_add_u64 v[74:75], v[148:149], 0, v[72:73]
	v_pk_add_f32 v[68:69], v[68:69], 1.0 op_sel_hi:[1,0]
	global_store_dwordx4 v[74:75], v[78:81], off
	v_pk_add_f32 v[74:75], v[64:65], v[96:97]
	v_pk_add_f32 v[70:71], v[70:71], v[102:103]
	v_pk_add_f32 v[66:67], v[66:67], v[98:99]
	v_readlane_b32 s12, v229, 48
	v_mul_f32_e32 v66, 0xbfb8aa3b, v66
	v_rcp_f32_e32 v69, v69
	v_mul_f32_e32 v65, 0xbfb8aa3b, v71
	v_mul_f32_e32 v64, 0xbfb8aa3b, v70
	v_exp_f32_e32 v64, v64
	v_exp_f32_e32 v65, v65
	s_nop 0
	v_pk_add_f32 v[70:71], v[64:65], 1.0 op_sel_hi:[1,0]
	v_rcp_f32_e32 v64, v68
	s_nop 0
	v_cvt_pk_bf16_f32 v64, v64, v69
	v_mul_f32_e32 v69, 0xbfb8aa3b, v75
	v_mul_f32_e32 v68, 0xbfb8aa3b, v74
	v_exp_f32_e32 v68, v68
	v_exp_f32_e32 v69, v69
	v_rcp_f32_e32 v65, v71
	v_pk_add_f32 v[68:69], v[68:69], 1.0 op_sel_hi:[1,0]
	v_rcp_f32_e32 v70, v70
	s_nop 0
	v_cvt_pk_bf16_f32 v65, v70, v65
	v_rcp_f32_e32 v69, v69
	v_mul_f32_e32 v67, 0xbfb8aa3b, v67
	v_exp_f32_e32 v66, v66
	v_exp_f32_e32 v67, v67
	s_nop 0
	v_pk_add_f32 v[70:71], v[66:67], 1.0 op_sel_hi:[1,0]
	v_rcp_f32_e32 v66, v68
	s_nop 0
	v_cvt_pk_bf16_f32 v66, v66, v69
	v_readlane_b32 s13, v229, 49
	v_rcp_f32_e32 v67, v71
	v_readlane_b32 s14, v229, 50
	v_rcp_f32_e32 v68, v70
	s_nop 0
	v_cvt_pk_bf16_f32 v67, v68, v67
	v_add_u32_e32 v68, 0xb0, v150
	v_ashrrev_i32_e32 v69, 31, v68
	v_lshlrev_b64 v[74:75], 11, v[68:69]
	v_lshl_add_u64 v[68:69], v[148:149], 0, v[74:75]
	global_store_dwordx4 v[68:69], v[64:67], off
	v_readlane_b32 s15, v229, 51
	v_readlane_b32 s16, v229, 52
	v_lshl_add_u64 v[64:65], s[12:13], 0, v[144:145]
	global_load_dwordx4 v[68:71], v[64:65], off
	s_nop 0
	global_load_dwordx4 v[64:67], v[64:65], off offset:16
	v_readlane_b32 s17, v229, 53
	v_readlane_b32 s18, v229, 54
	v_readlane_b32 s19, v229, 55
	v_readlane_b32 s20, v229, 56
	v_readlane_b32 s21, v229, 57
	v_readlane_b32 s22, v229, 58
	v_readlane_b32 s23, v229, 59
	v_readlane_b32 s24, v229, 60
	v_readlane_b32 s25, v229, 61
	v_readlane_b32 s26, v229, 62
	v_readlane_b32 s27, v229, 63
	s_waitcnt vmcnt(1)
	v_pk_add_f32 v[60:61], v[60:61], v[68:69]
	s_nop 0
	v_mul_f32_e32 v60, 0xbfb8aa3b, v60
	v_exp_f32_e32 v78, v60
	v_mul_f32_e32 v60, 0xbfb8aa3b, v61
	v_exp_f32_e32 v79, v60
	s_waitcnt vmcnt(0)
; __device__ __forceinline__ unsigned cvt_pk_bf16(float lo, float hi) { const f32x2 v = {lo, hi}; return __builtin_bit_cast(unsigned, __builtin_convertvector(v, bf16x2_t)); }
; __device__ __forceinline__ float sigm(float x) { return 1.0f / (1.0f + __expf(-x)); }
;     __device__ __forceinline__ void operator()(AccRef acc, const Unit& u, int wr, int wc, int fr, int fq) const {
;     ...
;             for (int ai = 0; ai < 2; ++ai)
; #pragma unroll
;                 for (int m = 0; m < 4; ++m) { const f32x4 v0 = acc[ai][bj][m][0] + b0, v1 = acc[ai][bj][m][1] + b1;
;                     u32x4 w; w.x = cvt_pk_bf16(sigm(v0[0]), sigm(v0[1])); w.y = cvt_pk_bf16(sigm(v0[2]), sigm(v0[3])); w.z = cvt_pk_bf16(sigm(v1[0]), sigm(v1[1])); w.w = cvt_pk_bf16(sigm(v1[2]), sigm(v1[3]));
;                     *(u32x4*)(base + (size_t)EPI_ROWS(ai, m) * D + col0) = w; }
	v_pk_add_f32 v[80:81], v[56:57], v[64:65]
	v_pk_add_f32 v[62:63], v[62:63], v[70:71]
	v_pk_add_f32 v[58:59], v[58:59], v[66:67]
	v_pk_add_f32 v[78:79], v[78:79], 1.0 op_sel_hi:[1,0]
	v_mul_f32_e32 v58, 0xbfb8aa3b, v58
	v_mul_f32_e32 v59, 0xbfb8aa3b, v59
	v_exp_f32_e32 v58, v58
	v_exp_f32_e32 v59, v59
	v_rcp_f32_e32 v79, v79
	v_mul_f32_e32 v57, 0xbfb8aa3b, v63
	v_mul_f32_e32 v56, 0xbfb8aa3b, v62
	v_exp_f32_e32 v56, v56
	v_exp_f32_e32 v57, v57
	s_nop 0
	v_pk_add_f32 v[62:63], v[56:57], 1.0 op_sel_hi:[1,0]
	v_rcp_f32_e32 v56, v78
	s_nop 0
	v_cvt_pk_bf16_f32 v56, v56, v79
	v_mul_f32_e32 v78, 0xbfb8aa3b, v80
	v_mul_f32_e32 v79, 0xbfb8aa3b, v81
	v_exp_f32_e32 v78, v78
	v_exp_f32_e32 v79, v79
	v_rcp_f32_e32 v57, v63
	v_pk_add_f32 v[78:79], v[78:79], 1.0 op_sel_hi:[1,0]
	v_rcp_f32_e32 v62, v62
	s_nop 0
	v_cvt_pk_bf16_f32 v57, v62, v57
	v_rcp_f32_e32 v79, v79
	v_pk_add_f32 v[52:53], v[52:53], v[68:69]
	v_pk_add_f32 v[62:63], v[58:59], 1.0 op_sel_hi:[1,0]
	v_rcp_f32_e32 v58, v78
	s_nop 0
	v_cvt_pk_bf16_f32 v58, v58, v79
	v_mul_f32_e32 v52, 0xbfb8aa3b, v52
	v_rcp_f32_e32 v59, v63
	v_mul_f32_e32 v53, 0xbfb8aa3b, v53
	v_exp_f32_e32 v52, v52
	v_exp_f32_e32 v53, v53
	v_lshl_add_u64 v[60:61], s[72:73], 0, v[146:147]
	v_rcp_f32_e32 v62, v62
	s_nop 0
	v_cvt_pk_bf16_f32 v59, v62, v59
	v_lshl_add_u64 v[62:63], v[60:61], 0, v[124:125]
	v_pk_add_f32 v[52:53], v[52:53], 1.0 op_sel_hi:[1,0]
	global_store_dwordx4 v[62:63], v[56:59], off
	v_pk_add_f32 v[54:55], v[54:55], v[70:71]
	v_pk_add_f32 v[50:51], v[50:51], v[66:67]
	v_pk_add_f32 v[56:57], v[48:49], v[64:65]
	v_mul_f32_e32 v50, 0xbfb8aa3b, v50
	v_mul_f32_e32 v51, 0xbfb8aa3b, v51
	v_rcp_f32_e32 v53, v53
	v_mul_f32_e32 v49, 0xbfb8aa3b, v55
	v_mul_f32_e32 v48, 0xbfb8aa3b, v54
	v_exp_f32_e32 v48, v48
	v_exp_f32_e32 v49, v49
	s_nop 0
	v_pk_add_f32 v[54:55], v[48:49], 1.0 op_sel_hi:[1,0]
	v_rcp_f32_e32 v48, v52
	s_nop 0
	v_cvt_pk_bf16_f32 v48, v48, v53
	v_mul_f32_e32 v53, 0xbfb8aa3b, v57
	v_mul_f32_e32 v52, 0xbfb8aa3b, v56
	v_exp_f32_e32 v52, v52
	v_exp_f32_e32 v53, v53
	v_rcp_f32_e32 v49, v55
	v_pk_add_f32 v[52:53], v[52:53], 1.0 op_sel_hi:[1,0]
	v_rcp_f32_e32 v54, v54
	s_nop 0
	v_cvt_pk_bf16_f32 v49, v54, v49
	v_rcp_f32_e32 v53, v53
	v_exp_f32_e32 v50, v50
	v_exp_f32_e32 v51, v51
	s_nop 0
	v_pk_add_f32 v[54:55], v[50:51], 1.0 op_sel_hi:[1,0]
	v_rcp_f32_e32 v50, v52
	s_nop 0
	v_cvt_pk_bf16_f32 v50, v50, v53
	v_pk_add_f32 v[44:45], v[44:45], v[68:69]
	v_rcp_f32_e32 v51, v55
	v_mul_f32_e32 v44, 0xbfb8aa3b, v44
	v_mul_f32_e32 v45, 0xbfb8aa3b, v45
	v_exp_f32_e32 v44, v44
	v_exp_f32_e32 v45, v45
	v_rcp_f32_e32 v52, v54
	s_nop 0
	v_cvt_pk_bf16_f32 v51, v52, v51
	v_lshl_add_u64 v[52:53], v[60:61], 0, v[116:117]
	v_pk_add_f32 v[44:45], v[44:45], 1.0 op_sel_hi:[1,0]
	global_store_dwordx4 v[52:53], v[48:51], off
	v_pk_add_f32 v[46:47], v[46:47], v[70:71]
	v_pk_add_f32 v[42:43], v[42:43], v[66:67]
	v_pk_add_f32 v[48:49], v[40:41], v[64:65]
	v_mul_f32_e32 v42, 0xbfb8aa3b, v42
	v_mul_f32_e32 v43, 0xbfb8aa3b, v43
	v_rcp_f32_e32 v45, v45
	v_mul_f32_e32 v41, 0xbfb8aa3b, v47
	v_mul_f32_e32 v40, 0xbfb8aa3b, v46
	v_exp_f32_e32 v40, v40
	v_exp_f32_e32 v41, v41
	s_nop 0
	v_pk_add_f32 v[46:47], v[40:41], 1.0 op_sel_hi:[1,0]
	v_rcp_f32_e32 v40, v44
	s_nop 0
	v_cvt_pk_bf16_f32 v40, v40, v45
	v_mul_f32_e32 v45, 0xbfb8aa3b, v49
	v_mul_f32_e32 v44, 0xbfb8aa3b, v48
	v_exp_f32_e32 v44, v44
	v_exp_f32_e32 v45, v45
	v_rcp_f32_e32 v41, v47
	v_pk_add_f32 v[44:45], v[44:45], 1.0 op_sel_hi:[1,0]
	v_rcp_f32_e32 v46, v46
	s_nop 0
	v_cvt_pk_bf16_f32 v41, v46, v41
	v_rcp_f32_e32 v45, v45
	v_exp_f32_e32 v42, v42
	v_exp_f32_e32 v43, v43
	s_nop 0
	v_pk_add_f32 v[46:47], v[42:43], 1.0 op_sel_hi:[1,0]
	v_rcp_f32_e32 v42, v44
	s_nop 0
	v_cvt_pk_bf16_f32 v42, v42, v45
	v_pk_add_f32 v[36:37], v[36:37], v[68:69]
	v_rcp_f32_e32 v43, v47
	v_mul_f32_e32 v36, 0xbfb8aa3b, v36
	v_mul_f32_e32 v37, 0xbfb8aa3b, v37
	v_exp_f32_e32 v36, v36
	v_exp_f32_e32 v37, v37
	v_rcp_f32_e32 v44, v46
	s_nop 0
	v_cvt_pk_bf16_f32 v43, v44, v43
	v_lshl_add_u64 v[44:45], v[60:61], 0, v[108:109]
	v_pk_add_f32 v[36:37], v[36:37], 1.0 op_sel_hi:[1,0]
	global_store_dwordx4 v[44:45], v[40:43], off
	v_pk_add_f32 v[38:39], v[38:39], v[70:71]
	v_pk_add_f32 v[34:35], v[34:35], v[66:67]
	v_pk_add_f32 v[40:41], v[32:33], v[64:65]
	v_mul_f32_e32 v34, 0xbfb8aa3b, v34
	v_mul_f32_e32 v35, 0xbfb8aa3b, v35
	v_rcp_f32_e32 v37, v37
	v_mul_f32_e32 v33, 0xbfb8aa3b, v39
	v_mul_f32_e32 v32, 0xbfb8aa3b, v38
	v_exp_f32_e32 v32, v32
	v_exp_f32_e32 v33, v33
	s_nop 0
	v_pk_add_f32 v[38:39], v[32:33], 1.0 op_sel_hi:[1,0]
	v_rcp_f32_e32 v32, v36
	s_nop 0
	v_cvt_pk_bf16_f32 v32, v32, v37
	v_mul_f32_e32 v37, 0xbfb8aa3b, v41
	v_mul_f32_e32 v36, 0xbfb8aa3b, v40
	v_exp_f32_e32 v36, v36
	v_exp_f32_e32 v37, v37
	v_rcp_f32_e32 v33, v39
	v_pk_add_f32 v[36:37], v[36:37], 1.0 op_sel_hi:[1,0]
	v_rcp_f32_e32 v38, v38
	s_nop 0
	v_cvt_pk_bf16_f32 v33, v38, v33
	v_rcp_f32_e32 v37, v37
	v_exp_f32_e32 v34, v34
	v_exp_f32_e32 v35, v35
	s_nop 0
	v_pk_add_f32 v[38:39], v[34:35], 1.0 op_sel_hi:[1,0]
	v_rcp_f32_e32 v34, v36
	s_nop 0
	v_cvt_pk_bf16_f32 v34, v34, v37
	v_pk_add_f32 v[28:29], v[28:29], v[68:69]
	v_rcp_f32_e32 v35, v39
	v_mul_f32_e32 v28, 0xbfb8aa3b, v28
	v_mul_f32_e32 v29, 0xbfb8aa3b, v29
	v_exp_f32_e32 v28, v28
	v_exp_f32_e32 v29, v29
	v_rcp_f32_e32 v36, v38
	s_nop 0
	v_cvt_pk_bf16_f32 v35, v36, v35
; __device__ __forceinline__ unsigned cvt_pk_bf16(float lo, float hi) { const f32x2 v = {lo, hi}; return __builtin_bit_cast(unsigned, __builtin_convertvector(v, bf16x2_t)); }
; __device__ __forceinline__ float sigm(float x) { return 1.0f / (1.0f + __expf(-x)); }
;     __device__ __forceinline__ void operator()(AccRef acc, const Unit& u, int wr, int wc, int fr, int fq) const {
;     ...
;             for (int ai = 0; ai < 2; ++ai)
; #pragma unroll
;                 for (int m = 0; m < 4; ++m) { const f32x4 v0 = acc[ai][bj][m][0] + b0, v1 = acc[ai][bj][m][1] + b1;
;                     u32x4 w; w.x = cvt_pk_bf16(sigm(v0[0]), sigm(v0[1])); w.y = cvt_pk_bf16(sigm(v0[2]), sigm(v0[3])); w.z = cvt_pk_bf16(sigm(v1[0]), sigm(v1[1])); w.w = cvt_pk_bf16(sigm(v1[2]), sigm(v1[3]));
;                     *(u32x4*)(base + (size_t)EPI_ROWS(ai, m) * D + col0) = w; }
	v_lshl_add_u64 v[36:37], v[60:61], 0, v[104:105]
	v_pk_add_f32 v[28:29], v[28:29], 1.0 op_sel_hi:[1,0]
	global_store_dwordx4 v[36:37], v[32:35], off
	v_pk_add_f32 v[30:31], v[30:31], v[70:71]
	v_pk_add_f32 v[26:27], v[26:27], v[66:67]
	v_pk_add_f32 v[32:33], v[24:25], v[64:65]
	v_mul_f32_e32 v26, 0xbfb8aa3b, v26
	v_mul_f32_e32 v27, 0xbfb8aa3b, v27
	v_rcp_f32_e32 v29, v29
	v_mul_f32_e32 v25, 0xbfb8aa3b, v31
	v_mul_f32_e32 v24, 0xbfb8aa3b, v30
	v_exp_f32_e32 v24, v24
	v_exp_f32_e32 v25, v25
	s_nop 0
	v_pk_add_f32 v[30:31], v[24:25], 1.0 op_sel_hi:[1,0]
	v_rcp_f32_e32 v24, v28
	s_nop 0
	v_cvt_pk_bf16_f32 v24, v24, v29
	v_mul_f32_e32 v29, 0xbfb8aa3b, v33
	v_mul_f32_e32 v28, 0xbfb8aa3b, v32
	v_exp_f32_e32 v28, v28
	v_exp_f32_e32 v29, v29
	v_rcp_f32_e32 v25, v31
	v_pk_add_f32 v[28:29], v[28:29], 1.0 op_sel_hi:[1,0]
	v_rcp_f32_e32 v30, v30
	s_nop 0
	v_cvt_pk_bf16_f32 v25, v30, v25
	v_rcp_f32_e32 v29, v29
	v_exp_f32_e32 v26, v26
	v_exp_f32_e32 v27, v27
	s_nop 0
	v_pk_add_f32 v[30:31], v[26:27], 1.0 op_sel_hi:[1,0]
	v_rcp_f32_e32 v26, v28
	s_nop 0
	v_cvt_pk_bf16_f32 v26, v26, v29
	v_pk_add_f32 v[20:21], v[20:21], v[68:69]
	v_rcp_f32_e32 v27, v31
	v_mul_f32_e32 v20, 0xbfb8aa3b, v20
	v_mul_f32_e32 v21, 0xbfb8aa3b, v21
	v_exp_f32_e32 v20, v20
	v_exp_f32_e32 v21, v21
	v_rcp_f32_e32 v28, v30
	s_nop 0
	v_cvt_pk_bf16_f32 v27, v28, v27
	v_lshl_add_u64 v[28:29], v[60:61], 0, v[84:85]
	v_pk_add_f32 v[20:21], v[20:21], 1.0 op_sel_hi:[1,0]
	global_store_dwordx4 v[28:29], v[24:27], off
	v_pk_add_f32 v[22:23], v[22:23], v[70:71]
	v_pk_add_f32 v[18:19], v[18:19], v[66:67]
	v_pk_add_f32 v[24:25], v[16:17], v[64:65]
	v_mul_f32_e32 v18, 0xbfb8aa3b, v18
	v_mul_f32_e32 v19, 0xbfb8aa3b, v19
	v_rcp_f32_e32 v21, v21
	v_mul_f32_e32 v17, 0xbfb8aa3b, v23
	v_mul_f32_e32 v16, 0xbfb8aa3b, v22
	v_exp_f32_e32 v16, v16
	v_exp_f32_e32 v17, v17
	s_nop 0
	v_pk_add_f32 v[22:23], v[16:17], 1.0 op_sel_hi:[1,0]
	v_rcp_f32_e32 v16, v20
	s_nop 0
	v_cvt_pk_bf16_f32 v16, v16, v21
	v_mul_f32_e32 v21, 0xbfb8aa3b, v25
	v_mul_f32_e32 v20, 0xbfb8aa3b, v24
	v_exp_f32_e32 v20, v20
	v_exp_f32_e32 v21, v21
	v_rcp_f32_e32 v17, v23
	v_pk_add_f32 v[20:21], v[20:21], 1.0 op_sel_hi:[1,0]
	v_rcp_f32_e32 v22, v22
	s_nop 0
	v_cvt_pk_bf16_f32 v17, v22, v17
	v_rcp_f32_e32 v21, v21
	v_exp_f32_e32 v18, v18
	v_exp_f32_e32 v19, v19
	s_nop 0
	v_pk_add_f32 v[22:23], v[18:19], 1.0 op_sel_hi:[1,0]
	v_rcp_f32_e32 v18, v20
	s_nop 0
	v_cvt_pk_bf16_f32 v18, v18, v21
	v_pk_add_f32 v[12:13], v[12:13], v[68:69]
	v_rcp_f32_e32 v19, v23
	v_mul_f32_e32 v12, 0xbfb8aa3b, v12
	v_mul_f32_e32 v13, 0xbfb8aa3b, v13
	v_exp_f32_e32 v12, v12
	v_exp_f32_e32 v13, v13
	v_rcp_f32_e32 v20, v22
	s_nop 0
	v_cvt_pk_bf16_f32 v19, v20, v19
	v_lshl_add_u64 v[20:21], v[60:61], 0, v[76:77]
	v_pk_add_f32 v[12:13], v[12:13], 1.0 op_sel_hi:[1,0]
	global_store_dwordx4 v[20:21], v[16:19], off
	v_pk_add_f32 v[14:15], v[14:15], v[70:71]
	v_pk_add_f32 v[10:11], v[10:11], v[66:67]
	v_pk_add_f32 v[16:17], v[8:9], v[64:65]
	v_mul_f32_e32 v10, 0xbfb8aa3b, v10
	v_mul_f32_e32 v11, 0xbfb8aa3b, v11
	v_rcp_f32_e32 v13, v13
	v_mul_f32_e32 v9, 0xbfb8aa3b, v15
	v_mul_f32_e32 v8, 0xbfb8aa3b, v14
	v_exp_f32_e32 v8, v8
	v_exp_f32_e32 v9, v9
	s_nop 0
	v_pk_add_f32 v[14:15], v[8:9], 1.0 op_sel_hi:[1,0]
	v_rcp_f32_e32 v8, v12
	s_nop 0
	v_cvt_pk_bf16_f32 v8, v8, v13
	v_mul_f32_e32 v13, 0xbfb8aa3b, v17
	v_mul_f32_e32 v12, 0xbfb8aa3b, v16
	v_exp_f32_e32 v12, v12
	v_exp_f32_e32 v13, v13
	v_rcp_f32_e32 v9, v15
	v_pk_add_f32 v[12:13], v[12:13], 1.0 op_sel_hi:[1,0]
	v_rcp_f32_e32 v14, v14
	s_nop 0
	v_cvt_pk_bf16_f32 v9, v14, v9
	v_rcp_f32_e32 v13, v13
	v_exp_f32_e32 v10, v10
	v_exp_f32_e32 v11, v11
	s_nop 0
	v_pk_add_f32 v[14:15], v[10:11], 1.0 op_sel_hi:[1,0]
	v_rcp_f32_e32 v10, v12
	s_nop 0
	v_cvt_pk_bf16_f32 v10, v10, v13
	v_pk_add_f32 v[4:5], v[4:5], v[68:69]
	v_rcp_f32_e32 v11, v15
	v_mul_f32_e32 v4, 0xbfb8aa3b, v4
	v_mul_f32_e32 v5, 0xbfb8aa3b, v5
	v_exp_f32_e32 v4, v4
	v_exp_f32_e32 v5, v5
	v_rcp_f32_e32 v12, v14
	s_nop 0
	v_cvt_pk_bf16_f32 v11, v12, v11
	v_lshl_add_u64 v[12:13], v[60:61], 0, v[72:73]
	v_pk_add_f32 v[4:5], v[4:5], 1.0 op_sel_hi:[1,0]
	global_store_dwordx4 v[12:13], v[8:11], off
	v_pk_add_f32 v[6:7], v[6:7], v[70:71]
	v_pk_add_f32 v[2:3], v[2:3], v[66:67]
	v_pk_add_f32 v[8:9], v[0:1], v[64:65]
	v_mul_f32_e32 v2, 0xbfb8aa3b, v2
	v_mul_f32_e32 v3, 0xbfb8aa3b, v3
	v_rcp_f32_e32 v5, v5
	v_mul_f32_e32 v1, 0xbfb8aa3b, v7
	v_mul_f32_e32 v0, 0xbfb8aa3b, v6
	v_exp_f32_e32 v0, v0
	v_exp_f32_e32 v1, v1
	s_nop 0
	v_pk_add_f32 v[6:7], v[0:1], 1.0 op_sel_hi:[1,0]
	v_rcp_f32_e32 v0, v4
	s_nop 0
	v_cvt_pk_bf16_f32 v0, v0, v5
	v_mul_f32_e32 v5, 0xbfb8aa3b, v9
	v_mul_f32_e32 v4, 0xbfb8aa3b, v8
	v_exp_f32_e32 v4, v4
	v_exp_f32_e32 v5, v5
	v_rcp_f32_e32 v1, v7
	v_pk_add_f32 v[4:5], v[4:5], 1.0 op_sel_hi:[1,0]
	v_rcp_f32_e32 v6, v6
	s_nop 0
	v_cvt_pk_bf16_f32 v1, v6, v1
	v_rcp_f32_e32 v5, v5
	v_exp_f32_e32 v2, v2
	v_exp_f32_e32 v3, v3
	s_nop 0
	v_pk_add_f32 v[6:7], v[2:3], 1.0 op_sel_hi:[1,0]
	v_rcp_f32_e32 v2, v4
	s_nop 0
	v_cvt_pk_bf16_f32 v2, v2, v5
	v_rcp_f32_e32 v3, v7
	s_mov_b64 s[0:1], -1
	v_rcp_f32_e32 v4, v6
	s_nop 0
	v_cvt_pk_bf16_f32 v3, v4, v3
	v_lshl_add_u64 v[4:5], v[60:61], 0, v[74:75]
	s_and_b64 vcc, exec, s[2:3]
	global_store_dwordx4 v[4:5], v[0:3], off
	s_cbranch_vccnz .LBB0_890
	s_andn2_b64 vcc, exec, s[44:45]
	s_cbranch_vccnz .LBB0_889
	s_barrier
	s_branch .LBB0_889

; __device__ __forceinline__ u32x2 pack4(f32x4 v) { u32x2 r; r.x = cvt_pk_bf16(v.x, v.y); r.y = cvt_pk_bf16(v.z, v.w); return r; }
; __device__ __forceinline__ float sigm(float x) { return 1.0f / (1.0f + __expf(-x)); }
; __device__ __forceinline__ float decay_e(float pre) { return 0.6065306597126334f * sigm(pre); }
; template <bool PAIR, class F>
; __device__ __forceinline__ void skinny(const bf16_t* A, int lda, const bf16_t* Bt, int ldb, int K, int tile_lo, int tile_hi, int kmode, int bx, int G, int tid_, LAS unsigned char* lds, F f) {
;     ...
;         if (kh == 1) { X[0] = a00; X[1] = a01; if (PAIR) { X[2] = a10; X[3] = a11; } }
;         __syncthreads();
;         if (kh == 0) {
;             a00 = a00 + X[0]; a01 = a01 + X[1]; if (PAIR) { a10 = a10 + X[2]; a11 = a11 + X[3]; }
;             f(row0, tile, cgp * 16 + 4 * fq, a00, a10);
;             f(row0 + 16, tile, cgp * 16 + 4 * fq, a01, a11);
; template <int ph>
; __device__ __forceinline__ void run_phase(const Args& args, LAS unsigned char* lds, const int G, const int bx, const bool fin = true) {
;     ...
;         skinny<false>(LB, 256, LORAT, 256, 256, 0, 12, 0, bx, G, tid, lds, [&](int row, int tile, int cin, f32x4 a, f32x4) {
;             const int kind = tile >> 2, c = (tile & 3) * 256 + cin; f32x4 o = a;
;             if (kind == 0) { const f32x4 bb = *(const f32x4*)(decay_w0 + c); o = (f32x4){decay_e(a[0] + bb[0]), decay_e(a[1] + bb[1]), decay_e(a[2] + bb[2]), decay_e(a[3] + bb[3])}; }
;             else if (kind == 1) { const f32x4 bb = *(const f32x4*)(aaa_a0 + c); o = (f32x4){sigm(a[0] + bb[0]), sigm(a[1] + bb[1]), sigm(a[2] + bb[2]), sigm(a[3] + bb[3])}; }
;             bf16_t* base = WD + (size_t)kind * ((WS_AA - WS_WD) / 2); *(u32x2*)(base + (size_t)row * D + c) = pack4(o); });
.LBB0_913:
	s_and_b64 vcc, exec, s[4:5]
	s_waitcnt lgkmcnt(0)
	s_barrier
	s_cbranch_vccnz .LBB0_910
	ds_read_b128 v[12:15], v26 offset:32768
	ds_read_b128 v[4:7], v26 offset:32784
	v_or_b32_e32 v16, s0, v25
	s_ashr_i32 s55, s6, 2
	s_and_b32 s0, s1, 0x300
	s_cmp_gt_u32 s6, 3
	v_add_u32_e32 v22, s0, v16
	s_cselect_b64 s[44:45], -1, 0
	s_waitcnt lgkmcnt(1)
	v_pk_add_f32 v[10:11], v[10:11], v[14:15]
	v_pk_add_f32 v[8:9], v[8:9], v[12:13]
	s_mov_b64 s[0:1], -1
	s_and_b64 vcc, exec, s[44:45]
	v_ashrrev_i32_e32 v23, 31, v22
	s_cbranch_vccz .LBB0_918
	v_mov_b64_e32 v[14:15], v[10:11]
	s_cmp_lg_u32 s55, 1
	v_mov_b64_e32 v[12:13], v[8:9]
	s_cbranch_scc1 .LBB0_917
	v_lshl_add_u64 v[12:13], v[22:23], 2, s[42:43]
	global_load_dwordx4 v[12:15], v[12:13], off
	s_waitcnt vmcnt(0)
	v_add_f32_e32 v14, v10, v14
	v_add_f32_e32 v15, v11, v15
	v_mul_f32_e32 v14, 0xbfb8aa3b, v14
	v_mul_f32_e32 v15, 0xbfb8aa3b, v15
	v_add_f32_e32 v12, v8, v12
	v_add_f32_e32 v13, v9, v13
	v_exp_f32_e32 v14, v14
	v_exp_f32_e32 v15, v15
	v_mul_f32_e32 v12, 0xbfb8aa3b, v12
	v_mul_f32_e32 v13, 0xbfb8aa3b, v13
	v_exp_f32_e32 v12, v12
	v_exp_f32_e32 v13, v13
	v_pk_add_f32 v[14:15], v[14:15], 1.0 op_sel_hi:[1,0]
	v_pk_add_f32 v[12:13], v[12:13], 1.0 op_sel_hi:[1,0]
	v_div_scale_f32 v30, s[0:1], v14, v14, 1.0
	v_div_scale_f32 v32, s[6:7], v13, v13, 1.0
	v_rcp_f32_e32 v37, v30
	v_div_scale_f32 v34, s[8:9], v12, v12, 1.0
	v_rcp_f32_e32 v38, v32
	v_rcp_f32_e32 v39, v34
	v_fma_f32 v41, -v30, v37, 1.0
	v_div_scale_f32 v31, s[0:1], 1.0, v14, 1.0
	v_fma_f32 v42, -v32, v38, 1.0
	v_fmac_f32_e32 v37, v41, v37
	v_div_scale_f32 v33, s[6:7], 1.0, v13, 1.0
	v_fma_f32 v43, -v34, v39, 1.0
	v_fmac_f32_e32 v38, v42, v38
	v_mul_f32_e32 v41, v31, v37
	v_div_scale_f32 v35, s[8:9], 1.0, v12, 1.0
	v_fmac_f32_e32 v39, v43, v39
	v_mul_f32_e32 v42, v33, v38
	v_fma_f32 v45, -v30, v41, v31
	v_mul_f32_e32 v43, v35, v39
	v_fma_f32 v46, -v32, v42, v33
	v_fmac_f32_e32 v41, v45, v37
	v_fma_f32 v47, -v34, v43, v35
	v_fmac_f32_e32 v42, v46, v38
	v_fma_f32 v29, -v30, v41, v31
	s_mov_b64 vcc, s[0:1]
	v_fmac_f32_e32 v43, v47, v39
	v_fma_f32 v30, -v32, v42, v33
	v_rcp_f32_e32 v15, v15
	v_div_fmas_f32 v16, v29, v37, v41
	s_mov_b64 vcc, s[6:7]
	v_fma_f32 v31, -v34, v43, v35
	v_div_fixup_f32 v14, v16, v14, 1.0
	v_div_fmas_f32 v16, v30, v38, v42
	s_mov_b64 vcc, s[8:9]
	v_div_fixup_f32 v13, v16, v13, 1.0
	v_div_fmas_f32 v16, v31, v39, v43
	v_div_fixup_f32 v12, v16, v12, 1.0

; __device__ __forceinline__ u32x2 pack4(f32x4 v) { u32x2 r; r.x = cvt_pk_bf16(v.x, v.y); r.y = cvt_pk_bf16(v.z, v.w); return r; }
; __device__ __forceinline__ float sigm(float x) { return 1.0f / (1.0f + __expf(-x)); }
; __device__ __forceinline__ float decay_e(float pre) { return 0.6065306597126334f * sigm(pre); }
; template <bool PAIR, class F>
; __device__ __forceinline__ void skinny(const bf16_t* A, int lda, const bf16_t* Bt, int ldb, int K, int tile_lo, int tile_hi, int kmode, int bx, int G, int tid_, LAS unsigned char* lds, F f) {
;     ...
;         if (kh == 1) { X[0] = a00; X[1] = a01; if (PAIR) { X[2] = a10; X[3] = a11; } }
;         __syncthreads();
;         if (kh == 0) {
;             a00 = a00 + X[0]; a01 = a01 + X[1]; if (PAIR) { a10 = a10 + X[2]; a11 = a11 + X[3]; }
;             f(row0, tile, cgp * 16 + 4 * fq, a00, a10);
;             f(row0 + 16, tile, cgp * 16 + 4 * fq, a01, a11);
; template <int ph>
; __device__ __forceinline__ void run_phase(const Args& args, LAS unsigned char* lds, const int G, const int bx, const bool fin = true) {
;     ...
;         skinny<false>(LB, 256, LORAT, 256, 256, 0, 12, 0, bx, G, tid, lds, [&](int row, int tile, int cin, f32x4 a, f32x4) {
;             const int kind = tile >> 2, c = (tile & 3) * 256 + cin; f32x4 o = a;
;             if (kind == 0) { const f32x4 bb = *(const f32x4*)(decay_w0 + c); o = (f32x4){decay_e(a[0] + bb[0]), decay_e(a[1] + bb[1]), decay_e(a[2] + bb[2]), decay_e(a[3] + bb[3])}; }
;             else if (kind == 1) { const f32x4 bb = *(const f32x4*)(aaa_a0 + c); o = (f32x4){sigm(a[0] + bb[0]), sigm(a[1] + bb[1]), sigm(a[2] + bb[2]), sigm(a[3] + bb[3])}; }
;             bf16_t* base = WD + (size_t)kind * ((WS_AA - WS_WD) / 2); *(u32x2*)(base + (size_t)row * D + c) = pack4(o); });
.LBB0_918:
	s_andn2_b64 vcc, exec, s[0:1]
	s_cbranch_vccnz .LBB0_920
	v_lshl_add_u64 v[12:13], v[22:23], 2, s[38:39]
	global_load_dwordx4 v[12:15], v[12:13], off
	s_waitcnt vmcnt(0)
	v_add_f32_e32 v8, v8, v12
	v_add_f32_e32 v9, v9, v13
	v_mul_f32_e32 v8, 0xbfb8aa3b, v8
	v_mul_f32_e32 v9, 0xbfb8aa3b, v9
	v_add_f32_e32 v10, v10, v14
	v_add_f32_e32 v11, v11, v15
	v_exp_f32_e32 v8, v8
	v_exp_f32_e32 v9, v9
	v_mul_f32_e32 v10, 0xbfb8aa3b, v10
	v_mul_f32_e32 v11, 0xbfb8aa3b, v11
	v_exp_f32_e32 v10, v10
	v_exp_f32_e32 v11, v11
	v_pk_add_f32 v[8:9], v[8:9], 1.0 op_sel_hi:[1,0]
	v_pk_add_f32 v[10:11], v[10:11], 1.0 op_sel_hi:[1,0]
	v_div_scale_f32 v14, s[0:1], v8, v8, 1.0
	v_div_scale_f32 v16, s[6:7], v11, v11, 1.0
	v_rcp_f32_e32 v33, v14
	v_div_scale_f32 v30, s[8:9], v10, v10, 1.0
	v_rcp_f32_e32 v34, v16
	v_rcp_f32_e32 v35, v30
	v_fma_f32 v37, -v14, v33, 1.0
	v_div_scale_f32 v15, s[0:1], 1.0, v8, 1.0
	v_fma_f32 v38, -v16, v34, 1.0
	v_fmac_f32_e32 v33, v37, v33
	v_div_scale_f32 v29, s[6:7], 1.0, v11, 1.0
	v_fma_f32 v39, -v30, v35, 1.0
	v_fmac_f32_e32 v34, v38, v34
	v_mul_f32_e32 v37, v15, v33
	v_div_scale_f32 v31, s[8:9], 1.0, v10, 1.0
	v_fmac_f32_e32 v35, v39, v35
	v_mul_f32_e32 v38, v29, v34
	v_fma_f32 v41, -v14, v37, v15
	v_mul_f32_e32 v39, v31, v35
	v_fma_f32 v42, -v16, v38, v29
	v_fmac_f32_e32 v37, v41, v33
	v_fma_f32 v43, -v30, v39, v31
	v_fmac_f32_e32 v38, v42, v34
	v_fma_f32 v13, -v14, v37, v15
	s_mov_b64 vcc, s[0:1]
	v_fmac_f32_e32 v39, v43, v35
	v_fma_f32 v14, -v16, v38, v29
	v_rcp_f32_e32 v9, v9
	v_div_fmas_f32 v12, v13, v33, v37
	s_mov_b64 vcc, s[6:7]
	v_fma_f32 v15, -v30, v39, v31
	v_div_fixup_f32 v8, v12, v8, 1.0
	v_div_fmas_f32 v12, v14, v34, v38
	s_mov_b64 vcc, s[8:9]
	v_div_fixup_f32 v11, v12, v11, 1.0
	v_div_fmas_f32 v12, v15, v35, v39
	v_div_fixup_f32 v10, v12, v10, 1.0
	v_pk_mul_f32 v[14:15], v[10:11], s[22:23] op_sel_hi:[1,0]
	v_pk_mul_f32 v[12:13], v[8:9], s[22:23] op_sel_hi:[1,0]
.LBB0_920:
	s_mul_i32 s1, s55, 0x2100000
	s_mul_hi_i32 s0, s55, 0x2100000
	s_add_u32 s46, s80, s1
	s_addc_u32 s47, s92, s0
	v_lshlrev_b32_e32 v16, 11, v28
	s_waitcnt lgkmcnt(0)
	v_pk_add_f32 v[2:3], v[2:3], v[6:7]
	v_lshl_add_u64 v[6:7], s[46:47], 0, v[16:17]
	v_pk_add_f32 v[0:1], v[0:1], v[4:5]
	v_cvt_pk_bf16_f32 v4, v12, v13
	v_cvt_pk_bf16_f32 v5, v14, v15
	v_lshl_add_u64 v[6:7], v[22:23], 1, v[6:7]
	s_mov_b64 s[0:1], -1
	s_and_b64 vcc, exec, s[44:45]
	global_store_dwordx2 v[6:7], v[4:5], off
	s_cbranch_vccz .LBB0_924
	v_mov_b64_e32 v[6:7], v[2:3]
	s_cmp_lg_u32 s55, 1
	v_mov_b64_e32 v[4:5], v[0:1]
	s_cbranch_scc1 .LBB0_923
	v_lshl_add_u64 v[4:5], v[22:23], 2, s[42:43]
	global_load_dwordx4 v[4:7], v[4:5], off
	s_waitcnt vmcnt(0)
	v_add_f32_e32 v6, v2, v6
	v_add_f32_e32 v7, v3, v7
	v_mul_f32_e32 v6, 0xbfb8aa3b, v6
	v_mul_f32_e32 v7, 0xbfb8aa3b, v7
	v_add_f32_e32 v4, v0, v4
	v_add_f32_e32 v5, v1, v5
	v_exp_f32_e32 v6, v6
	v_exp_f32_e32 v7, v7
	v_mul_f32_e32 v4, 0xbfb8aa3b, v4
	v_mul_f32_e32 v5, 0xbfb8aa3b, v5
	v_exp_f32_e32 v4, v4
	v_exp_f32_e32 v5, v5
	v_pk_add_f32 v[6:7], v[6:7], 1.0 op_sel_hi:[1,0]
	v_pk_add_f32 v[4:5], v[4:5], 1.0 op_sel_hi:[1,0]
	v_div_scale_f32 v10, s[0:1], v6, v6, 1.0
	v_div_scale_f32 v12, s[6:7], v5, v5, 1.0
	v_rcp_f32_e32 v28, v10
	v_div_scale_f32 v14, s[8:9], v4, v4, 1.0
	v_rcp_f32_e32 v29, v12
	v_rcp_f32_e32 v30, v14
	v_fma_f32 v32, -v10, v28, 1.0
	v_div_scale_f32 v11, s[0:1], 1.0, v6, 1.0
	v_fma_f32 v33, -v12, v29, 1.0
	v_fmac_f32_e32 v28, v32, v28
	v_div_scale_f32 v13, s[6:7], 1.0, v5, 1.0
	v_fma_f32 v34, -v14, v30, 1.0
	v_fmac_f32_e32 v29, v33, v29
	v_mul_f32_e32 v32, v11, v28
	v_div_scale_f32 v15, s[8:9], 1.0, v4, 1.0
	v_fmac_f32_e32 v30, v34, v30
	v_mul_f32_e32 v33, v13, v29
	v_fma_f32 v36, -v10, v32, v11
	v_mul_f32_e32 v34, v15, v30
	v_fma_f32 v37, -v12, v33, v13
	v_fmac_f32_e32 v32, v36, v28
	v_fma_f32 v38, -v14, v34, v15
	v_fmac_f32_e32 v33, v37, v29
	v_fma_f32 v9, -v10, v32, v11
	s_mov_b64 vcc, s[0:1]
	v_fmac_f32_e32 v34, v38, v30
	v_fma_f32 v10, -v12, v33, v13
	v_rcp_f32_e32 v7, v7
	v_div_fmas_f32 v8, v9, v28, v32
	s_mov_b64 vcc, s[6:7]
	v_fma_f32 v11, -v14, v34, v15
	v_div_fixup_f32 v6, v8, v6, 1.0
	v_div_fmas_f32 v8, v10, v29, v33
	s_mov_b64 vcc, s[8:9]
	v_div_fixup_f32 v5, v8, v5, 1.0
	v_div_fmas_f32 v8, v11, v30, v34
	v_div_fixup_f32 v4, v8, v4, 1.0

; __device__ __forceinline__ u32x2 pack4(f32x4 v) { u32x2 r; r.x = cvt_pk_bf16(v.x, v.y); r.y = cvt_pk_bf16(v.z, v.w); return r; }
; __device__ __forceinline__ float sigm(float x) { return 1.0f / (1.0f + __expf(-x)); }
; __device__ __forceinline__ float decay_e(float pre) { return 0.6065306597126334f * sigm(pre); }
; template <int ph>
; __device__ __forceinline__ void run_phase(const Args& args, LAS unsigned char* lds, const int G, const int bx, const bool fin = true) {
;     ...
;         skinny<false>(LB, 256, LORAT, 256, 256, 0, 12, 0, bx, G, tid, lds, [&](int row, int tile, int cin, f32x4 a, f32x4) {
;             const int kind = tile >> 2, c = (tile & 3) * 256 + cin; f32x4 o = a;
;             if (kind == 0) { const f32x4 bb = *(const f32x4*)(decay_w0 + c); o = (f32x4){decay_e(a[0] + bb[0]), decay_e(a[1] + bb[1]), decay_e(a[2] + bb[2]), decay_e(a[3] + bb[3])}; }
;             else if (kind == 1) { const f32x4 bb = *(const f32x4*)(aaa_a0 + c); o = (f32x4){sigm(a[0] + bb[0]), sigm(a[1] + bb[1]), sigm(a[2] + bb[2]), sigm(a[3] + bb[3])}; }
;             bf16_t* base = WD + (size_t)kind * ((WS_AA - WS_WD) / 2); *(u32x2*)(base + (size_t)row * D + c) = pack4(o); });
.LBB0_924:
	s_andn2_b64 vcc, exec, s[0:1]
	s_cbranch_vccnz .LBB0_909
	v_lshl_add_u64 v[4:5], v[22:23], 2, s[38:39]
	global_load_dwordx4 v[4:7], v[4:5], off
	s_waitcnt vmcnt(0)
	v_add_f32_e32 v0, v0, v4
	v_add_f32_e32 v1, v1, v5
	v_mul_f32_e32 v0, 0xbfb8aa3b, v0
	v_mul_f32_e32 v1, 0xbfb8aa3b, v1
	v_add_f32_e32 v2, v2, v6
	v_add_f32_e32 v3, v3, v7
	v_exp_f32_e32 v0, v0
	v_exp_f32_e32 v1, v1
	v_mul_f32_e32 v2, 0xbfb8aa3b, v2
	v_mul_f32_e32 v3, 0xbfb8aa3b, v3
	v_exp_f32_e32 v2, v2
	v_exp_f32_e32 v3, v3
	v_pk_add_f32 v[0:1], v[0:1], 1.0 op_sel_hi:[1,0]
	v_pk_add_f32 v[2:3], v[2:3], 1.0 op_sel_hi:[1,0]
	v_div_scale_f32 v6, s[0:1], v0, v0, 1.0
	v_div_scale_f32 v8, s[6:7], v3, v3, 1.0
	v_rcp_f32_e32 v13, v6
	v_div_scale_f32 v10, s[8:9], v2, v2, 1.0
	v_rcp_f32_e32 v14, v8
	v_rcp_f32_e32 v15, v10
	v_fma_f32 v28, -v6, v13, 1.0
	v_div_scale_f32 v7, s[0:1], 1.0, v0, 1.0
	v_fma_f32 v29, -v8, v14, 1.0
	v_fmac_f32_e32 v13, v28, v13
	v_div_scale_f32 v9, s[6:7], 1.0, v3, 1.0
	v_fma_f32 v30, -v10, v15, 1.0
	v_fmac_f32_e32 v14, v29, v14
	v_mul_f32_e32 v28, v7, v13
	v_div_scale_f32 v11, s[8:9], 1.0, v2, 1.0
	v_fmac_f32_e32 v15, v30, v15
	v_mul_f32_e32 v29, v9, v14
	v_fma_f32 v32, -v6, v28, v7
	v_mul_f32_e32 v30, v11, v15
	v_fma_f32 v33, -v8, v29, v9
	v_fmac_f32_e32 v28, v32, v13
	v_fma_f32 v34, -v10, v30, v11
	v_fmac_f32_e32 v29, v33, v14
	v_fma_f32 v5, -v6, v28, v7
	s_mov_b64 vcc, s[0:1]
	v_fmac_f32_e32 v30, v34, v15
	v_fma_f32 v6, -v8, v29, v9
	v_rcp_f32_e32 v1, v1
	v_div_fmas_f32 v4, v5, v13, v28
	s_mov_b64 vcc, s[6:7]
	v_fma_f32 v7, -v10, v30, v11
	v_div_fixup_f32 v0, v4, v0, 1.0
	v_div_fmas_f32 v4, v6, v14, v29
	s_mov_b64 vcc, s[8:9]
	v_div_fixup_f32 v3, v4, v3, 1.0
	v_div_fmas_f32 v4, v7, v15, v30
	v_div_fixup_f32 v2, v4, v2, 1.0
	v_pk_mul_f32 v[6:7], v[2:3], s[22:23] op_sel_hi:[1,0]
	v_pk_mul_f32 v[4:5], v[0:1], s[22:23] op_sel_hi:[1,0]
	s_branch .LBB0_909

; __device__ __forceinline__ u32x2 pack4(f32x4 v) { u32x2 r; r.x = cvt_pk_bf16(v.x, v.y); r.y = cvt_pk_bf16(v.z, v.w); return r; }
; __device__ __forceinline__ float sigm(float x) { return 1.0f / (1.0f + __expf(-x)); }
; template <bool PAIR, class F>
; __device__ __forceinline__ void skinny(const bf16_t* A, int lda, const bf16_t* Bt, int ldb, int K, int tile_lo, int tile_hi, int kmode, int bx, int G, int tid_, LAS unsigned char* lds, F f) {
;     ...
;         if (kh == 1) { X[0] = a00; X[1] = a01; if (PAIR) { X[2] = a10; X[3] = a11; } }
;         __syncthreads();
;         if (kh == 0) {
;             a00 = a00 + X[0]; a01 = a01 + X[1]; if (PAIR) { a10 = a10 + X[2]; a11 = a11 + X[3]; }
;             f(row0, tile, cgp * 16 + 4 * fq, a00, a10);
;             f(row0 + 16, tile, cgp * 16 + 4 * fq, a01, a11);
; template <int ph>
; __device__ __forceinline__ void run_phase(const Args& args, LAS unsigned char* lds, const int G, const int bx, const bool fin = true) {
;     ...
;         skinny<true>(XC, D, LRUT, 256, 256, 0, 8, 1, bx, G, tid, lds, [&](int row, int tile, int cin, f32x4 a, f32x4 b) {
;             const int c = tile * 128 + cin; const f32x4 b0 = *(const f32x4*)(lru_br + c), b1 = *(const f32x4*)(lru_bi + c);
;             *(u32x2*)(GR + (size_t)row * D + c) = pack4((f32x4){sigm(a[0] + b0[0]), sigm(a[1] + b0[1]), sigm(a[2] + b0[2]), sigm(a[3] + b0[3])});
;             *(u32x2*)(GI + (size_t)row * D + c) = pack4((f32x4){sigm(b[0] + b1[0]), sigm(b[1] + b1[1]), sigm(b[2] + b1[2]), sigm(b[3] + b1[3])}); });
.LBB0_931:
	s_andn2_b64 vcc, exec, s[14:15]
	s_waitcnt lgkmcnt(0)
	s_barrier
	s_cbranch_vccnz .LBB0_928
	v_or_b32_e32 v8, s1, v37
	v_add_u32_e32 v30, s0, v8
	v_ashrrev_i32_e32 v31, 31, v30
	v_readlane_b32 s52, v229, 32
	v_lshlrev_b64 v[8:9], 2, v[30:31]
	v_readlane_b32 s53, v229, 33
	v_readlane_b32 s54, v229, 34
	v_readlane_b32 s55, v229, 35
	v_readlane_b32 s56, v229, 36
	v_readlane_b32 s57, v229, 37
	v_readlane_b32 s58, v229, 38
	v_readlane_b32 s59, v229, 39
	v_readlane_b32 s60, v229, 40
	v_readlane_b32 s61, v229, 41
	v_readlane_b32 s62, v229, 42
	v_readlane_b32 s63, v229, 43
	v_readlane_b32 s64, v229, 44
	v_readlane_b32 s65, v229, 45
	v_readlane_b32 s66, v229, 46
	v_readlane_b32 s67, v229, 47
	v_lshl_add_u64 v[32:33], s[64:65], 0, v[8:9]
	v_readlane_b32 s52, v229, 48
	v_readlane_b32 s53, v229, 49
	global_load_dwordx4 v[42:45], v[32:33], off
	v_lshl_add_u64 v[58:59], s[70:71], 0, v[24:25]
	v_lshl_add_u64 v[34:35], s[52:53], 0, v[8:9]
	global_load_dwordx4 v[46:49], v[34:35], off
	ds_read_b128 v[50:53], v38 offset:32768
	ds_read_b128 v[12:15], v38 offset:32784
	ds_read_b128 v[54:57], v38 offset:32800
	ds_read_b128 v[8:11], v38 offset:32816
	v_lshlrev_b64 v[30:31], 1, v[30:31]
	s_waitcnt lgkmcnt(3)
	v_pk_add_f32 v[20:21], v[20:21], v[50:51]
	v_pk_add_f32 v[22:23], v[22:23], v[52:53]
	s_waitcnt lgkmcnt(1)
	v_pk_add_f32 v[16:17], v[16:17], v[54:55]
	v_pk_add_f32 v[18:19], v[18:19], v[56:57]
	v_lshl_add_u64 v[58:59], v[58:59], 0, v[30:31]
	v_pk_add_f32 v[4:5], v[4:5], v[12:13]
	s_waitcnt lgkmcnt(0)
	v_pk_add_f32 v[0:1], v[0:1], v[8:9]
	v_pk_add_f32 v[6:7], v[6:7], v[14:15]
	v_pk_add_f32 v[2:3], v[2:3], v[10:11]
	v_readlane_b32 s54, v229, 50
	v_readlane_b32 s55, v229, 51
	v_readlane_b32 s56, v229, 52
	v_readlane_b32 s57, v229, 53
	v_readlane_b32 s58, v229, 54
	v_readlane_b32 s59, v229, 55
	v_readlane_b32 s60, v229, 56
	v_readlane_b32 s61, v229, 57
	v_readlane_b32 s62, v229, 58
	v_readlane_b32 s63, v229, 59
	v_readlane_b32 s64, v229, 60
	v_readlane_b32 s65, v229, 61
	v_readlane_b32 s66, v229, 62
	v_readlane_b32 s67, v229, 63
	s_waitcnt vmcnt(1)
	v_add_f32_e32 v20, v20, v42
	v_add_f32_e32 v21, v21, v43
	v_mul_f32_e32 v20, 0xbfb8aa3b, v20
	s_waitcnt vmcnt(0)
	v_add_f32_e32 v16, v16, v46
	v_add_f32_e32 v17, v17, v47
	v_mul_f32_e32 v21, 0xbfb8aa3b, v21
	v_add_f32_e32 v22, v22, v44
	v_add_f32_e32 v23, v23, v45
	v_mul_f32_e32 v41, 0xbfb8aa3b, v16
	v_mul_f32_e32 v42, 0xbfb8aa3b, v17
	v_exp_f32_e32 v16, v20
	v_exp_f32_e32 v17, v21
	v_mul_f32_e32 v22, 0xbfb8aa3b, v22
	v_mul_f32_e32 v23, 0xbfb8aa3b, v23
	v_exp_f32_e32 v20, v22
	v_exp_f32_e32 v21, v23
	v_pk_add_f32 v[16:17], v[16:17], 1.0 op_sel_hi:[1,0]
	v_exp_f32_e32 v22, v41
	v_pk_add_f32 v[20:21], v[20:21], 1.0 op_sel_hi:[1,0]
	v_div_scale_f32 v43, s[0:1], v16, v16, 1.0
	v_div_scale_f32 v45, s[4:5], v21, v21, 1.0
	v_rcp_f32_e32 v54, v43
	v_exp_f32_e32 v23, v42
	v_div_scale_f32 v47, s[6:7], v20, v20, 1.0
	v_rcp_f32_e32 v55, v45
	v_rcp_f32_e32 v56, v47
	v_fma_f32 v61, -v43, v54, 1.0
	v_pk_add_f32 v[22:23], v[22:23], 1.0 op_sel_hi:[1,0]
	v_div_scale_f32 v44, s[0:1], 1.0, v16, 1.0
	v_fma_f32 v62, -v45, v55, 1.0
	v_fmac_f32_e32 v54, v61, v54
	v_div_scale_f32 v46, s[4:5], 1.0, v21, 1.0
	v_div_scale_f32 v51, s[8:9], v23, v23, 1.0
	v_fma_f32 v63, -v47, v56, 1.0
	v_fmac_f32_e32 v55, v62, v55
	v_mul_f32_e32 v61, v44, v54
	v_div_scale_f32 v50, s[6:7], 1.0, v20, 1.0
	v_rcp_f32_e32 v57, v51
	v_fmac_f32_e32 v56, v63, v56
	v_mul_f32_e32 v62, v46, v55
	v_fma_f32 v66, -v43, v61, v44
	v_mul_f32_e32 v63, v50, v56
	v_fma_f32 v67, -v45, v62, v46
	v_fmac_f32_e32 v61, v66, v54
	v_fma_f32 v68, -v47, v63, v50
	v_fmac_f32_e32 v62, v67, v55
	v_fma_f32 v42, -v43, v61, v44
	s_mov_b64 vcc, s[0:1]
	v_fmac_f32_e32 v63, v68, v56
	v_fma_f32 v43, -v45, v62, v46
	v_rcp_f32_e32 v17, v17
	v_div_fmas_f32 v41, v42, v54, v61
	s_mov_b64 vcc, s[4:5]
	v_fma_f32 v64, -v51, v57, 1.0
	v_fma_f32 v44, -v47, v63, v50
	v_div_fixup_f32 v16, v41, v16, 1.0
	v_div_fmas_f32 v41, v43, v55, v62
	s_mov_b64 vcc, s[6:7]
	v_div_scale_f32 v52, s[8:9], 1.0, v23, 1.0
	v_fmac_f32_e32 v57, v64, v57
	v_div_fixup_f32 v21, v41, v21, 1.0
	v_div_fmas_f32 v41, v44, v56, v63
	v_mul_f32_e32 v64, v52, v57
	v_cvt_pk_bf16_f32 v16, v16, v17
	v_div_fixup_f32 v17, v41, v20, 1.0
	v_fma_f32 v69, -v51, v64, v52
	v_cvt_pk_bf16_f32 v17, v17, v21
	v_fmac_f32_e32 v64, v69, v57
	v_fma_f32 v45, -v51, v64, v52
	s_mov_b64 vcc, s[8:9]
	global_store_dwordx2 v[58:59], v[16:17], off
	v_div_fmas_f32 v16, v45, v57, v64
	v_div_fixup_f32 v23, v16, v23, 1.0
	v_add_f32_e32 v16, v18, v48
	v_add_f32_e32 v17, v19, v49
	v_mul_f32_e32 v16, 0xbfb8aa3b, v16
	v_mul_f32_e32 v17, 0xbfb8aa3b, v17
	v_exp_f32_e32 v16, v16
	v_exp_f32_e32 v17, v17
	s_nop 0
	v_pk_add_f32 v[16:17], v[16:17], 1.0 op_sel_hi:[1,0]
	v_rcp_f32_e32 v18, v22
	v_rcp_f32_e32 v17, v17
	v_rcp_f32_e32 v19, v16
	v_cvt_pk_bf16_f32 v16, v18, v23
	v_cvt_pk_bf16_f32 v17, v19, v17
	v_lshl_add_u64 v[18:19], s[72:73], 0, v[24:25]
	v_lshl_add_u64 v[18:19], v[18:19], 0, v[30:31]
	global_store_dwordx2 v[18:19], v[16:17], off
	global_load_dwordx4 v[16:19], v[32:33], off
	s_nop 0
	global_load_dwordx4 v[20:23], v[34:35], off
	v_lshl_or_b32 v24, v40, 1, v39
	s_waitcnt vmcnt(1)
	v_add_f32_e32 v4, v4, v16
	v_add_f32_e32 v5, v5, v17
	v_mul_f32_e32 v4, 0xbfb8aa3b, v4
	v_mul_f32_e32 v5, 0xbfb8aa3b, v5
	v_exp_f32_e32 v4, v4
	v_exp_f32_e32 v5, v5
	v_add_f32_e32 v6, v6, v18
	v_add_f32_e32 v7, v7, v19
	v_mul_f32_e32 v6, 0xbfb8aa3b, v6
	v_pk_add_f32 v[4:5], v[4:5], 1.0 op_sel_hi:[1,0]
	v_mul_f32_e32 v7, 0xbfb8aa3b, v7
	v_div_scale_f32 v10, s[0:1], v4, v4, 1.0
	s_nop 0
	v_rcp_f32_e32 v13, v10
	v_exp_f32_e32 v6, v6
	v_exp_f32_e32 v7, v7
	v_fma_f32 v16, -v10, v13, 1.0
	v_pk_add_f32 v[6:7], v[6:7], 1.0 op_sel_hi:[1,0]
	v_div_scale_f32 v11, s[0:1], 1.0, v4, 1.0
	v_fmac_f32_e32 v13, v16, v13
	v_mul_f32_e32 v16, v11, v13
	v_fma_f32 v18, -v10, v16, v11
	v_rcp_f32_e32 v5, v5
	v_fmac_f32_e32 v16, v18, v13
	v_fma_f32 v9, -v10, v16, v11
	s_mov_b64 vcc, s[0:1]
	v_div_fmas_f32 v9, v9, v13, v16
	v_div_fixup_f32 v4, v9, v4, 1.0
	v_rcp_f32_e32 v7, v7
	s_waitcnt vmcnt(0)
	v_add_f32_e32 v0, v0, v20
	v_add_f32_e32 v1, v1, v21
	v_mul_f32_e32 v0, 0xbfb8aa3b, v0
	v_mul_f32_e32 v1, 0xbfb8aa3b, v1
	v_exp_f32_e32 v0, v0
	v_exp_f32_e32 v1, v1
	s_nop 0
	v_pk_add_f32 v[0:1], v[0:1], 1.0 op_sel_hi:[1,0]
	v_rcp_f32_e32 v6, v6
	v_cvt_pk_bf16_f32 v4, v4, v5
	v_cvt_pk_bf16_f32 v5, v6, v7
	v_lshl_add_u64 v[6:7], s[70:71], 0, v[24:25]
	v_lshl_add_u64 v[6:7], v[6:7], 0, v[30:31]
	global_store_dwordx2 v[6:7], v[4:5], off
	v_add_f32_e32 v2, v2, v22
	v_add_f32_e32 v3, v3, v23
	v_mul_f32_e32 v2, 0xbfb8aa3b, v2
	v_mul_f32_e32 v3, 0xbfb8aa3b, v3
	v_rcp_f32_e32 v1, v1
	v_exp_f32_e32 v2, v2
	v_exp_f32_e32 v3, v3
	s_nop 0
	v_pk_add_f32 v[2:3], v[2:3], 1.0 op_sel_hi:[1,0]
	v_rcp_f32_e32 v0, v0
	s_nop 0
	v_cvt_pk_bf16_f32 v0, v0, v1
	v_rcp_f32_e32 v3, v3
	v_rcp_f32_e32 v2, v2
	s_nop 0
	v_cvt_pk_bf16_f32 v1, v2, v3
	v_lshl_add_u64 v[2:3], s[72:73], 0, v[24:25]
	v_lshl_add_u64 v[2:3], v[2:3], 0, v[30:31]
	global_store_dwordx2 v[2:3], v[0:1], off
	s_branch .LBB0_928

; #define LAS __attribute__((address_space(3)))
; __device__ __forceinline__ f32x4 unpack4(u32x2 u) { return (f32x4){__uint_as_float(u.x << 16), __uint_as_float(u.x & 0xffff0000u), __uint_as_float(u.y << 16), __uint_as_float(u.y & 0xffff0000u)}; }
; __device__ __forceinline__ float dot4(f32x4 a, f32x4 b) { return (a.x * b.x + a.y * b.y) + (a.z * b.z + a.w * b.w); }
; template <int ph>
; __device__ __forceinline__ void run_phase(const Args& args, LAS unsigned char* lds, const int G, const int bx, const bool fin = true) {
;     ...
;                     const int tg = chunk * TC + tt0 + 16 * it; const size_t row = (size_t)b * T + tg; const bf16_t* base = PR + row * RP + chb;
;                     q_r[it] = *(const u32x2*)(base); q_k[it] = *(const u32x2*)(base + 1024); q_v[it] = *(const u32x2*)(base + 2048);
;                     if (tg > 0) { q_rp[it] = *(const u32x2*)(base - RP); q_kp[it] = *(const u32x2*)(base - RP + 1024); q_vp[it] = *(const u32x2*)(base - RP + 2048); }
;                     else { q_rp[it] = (u32x2){0u, 0u}; q_kp[it] = q_rp[it]; q_vp[it] = q_rp[it]; }
;                     q_e[it] = *(const u32x2*)(WD + row * D + chb); q_a[it] = *(const u32x2*)(AA + row * D + chb);
;     ...
;                     const f32x4 pr = unpack4(q_r[it]), pk = unpack4(q_k[it]), pv = unpack4(q_v[it]);
;                     const f32x4 r = pr + (unpack4(q_rp[it]) - pr) * mu_r, k = pk + (unpack4(q_kp[it]) - pk) * mu_k, v = pv + (unpack4(q_vp[it]) - pv) * mu_v;
;                     const f32x4 e = unpack4(q_e[it]), a = unpack4(q_a[it]);
;                     const f32x4 w = (f32x4){__expf(-e[0]), __expf(-e[1]), __expf(-e[2]), __expf(-e[3])};
;                     f32x4 kk = k * kkc; const float n2 = red16(dot4(kk, kk)); kk = kk * (1.0f / fmaxf(sqrtf(n2), 1e-12f));
;                     const f32x4 kp = k * (1.0f + (a - 1.0f) * kac), bv = kk * a, wrv = w * r;
;                     const float br = red16(dot4(bv, r)), kr = red16(dot4(kp, r));
;                     const int o = tt * 64 + 4 * cgq;
;                     *(LAS f32x4*)(V + 0 * TC * 64 + o) = -kk; *(LAS f32x4*)(V + 1 * TC * 64 + o) = wrv; *(LAS f32x4*)(V + 2 * TC * 64 + o) = w;
;                     *(LAS f32x4*)(V + 3 * TC * 64 + o) = bv; *(LAS f32x4*)(V + 4 * TC * 64 + o) = kp; *(LAS f32x4*)(V + 5 * TC * 64 + o) = v;
.LBB0_999:
	s_or_b64 exec, exec, s[0:1]
	v_lshlrev_b64 v[34:35], 11, v[34:35]
	v_lshl_add_u64 v[36:37], s[20:21], 0, v[34:35]
	v_lshl_add_u64 v[36:37], v[36:37], 0, v[20:21]
	global_load_dwordx2 v[38:39], v[36:37], off
	v_lshl_add_u64 v[34:35], s[22:23], 0, v[34:35]
	v_lshl_add_u64 v[34:35], v[34:35], 0, v[20:21]
	global_load_dwordx2 v[40:41], v[34:35], off
	v_or_b32_e32 v34, s42, v74
	v_mov_b64_e32 v[36:37], s[8:9]
	v_mov_b32_e32 v35, s43
	s_waitcnt vmcnt(0)
	v_lshlrev_b32_e32 v42, 16, v30
	v_and_b32_e32 v43, 0xffff0000, v30
	v_lshlrev_b32_e32 v44, 16, v26
	v_and_b32_e32 v45, 0xffff0000, v26
	v_lshlrev_b32_e32 v26, 16, v27
	v_and_b32_e32 v27, 0xffff0000, v27
	v_lshlrev_b32_e32 v46, 16, v28
	v_and_b32_e32 v47, 0xffff0000, v28
	v_lshlrev_b32_e32 v28, 16, v29
	v_and_b32_e32 v29, 0xffff0000, v29
	v_lshlrev_b32_e32 v48, 16, v32
	v_and_b32_e32 v49, 0xffff0000, v32
	v_lshlrev_b32_e32 v50, 16, v24
	v_and_b32_e32 v51, 0xffff0000, v24
	v_lshlrev_b32_e32 v52, 16, v25
	v_and_b32_e32 v53, 0xffff0000, v25
	v_lshlrev_b32_e32 v54, 16, v22
	v_and_b32_e32 v55, 0xffff0000, v22
	v_lshlrev_b32_e32 v56, 16, v23
	v_and_b32_e32 v57, 0xffff0000, v23
	v_mad_u64_u32 v[22:23], s[0:1], v34, s52, v[36:37]
	v_lshlrev_b32_e32 v30, 16, v31
	v_and_b32_e32 v31, 0xffff0000, v31
	v_lshlrev_b32_e32 v32, 16, v33
	v_and_b32_e32 v33, 0xffff0000, v33
	v_lshlrev_b64 v[24:25], 11, v[34:35]
	v_sub_f32_e32 v35, v49, v43
	v_sub_f32_e32 v34, v48, v42
	v_sub_f32_e32 v37, v51, v45
	v_sub_f32_e32 v36, v50, v44
	v_sub_f32_e32 v49, v53, v27
	v_sub_f32_e32 v48, v52, v26
	v_sub_f32_e32 v53, v57, v29
	v_sub_f32_e32 v52, v56, v28
	v_mad_i32_i24 v23, s43, v153, v23
	v_sub_f32_e32 v33, v33, v31
	v_sub_f32_e32 v32, v32, v30
	v_pk_fma_f32 v[58:59], v[12:13], v[36:37], v[44:45]
	v_pk_fma_f32 v[44:45], v[10:11], v[52:53], v[28:29]
	v_lshl_add_u64 v[28:29], v[22:23], 0, v[20:21]
	v_pk_fma_f32 v[88:89], v[18:19], v[32:33], v[30:31]
	v_add_co_u32_e32 v32, vcc, s53, v28
	v_sub_f32_e32 v51, v55, v47
	v_sub_f32_e32 v50, v54, v46
	v_lshl_add_u64 v[54:55], s[20:21], 0, v[24:25]
	v_lshl_add_u64 v[24:25], s[22:23], 0, v[24:25]
	v_addc_co_u32_e32 v33, vcc, 0, v29, vcc
	v_pk_fma_f32 v[66:67], v[16:17], v[34:35], v[42:43]
	v_pk_fma_f32 v[42:43], v[8:9], v[50:51], v[46:47]
	v_lshl_add_u64 v[22:23], v[54:55], 0, v[20:21]
	v_lshl_add_u64 v[30:31], v[24:25], 0, v[20:21]
	v_add_co_u32_e32 v46, vcc, s54, v28
	v_pk_fma_f32 v[56:57], v[14:15], v[48:49], v[26:27]
	s_nop 0
	v_addc_co_u32_e32 v47, vcc, -1, v29, vcc
	global_load_dwordx2 v[34:35], v[28:29], off
	global_load_dwordx2 v[26:27], v[28:29], off offset:-2560
	global_load_dwordx2 v[24:25], v[22:23], off
	s_nop 0
	global_load_dwordx2 v[22:23], v[30:31], off
	global_load_dwordx2 v[36:37], v[28:29], off offset:2048
	s_nop 0
	global_load_dwordx2 v[32:33], v[32:33], off
	s_nop 0
	global_load_dwordx2 v[30:31], v[46:47], off offset:-2560
	global_load_dwordx2 v[28:29], v[46:47], off offset:-512
	v_pk_mul_f32 v[54:55], v[0:1], v[58:59]
	v_pk_mul_f32 v[60:61], v[2:3], v[56:57]
	v_pk_mul_f32 v[50:51], v[54:55], v[54:55]
	v_pk_mul_f32 v[48:49], v[60:61], v[60:61]
	v_lshlrev_b32_e32 v21, 16, v38
	v_pk_mov_b32 v[52:53], v[50:51], v[48:49] op_sel:[1,0]
	v_mov_b32_e32 v51, v49
	v_mul_f32_e32 v21, 0xbfb8aa3b, v21
	v_pk_add_f32 v[48:49], v[52:53], v[50:51]
	v_exp_f32_e32 v46, v21
	v_add_f32_e32 v21, v48, v49
	v_lshlrev_b32_e32 v62, 16, v39
	v_mul_f32_e32 v49, 0xbfb8aa3b, v62
	v_add_f32_dpp v21, v21, v21 quad_perm:[1,0,3,2] row_mask:0xf bank_mask:0xf bound_ctrl:1
	v_and_b32_e32 v47, 0xffff0000, v38
	v_and_b32_e32 v63, 0xffff0000, v39
	v_add_f32_dpp v21, v21, v21 quad_perm:[2,3,0,1] row_mask:0xf bank_mask:0xf bound_ctrl:1
	v_lshlrev_b32_e32 v38, 16, v40
	v_and_b32_e32 v39, 0xffff0000, v40
	v_add_f32_dpp v21, v21, v21 row_half_mirror row_mask:0xf bank_mask:0xf bound_ctrl:1
	v_lshlrev_b32_e32 v40, 16, v41
	v_and_b32_e32 v41, 0xffff0000, v41
	v_add_f32_dpp v21, v21, v21 row_mirror row_mask:0xf bank_mask:0xf bound_ctrl:1
	v_mul_f32_e32 v48, 0x4f800000, v21
	v_cmp_gt_f32_e32 vcc, s55, v21
	v_mul_f32_e32 v47, 0xbfb8aa3b, v47
	v_exp_f32_e32 v47, v47
	v_cndmask_b32_e32 v21, v21, v48, vcc
	v_sqrt_f32_e32 v48, v21
	s_nop 0
	v_add_u32_e32 v50, -1, v48
	v_fma_f32 v51, -v50, v48, v21
	v_cmp_ge_f32_e64 s[0:1], 0, v51
	v_add_u32_e32 v51, 1, v48
	s_nop 0
	v_cndmask_b32_e64 v50, v48, v50, s[0:1]
	v_fma_f32 v48, -v51, v48, v21
	v_cmp_lt_f32_e64 s[0:1], 0, v48
	s_nop 1
	v_cndmask_b32_e64 v48, v50, v51, s[0:1]
	v_mul_f32_e32 v50, 0x37800000, v48
	v_cndmask_b32_e32 v48, v48, v50, vcc
	v_cmp_class_f32_e32 vcc, v21, v152
	s_nop 1
	v_cndmask_b32_e32 v21, v48, v21, vcc
	v_max_f32_e32 v21, 0x2b8cbccc, v21
	v_div_scale_f32 v50, s[0:1], v21, v21, -1.0
	s_nop 0
	v_rcp_f32_e32 v51, v50
	v_exp_f32_e32 v48, v49
	v_mul_f32_e32 v49, 0xbfb8aa3b, v63
	v_exp_f32_e32 v49, v49
	v_fma_f32 v52, -v50, v51, 1.0
	v_fmac_f32_e32 v51, v52, v51
	v_div_scale_f32 v52, vcc, -1.0, v21, -1.0
	v_mul_f32_e32 v53, v52, v51
	v_fma_f32 v62, -v50, v53, v52
	v_fmac_f32_e32 v53, v62, v51
	v_fma_f32 v50, -v50, v53, v52
	v_div_fmas_f32 v50, v50, v51, v53
	v_div_fixup_f32 v62, v50, v21, -1.0
	v_pk_add_f32 v[50:51], v[40:41], -1.0 op_sel_hi:[1,0]
	v_pk_add_f32 v[52:53], v[38:39], -1.0 op_sel_hi:[1,0]
	v_pk_fma_f32 v[50:51], v[6:7], v[50:51], 1.0 op_sel_hi:[1,1,0]
	v_pk_fma_f32 v[64:65], v[4:5], v[52:53], 1.0 op_sel_hi:[1,1,0]
	v_pk_mul_f32 v[54:55], v[54:55], v[62:63] op_sel_hi:[1,0]
	v_pk_mul_f32 v[52:53], v[56:57], v[50:51]
	v_pk_mul_f32 v[50:51], v[58:59], v[64:65]
	v_pk_mul_f32 v[56:57], v[60:61], v[62:63] op_sel_hi:[1,0]
	v_pk_mul_f32 v[58:59], v[54:55], v[38:39] neg_lo:[1,0] neg_hi:[1,0]
	v_pk_mul_f32 v[60:61], v[56:57], v[40:41] neg_lo:[1,0] neg_hi:[1,0]
; #define LAS __attribute__((address_space(3)))
; __device__ __forceinline__ f32x4 unpack4(u32x2 u) { return (f32x4){__uint_as_float(u.x << 16), __uint_as_float(u.x & 0xffff0000u), __uint_as_float(u.y << 16), __uint_as_float(u.y & 0xffff0000u)}; }
; __device__ __forceinline__ float dot4(f32x4 a, f32x4 b) { return (a.x * b.x + a.y * b.y) + (a.z * b.z + a.w * b.w); }
; template <int ph>
; __device__ __forceinline__ void run_phase(const Args& args, LAS unsigned char* lds, const int G, const int bx, const bool fin = true) {
;     ...
;                     const f32x4 pr = unpack4(q_r[it]), pk = unpack4(q_k[it]), pv = unpack4(q_v[it]);
;                     const f32x4 r = pr + (unpack4(q_rp[it]) - pr) * mu_r, k = pk + (unpack4(q_kp[it]) - pk) * mu_k, v = pv + (unpack4(q_vp[it]) - pv) * mu_v;
;                     const f32x4 e = unpack4(q_e[it]), a = unpack4(q_a[it]);
;                     const f32x4 w = (f32x4){__expf(-e[0]), __expf(-e[1]), __expf(-e[2]), __expf(-e[3])};
;                     f32x4 kk = k * kkc; const float n2 = red16(dot4(kk, kk)); kk = kk * (1.0f / fmaxf(sqrtf(n2), 1e-12f));
;                     const f32x4 kp = k * (1.0f + (a - 1.0f) * kac), bv = kk * a, wrv = w * r;
;                     const float br = red16(dot4(bv, r)), kr = red16(dot4(kp, r));
;                     const int o = tt * 64 + 4 * cgq;
;                     *(LAS f32x4*)(V + 0 * TC * 64 + o) = -kk; *(LAS f32x4*)(V + 1 * TC * 64 + o) = wrv; *(LAS f32x4*)(V + 2 * TC * 64 + o) = w;
;                     *(LAS f32x4*)(V + 3 * TC * 64 + o) = bv; *(LAS f32x4*)(V + 4 * TC * 64 + o) = kp; *(LAS f32x4*)(V + 5 * TC * 64 + o) = v;
;                     if (cgq == 0) *(LAS f32x2*)(SCb + buf * TC * 2 + 2 * tt) = (f32x2){br, kr};
	v_mov_b32_e32 v40, v58
	v_mov_b32_e32 v41, v51
	v_pk_mov_b32 v[38:39], v[58:59], v[50:51] op_sel:[1,0]
	v_pk_mul_f32 v[40:41], v[66:67], v[40:41]
	v_pk_mul_f32 v[62:63], v[66:67], v[46:47]
	v_pk_fma_f32 v[38:39], v[66:67], v[38:39], v[40:41] op_sel:[1,0,0] op_sel_hi:[0,1,1]
	v_mov_b32_e32 v66, v60
	v_mov_b32_e32 v67, v53
	v_pk_mov_b32 v[40:41], v[60:61], v[52:53] op_sel:[1,0]
	v_pk_mul_f32 v[66:67], v[88:89], v[66:67]
	v_pk_mul_f32 v[64:65], v[88:89], v[48:49]
	v_pk_fma_f32 v[40:41], v[88:89], v[40:41], v[66:67] op_sel:[1,0,0] op_sel_hi:[0,1,1]
	v_pk_add_f32 v[38:39], v[38:39], v[40:41]
	ds_write_b128 v139, v[54:57]
	ds_write_b128 v139, v[62:65] offset:8192
	ds_write_b128 v139, v[46:49] offset:16384
	ds_write_b128 v139, v[58:61] offset:24576
	ds_write_b128 v139, v[50:53] offset:32768
	ds_write_b128 v139, v[42:45] offset:40960
	v_mov_b32_dpp v40, v38 quad_perm:[1,0,3,2] row_mask:0xf bank_mask:0xf bound_ctrl:1
	v_mov_b32_dpp v41, v39 quad_perm:[1,0,3,2] row_mask:0xf bank_mask:0xf bound_ctrl:1
	v_pk_add_f32 v[38:39], v[38:39], v[40:41]
	s_nop 1
	v_mov_b32_dpp v40, v38 quad_perm:[2,3,0,1] row_mask:0xf bank_mask:0xf bound_ctrl:1
	v_mov_b32_dpp v41, v39 quad_perm:[2,3,0,1] row_mask:0xf bank_mask:0xf bound_ctrl:1
	v_pk_add_f32 v[38:39], v[38:39], v[40:41]
	s_nop 1
	v_mov_b32_dpp v40, v38 row_half_mirror row_mask:0xf bank_mask:0xf bound_ctrl:1
	v_mov_b32_dpp v41, v39 row_half_mirror row_mask:0xf bank_mask:0xf bound_ctrl:1
	v_pk_add_f32 v[38:39], v[38:39], v[40:41]
	s_nop 1
	v_mov_b32_dpp v40, v38 row_mirror row_mask:0xf bank_mask:0xf bound_ctrl:1
	v_mov_b32_dpp v41, v39 row_mirror row_mask:0xf bank_mask:0xf bound_ctrl:1
	s_and_saveexec_b64 s[0:1], s[2:3]
	v_pk_add_f32 v[38:39], v[38:39], v[40:41]
	ds_write_b64 v140, v[38:39]
	s_or_b64 exec, exec, s[0:1]
	s_waitcnt vmcnt(7)
	v_lshlrev_b32_e32 v38, 16, v34
	v_and_b32_e32 v39, 0xffff0000, v34
	v_lshlrev_b32_e32 v34, 16, v35
	v_and_b32_e32 v35, 0xffff0000, v35
	s_waitcnt vmcnt(1)
	v_lshlrev_b32_e32 v21, 16, v30
	v_and_b32_e32 v44, 0xffff0000, v30
	v_lshlrev_b32_e32 v30, 16, v31
	v_and_b32_e32 v31, 0xffff0000, v31
	v_sub_f32_e32 v31, v31, v35
	v_sub_f32_e32 v30, v30, v34
	v_lshlrev_b32_e32 v40, 16, v36
	v_and_b32_e32 v41, 0xffff0000, v36
	v_lshlrev_b32_e32 v36, 16, v37
	v_and_b32_e32 v37, 0xffff0000, v37
	v_sub_f32_e32 v45, v44, v39
	v_sub_f32_e32 v44, v21, v38
	v_pk_fma_f32 v[52:53], v[18:19], v[30:31], v[34:35]
	s_waitcnt vmcnt(0)
	v_lshlrev_b32_e32 v21, 16, v28
	v_and_b32_e32 v28, 0xffff0000, v28
	v_lshlrev_b32_e32 v30, 16, v29
	v_and_b32_e32 v31, 0xffff0000, v29
	v_lshlrev_b32_e32 v42, 16, v32
	v_and_b32_e32 v43, 0xffff0000, v32
	v_sub_f32_e32 v29, v28, v41
	v_sub_f32_e32 v28, v21, v40
	v_sub_f32_e32 v31, v31, v37
	v_sub_f32_e32 v30, v30, v36
	v_lshlrev_b32_e32 v21, 16, v26
	v_and_b32_e32 v26, 0xffff0000, v26
	v_lshlrev_b32_e32 v32, 16, v33
	v_and_b32_e32 v33, 0xffff0000, v33
	v_pk_fma_f32 v[50:51], v[16:17], v[44:45], v[38:39]
	v_pk_fma_f32 v[34:35], v[14:15], v[30:31], v[36:37]
	v_pk_fma_f32 v[38:39], v[12:13], v[28:29], v[40:41]
	v_lshlrev_b32_e32 v28, 16, v27
	v_and_b32_e32 v29, 0xffff0000, v27
	v_sub_f32_e32 v27, v26, v43
	v_sub_f32_e32 v26, v21, v42
	v_sub_f32_e32 v29, v29, v33
	v_sub_f32_e32 v28, v28, v32
	v_pk_fma_f32 v[26:27], v[8:9], v[26:27], v[42:43]
	v_pk_mul_f32 v[42:43], v[0:1], v[38:39]
	v_pk_mul_f32 v[40:41], v[2:3], v[34:35]
	v_pk_fma_f32 v[28:29], v[10:11], v[28:29], v[32:33]
	v_pk_mul_f32 v[32:33], v[40:41], v[40:41]
	v_pk_mul_f32 v[36:37], v[42:43], v[42:43]
	v_lshlrev_b32_e32 v21, 16, v24
	v_pk_mov_b32 v[44:45], v[36:37], v[32:33] op_sel:[1,0]
	v_mov_b32_e32 v37, v33
	v_mul_f32_e32 v21, 0xbfb8aa3b, v21
	v_pk_add_f32 v[32:33], v[44:45], v[36:37]
	v_exp_f32_e32 v30, v21
	v_add_f32_e32 v21, v32, v33
	v_lshlrev_b32_e32 v46, 16, v25
	v_mul_f32_e32 v33, 0xbfb8aa3b, v46
	v_add_f32_dpp v21, v21, v21 quad_perm:[1,0,3,2] row_mask:0xf bank_mask:0xf bound_ctrl:1
	v_and_b32_e32 v31, 0xffff0000, v24
	v_and_b32_e32 v47, 0xffff0000, v25
	v_add_f32_dpp v21, v21, v21 quad_perm:[2,3,0,1] row_mask:0xf bank_mask:0xf bound_ctrl:1
	v_lshlrev_b32_e32 v24, 16, v22
	v_and_b32_e32 v25, 0xffff0000, v22
	v_add_f32_dpp v21, v21, v21 row_half_mirror row_mask:0xf bank_mask:0xf bound_ctrl:1
	v_lshlrev_b32_e32 v22, 16, v23
	v_and_b32_e32 v23, 0xffff0000, v23
	v_add_f32_dpp v21, v21, v21 row_mirror row_mask:0xf bank_mask:0xf bound_ctrl:1
	v_mul_f32_e32 v32, 0x4f800000, v21
	v_cmp_gt_f32_e32 vcc, s55, v21
	v_mul_f32_e32 v31, 0xbfb8aa3b, v31
	v_exp_f32_e32 v31, v31
	v_cndmask_b32_e32 v21, v21, v32, vcc
	v_sqrt_f32_e32 v32, v21
	s_nop 0
	v_add_u32_e32 v36, -1, v32
	v_fma_f32 v37, -v36, v32, v21
	v_cmp_ge_f32_e64 s[0:1], 0, v37
	v_add_u32_e32 v37, 1, v32
	s_nop 0
	v_cndmask_b32_e64 v36, v32, v36, s[0:1]
	v_fma_f32 v32, -v37, v32, v21
	v_cmp_lt_f32_e64 s[0:1], 0, v32
	s_nop 1
	v_cndmask_b32_e64 v32, v36, v37, s[0:1]
	v_mul_f32_e32 v36, 0x37800000, v32
	v_cndmask_b32_e32 v32, v32, v36, vcc
	v_cmp_class_f32_e32 vcc, v21, v152
	s_nop 1
; #define LAS __attribute__((address_space(3)))
; __device__ __forceinline__ f32x4 unpack4(u32x2 u) { return (f32x4){__uint_as_float(u.x << 16), __uint_as_float(u.x & 0xffff0000u), __uint_as_float(u.y << 16), __uint_as_float(u.y & 0xffff0000u)}; }
; __device__ __forceinline__ float dot4(f32x4 a, f32x4 b) { return (a.x * b.x + a.y * b.y) + (a.z * b.z + a.w * b.w); }
; template <int ph>
; __device__ __forceinline__ void run_phase(const Args& args, LAS unsigned char* lds, const int G, const int bx, const bool fin = true) {
;     ...
;                     const int tg = chunk * TC + tt0 + 16 * it; const size_t row = (size_t)b * T + tg; const bf16_t* base = PR + row * RP + chb;
;                     q_r[it] = *(const u32x2*)(base); q_k[it] = *(const u32x2*)(base + 1024); q_v[it] = *(const u32x2*)(base + 2048);
;                     if (tg > 0) { q_rp[it] = *(const u32x2*)(base - RP); q_kp[it] = *(const u32x2*)(base - RP + 1024); q_vp[it] = *(const u32x2*)(base - RP + 2048); }
;                     else { q_rp[it] = (u32x2){0u, 0u}; q_kp[it] = q_rp[it]; q_vp[it] = q_rp[it]; }
;                     q_e[it] = *(const u32x2*)(WD + row * D + chb); q_a[it] = *(const u32x2*)(AA + row * D + chb);
;     ...
;                     const f32x4 pr = unpack4(q_r[it]), pk = unpack4(q_k[it]), pv = unpack4(q_v[it]);
;                     const f32x4 r = pr + (unpack4(q_rp[it]) - pr) * mu_r, k = pk + (unpack4(q_kp[it]) - pk) * mu_k, v = pv + (unpack4(q_vp[it]) - pv) * mu_v;
;                     const f32x4 e = unpack4(q_e[it]), a = unpack4(q_a[it]);
;                     const f32x4 w = (f32x4){__expf(-e[0]), __expf(-e[1]), __expf(-e[2]), __expf(-e[3])};
;                     f32x4 kk = k * kkc; const float n2 = red16(dot4(kk, kk)); kk = kk * (1.0f / fmaxf(sqrtf(n2), 1e-12f));
;                     const f32x4 kp = k * (1.0f + (a - 1.0f) * kac), bv = kk * a, wrv = w * r;
;                     const float br = red16(dot4(bv, r)), kr = red16(dot4(kp, r));
;                     const int o = tt * 64 + 4 * cgq;
;                     *(LAS f32x4*)(V + 0 * TC * 64 + o) = -kk; *(LAS f32x4*)(V + 1 * TC * 64 + o) = wrv; *(LAS f32x4*)(V + 2 * TC * 64 + o) = w;
;                     *(LAS f32x4*)(V + 3 * TC * 64 + o) = bv; *(LAS f32x4*)(V + 4 * TC * 64 + o) = kp; *(LAS f32x4*)(V + 5 * TC * 64 + o) = v;
;                     if (cgq == 0) *(LAS f32x2*)(SCb + buf * TC * 2 + 2 * tt) = (f32x2){br, kr};
	v_cndmask_b32_e32 v21, v32, v21, vcc
	v_max_f32_e32 v21, 0x2b8cbccc, v21
	v_div_scale_f32 v36, s[0:1], v21, v21, -1.0
	s_nop 0
	v_rcp_f32_e32 v37, v36
	v_exp_f32_e32 v32, v33
	v_mul_f32_e32 v33, 0xbfb8aa3b, v47
	v_exp_f32_e32 v33, v33
	v_fma_f32 v44, -v36, v37, 1.0
	v_fmac_f32_e32 v37, v44, v37
	v_div_scale_f32 v44, vcc, -1.0, v21, -1.0
	v_mul_f32_e32 v45, v44, v37
	v_fma_f32 v46, -v36, v45, v44
	v_fmac_f32_e32 v45, v46, v37
	v_fma_f32 v36, -v36, v45, v44
	v_div_fmas_f32 v36, v36, v37, v45
	v_div_fixup_f32 v46, v36, v21, -1.0
	v_pk_add_f32 v[36:37], v[22:23], -1.0 op_sel_hi:[1,0]
	v_pk_add_f32 v[44:45], v[24:25], -1.0 op_sel_hi:[1,0]
	v_pk_fma_f32 v[36:37], v[6:7], v[36:37], 1.0 op_sel_hi:[1,1,0]
	v_pk_fma_f32 v[44:45], v[4:5], v[44:45], 1.0 op_sel_hi:[1,1,0]
	v_pk_mul_f32 v[36:37], v[34:35], v[36:37]
	v_pk_mul_f32 v[34:35], v[38:39], v[44:45]
	v_pk_mul_f32 v[38:39], v[42:43], v[46:47] op_sel_hi:[1,0]
	v_pk_mul_f32 v[40:41], v[40:41], v[46:47] op_sel_hi:[1,0]
	v_pk_mul_f32 v[42:43], v[38:39], v[24:25] neg_lo:[1,0] neg_hi:[1,0]
	v_mov_b32_e32 v25, v35
	v_mov_b32_e32 v24, v42
	v_pk_mul_f32 v[44:45], v[40:41], v[22:23] neg_lo:[1,0] neg_hi:[1,0]
	v_pk_mov_b32 v[22:23], v[42:43], v[34:35] op_sel:[1,0]
	v_pk_mul_f32 v[24:25], v[50:51], v[24:25]
	v_pk_mul_f32 v[46:47], v[50:51], v[30:31]
	v_pk_fma_f32 v[22:23], v[50:51], v[22:23], v[24:25] op_sel:[1,0,0] op_sel_hi:[0,1,1]
	v_mov_b32_e32 v50, v44
	v_mov_b32_e32 v51, v37
	v_pk_mov_b32 v[24:25], v[44:45], v[36:37] op_sel:[1,0]
	v_pk_mul_f32 v[50:51], v[52:53], v[50:51]
	v_pk_mul_f32 v[48:49], v[52:53], v[32:33]
	v_pk_fma_f32 v[24:25], v[52:53], v[24:25], v[50:51] op_sel:[1,0,0] op_sel_hi:[0,1,1]
	v_pk_add_f32 v[22:23], v[22:23], v[24:25]
	ds_write_b128 v142, v[38:41]
	ds_write_b128 v142, v[46:49] offset:8192
	ds_write_b128 v142, v[30:33] offset:16384
	ds_write_b128 v142, v[42:45] offset:24576
	ds_write_b128 v142, v[34:37] offset:32768
	ds_write_b128 v142, v[26:29] offset:40960
	v_mov_b32_dpp v24, v22 quad_perm:[1,0,3,2] row_mask:0xf bank_mask:0xf bound_ctrl:1
	v_mov_b32_dpp v25, v23 quad_perm:[1,0,3,2] row_mask:0xf bank_mask:0xf bound_ctrl:1
	v_pk_add_f32 v[22:23], v[22:23], v[24:25]
	s_nop 1
	v_mov_b32_dpp v24, v22 quad_perm:[2,3,0,1] row_mask:0xf bank_mask:0xf bound_ctrl:1
	v_mov_b32_dpp v25, v23 quad_perm:[2,3,0,1] row_mask:0xf bank_mask:0xf bound_ctrl:1
	v_pk_add_f32 v[22:23], v[22:23], v[24:25]
	s_nop 1
	v_mov_b32_dpp v24, v22 row_half_mirror row_mask:0xf bank_mask:0xf bound_ctrl:1
	v_mov_b32_dpp v25, v23 row_half_mirror row_mask:0xf bank_mask:0xf bound_ctrl:1
	v_pk_add_f32 v[22:23], v[22:23], v[24:25]
	s_nop 1
	v_mov_b32_dpp v24, v22 row_mirror row_mask:0xf bank_mask:0xf bound_ctrl:1
	v_mov_b32_dpp v25, v23 row_mirror row_mask:0xf bank_mask:0xf bound_ctrl:1
	s_and_saveexec_b64 s[0:1], s[2:3]
	v_pk_add_f32 v[22:23], v[22:23], v[24:25]
	ds_write_b64 v143, v[22:23]
	s_or_b64 exec, exec, s[0:1]
	v_or_b32_e32 v22, s42, v76
	v_mov_b64_e32 v[24:25], s[8:9]
	v_mad_u64_u32 v[26:27], s[0:1], v22, s52, v[24:25]
	v_mad_i32_i24 v27, s43, v153, v27
	v_mov_b32_e32 v21, v73
	v_lshl_add_u64 v[26:27], v[26:27], 0, v[20:21]
	v_add_co_u32_e32 v28, vcc, s53, v26
	v_mov_b32_e32 v23, s43
	s_nop 0
	v_addc_co_u32_e32 v29, vcc, 0, v27, vcc
	v_add_co_u32_e32 v30, vcc, s54, v26
	v_lshlrev_b64 v[22:23], 11, v[22:23]
	s_nop 0
	v_addc_co_u32_e32 v31, vcc, -1, v27, vcc
	global_load_dwordx2 v[90:91], v[26:27], off
	global_load_dwordx2 v[92:93], v[26:27], off offset:2048
	global_load_dwordx2 v[88:89], v[28:29], off
	global_load_dwordx2 v[100:101], v[26:27], off offset:-2560
	v_lshl_add_u64 v[26:27], s[20:21], 0, v[22:23]
	v_lshl_add_u64 v[22:23], s[22:23], 0, v[22:23]
	v_lshl_add_u64 v[22:23], v[22:23], 0, v[20:21]
	v_lshl_add_u64 v[26:27], v[26:27], 0, v[20:21]
	global_load_dwordx2 v[98:99], v[30:31], off offset:-2560
	global_load_dwordx2 v[96:97], v[30:31], off offset:-512
	global_load_dwordx2 v[94:95], v[26:27], off
	global_load_dwordx2 v[102:103], v[22:23], off
	v_or_b32_e32 v22, s42, v78
	v_mad_u64_u32 v[24:25], s[0:1], v22, s52, v[24:25]
	v_mad_i32_i24 v25, s43, v153, v25
	v_lshl_add_u64 v[24:25], v[24:25], 0, v[20:21]
	v_add_co_u32_e32 v26, vcc, s53, v24
	v_mov_b32_e32 v23, s43
	s_nop 0
	v_addc_co_u32_e32 v27, vcc, 0, v25, vcc
	v_add_co_u32_e32 v28, vcc, 0xfffff000, v24
	v_lshlrev_b64 v[22:23], 11, v[22:23]
	s_nop 0
	v_addc_co_u32_e32 v29, vcc, -1, v25, vcc
	global_load_dwordx2 v[108:109], v[24:25], off
	global_load_dwordx2 v[104:105], v[24:25], off offset:2048
	global_load_dwordx2 v[106:107], v[26:27], off
	global_load_dwordx2 v[110:111], v[24:25], off offset:-2560
	v_lshl_add_u64 v[24:25], s[20:21], 0, v[22:23]
	v_lshl_add_u64 v[22:23], s[22:23], 0, v[22:23]
	v_lshl_add_u64 v[24:25], v[24:25], 0, v[20:21]
	v_lshl_add_u64 v[20:21], v[22:23], 0, v[20:21]
	global_load_dwordx2 v[114:115], v[28:29], off offset:-2560
	global_load_dwordx2 v[112:113], v[28:29], off offset:-512
	global_load_dwordx2 v[118:119], v[24:25], off
	global_load_dwordx2 v[116:117], v[20:21], off
